# v19 plus first K iteration after an epilogue: the S_0 and S_1 vmcnt waits are counted past the epilogue's own stores (vmcnt 24 after lean epilogues, 63 after residual epilogues that drain at their top
# baseline (speedup 1.0000x reference)
.LBB0_430:
	s_mov_b64 s[0:1], s[78:79]
	s_load_dword s0, s[0:1], 0xa8
	s_waitcnt lgkmcnt(0)
	s_cmp_gt_i32 s0, 4
	s_cbranch_scc1 .LBB0_474
	s_mov_b64 s[0:1], s[78:79]
	s_load_dword s0, s[0:1], 0xac
	s_waitcnt lgkmcnt(0)
	s_cmp_lt_i32 s0, 5
	s_cbranch_scc1 .LBB0_474
	s_mov_b32 s94, 0
	s_mov_b64 s[0:1], s[78:79]
	s_load_dwordx2 s[2:3], s[0:1], 0xa0
	s_cmpk_lt_i32 s87, 0x400
	s_mov_b32 s6, -1
	s_cselect_b64 s[0:1], -1, 0
	s_cmpk_gt_i32 s87, 0x3ff
	s_cbranch_scc1 .LBB0_438
	s_ashr_i32 s4, s87, 31
	s_lshr_b32 s4, s4, 29
	s_add_i32 s7, s87, s4
	s_and_b32 s4, s7, -8
	s_sub_i32 s8, s87, s4
	s_cmp_gt_i32 s8, -1
	s_cbranch_scc0 .LBB0_435
	s_lshl_b32 s9, s8, 7
	s_cbranch_execz .LBB0_436
	s_branch .LBB0_437

.Lsp_skip3:
.LBB0_451:
	ds_read_b128 v[112:115], v193
	ds_read_b128 v[124:127], v193 offset:1024
	ds_read_b128 v[136:139], v193 offset:2048
	ds_read_b128 v[140:143], v193 offset:3072
	ds_read_b128 v[144:147], v194
	ds_read_b128 v[148:151], v194 offset:1024
	ds_read_b128 v[168:171], v194 offset:2048
	ds_read_b128 v[172:175], v194 offset:3072
	ds_read_b128 v[176:179], v195
	ds_read_b128 v[180:183], v195 offset:1024
	ds_read_b128 v[184:187], v195 offset:2048
	ds_read_b128 v[200:203], v195 offset:3072
	ds_read_b128 v[204:207], v195 offset:4096
	ds_read_b128 v[208:211], v195 offset:5120
	ds_read_b128 v[212:215], v195 offset:6144
	ds_read_b128 v[216:219], v195 offset:7168
	s_add_u32 s34, s30, 0xfff00080
	s_addc_u32 s35, s31, -1
	s_cmp_eq_u32 s58, 60
	s_cselect_b32 s37, s21, s35
	s_cselect_b32 s36, s27, s34
	s_cselect_b32 s35, s19, s57
	s_cselect_b32 s34, s55, s56
	s_add_i32 m0, s29, 0xc000
	s_nop 0
	global_load_lds_dwordx4 v162, s[30:31]
	s_add_i32 m0, s29, 0xe000
	s_nop 0
	global_load_lds_dwordx4 v160, s[30:31]
	s_cmp_eq_u32 s94, 1
	s_cbranch_scc1 .Lrx4_0a
	s_waitcnt vmcnt(8)
	s_branch .Lrx4_0b
.Lrx4_0a:
	s_waitcnt vmcnt(63)
.Lrx4_0b:
	s_waitcnt lgkmcnt(0)
	s_barrier
	s_waitcnt lgkmcnt(0)
	v_mfma_f32_16x16x32_bf16 v[132:135], v[112:115], v[176:179], v[132:135]
	v_mfma_f32_16x16x32_bf16 v[128:131], v[136:139], v[176:179], v[128:131]
	v_mfma_f32_16x16x32_bf16 v[108:111], v[112:115], v[184:187], v[108:111]
	v_mfma_f32_16x16x32_bf16 v[104:107], v[136:139], v[184:187], v[104:107]
	s_add_u32 s98, s34, s14
	s_addc_u32 s99, s35, s15
	s_add_i32 s59, s50, s41
	v_mfma_f32_16x16x32_bf16 v[92:95], v[112:115], v[204:207], v[92:95]
	s_add_u32 s100, s36, s14
	s_addc_u32 s101, s37, s15
	v_mfma_f32_16x16x32_bf16 v[88:91], v[136:139], v[204:207], v[88:91]
	v_mfma_f32_16x16x32_bf16 v[76:79], v[112:115], v[212:215], v[76:79]
	v_mfma_f32_16x16x32_bf16 v[72:75], v[136:139], v[212:215], v[72:75]
	s_add_u32 s60, s34, 0x100000
	v_mfma_f32_16x16x32_bf16 v[132:135], v[124:127], v[180:183], v[132:135]
	v_mfma_f32_16x16x32_bf16 v[128:131], v[140:143], v[180:183], v[128:131]
	v_mfma_f32_16x16x32_bf16 v[108:111], v[124:127], v[200:203], v[108:111]
	v_mfma_f32_16x16x32_bf16 v[104:107], v[140:143], v[200:203], v[104:107]
	s_addc_u32 s61, s35, 0
	v_mfma_f32_16x16x32_bf16 v[92:95], v[124:127], v[208:211], v[92:95]
	v_mfma_f32_16x16x32_bf16 v[88:91], v[140:143], v[208:211], v[88:91]
	v_mfma_f32_16x16x32_bf16 v[76:79], v[124:127], v[216:219], v[76:79]
	v_mfma_f32_16x16x32_bf16 v[72:75], v[140:143], v[216:219], v[72:75]
	v_mfma_f32_16x16x32_bf16 v[120:123], v[144:147], v[176:179], v[120:123]
	v_mfma_f32_16x16x32_bf16 v[116:119], v[168:171], v[176:179], v[116:119]
	v_mfma_f32_16x16x32_bf16 v[100:103], v[144:147], v[184:187], v[100:103]
	v_mfma_f32_16x16x32_bf16 v[96:99], v[168:171], v[184:187], v[96:99]
	v_mfma_f32_16x16x32_bf16 v[84:87], v[144:147], v[204:207], v[84:87]
	v_mfma_f32_16x16x32_bf16 v[80:83], v[168:171], v[204:207], v[80:83]
	v_mfma_f32_16x16x32_bf16 v[68:71], v[144:147], v[212:215], v[68:71]
	v_mfma_f32_16x16x32_bf16 v[64:67], v[168:171], v[212:215], v[64:67]
	v_mfma_f32_16x16x32_bf16 v[120:123], v[148:151], v[180:183], v[120:123]
	v_mfma_f32_16x16x32_bf16 v[116:119], v[172:175], v[180:183], v[116:119]
	v_mfma_f32_16x16x32_bf16 v[100:103], v[148:151], v[200:203], v[100:103]
	v_mfma_f32_16x16x32_bf16 v[96:99], v[172:175], v[200:203], v[96:99]
	v_mfma_f32_16x16x32_bf16 v[84:87], v[148:151], v[208:211], v[84:87]
	v_mfma_f32_16x16x32_bf16 v[80:83], v[172:175], v[208:211], v[80:83]
	v_mfma_f32_16x16x32_bf16 v[68:71], v[148:151], v[216:219], v[68:71]
	v_mfma_f32_16x16x32_bf16 v[64:67], v[172:175], v[216:219], v[64:67]
	s_barrier
	ds_read_b128 v[176:179], v195 offset:16384
	ds_read_b128 v[180:183], v195 offset:17408
	ds_read_b128 v[184:187], v195 offset:18432
	ds_read_b128 v[200:203], v195 offset:19456
	ds_read_b128 v[204:207], v195 offset:20480
	ds_read_b128 v[208:211], v195 offset:21504
	ds_read_b128 v[212:215], v195 offset:22528
	ds_read_b128 v[216:219], v195 offset:23552
	s_mov_b32 m0, s59
	s_nop 0
	global_load_lds_dwordx4 v154, s[34:35]
	s_add_i32 m0, s59, 0x2000
	s_add_i32 s59, s51, s41
	global_load_lds_dwordx4 v158, s[34:35]
	s_mov_b32 m0, s59
	s_nop 0
	global_load_lds_dwordx4 v154, s[60:61]
	s_add_i32 m0, s59, 0x2000
	s_nop 0
	global_load_lds_dwordx4 v158, s[60:61]
	s_mov_b32 m0, s29
	s_nop 0
	global_load_lds_dwordx4 v152, s[36:37]
	s_mov_b32 m0, s42
	s_nop 0
	global_load_lds_dwordx4 v156, s[36:37]
	s_cmp_eq_u32 s94, 1
	s_cbranch_scc1 .Lrx4_1a
	s_waitcnt vmcnt(8)
	s_branch .Lrx4_1b

.Lrx4_1b:
	s_mov_b32 s94, 0
	s_waitcnt lgkmcnt(0)
	s_barrier
	s_waitcnt lgkmcnt(0)
	v_mfma_f32_16x16x32_bf16 v[60:63], v[112:115], v[176:179], v[60:63]
	v_mfma_f32_16x16x32_bf16 v[56:59], v[136:139], v[176:179], v[56:59]
	v_mfma_f32_16x16x32_bf16 v[44:47], v[112:115], v[184:187], v[44:47]
	v_mfma_f32_16x16x32_bf16 v[40:43], v[136:139], v[184:187], v[40:43]
	s_add_i32 s59, 0, 0x18000
	v_mfma_f32_16x16x32_bf16 v[28:31], v[112:115], v[204:207], v[28:31]
	v_mfma_f32_16x16x32_bf16 v[24:27], v[136:139], v[204:207], v[24:27]
	s_add_i32 s60, 0, 0x1c000
	v_mfma_f32_16x16x32_bf16 v[12:15], v[112:115], v[212:215], v[12:15]
	v_mfma_f32_16x16x32_bf16 v[8:11], v[136:139], v[212:215], v[8:11]
	s_add_u32 s36, s36, 0x100000
	v_mfma_f32_16x16x32_bf16 v[60:63], v[124:127], v[180:183], v[60:63]
	v_mfma_f32_16x16x32_bf16 v[56:59], v[140:143], v[180:183], v[56:59]
	s_addc_u32 s37, s37, 0
	v_mfma_f32_16x16x32_bf16 v[44:47], v[124:127], v[200:203], v[44:47]
	v_mfma_f32_16x16x32_bf16 v[40:43], v[140:143], v[200:203], v[40:43]
	v_mfma_f32_16x16x32_bf16 v[28:31], v[124:127], v[208:211], v[28:31]
	v_mfma_f32_16x16x32_bf16 v[24:27], v[140:143], v[208:211], v[24:27]
	v_mfma_f32_16x16x32_bf16 v[12:15], v[124:127], v[216:219], v[12:15]
	v_mfma_f32_16x16x32_bf16 v[8:11], v[140:143], v[216:219], v[8:11]
	v_mfma_f32_16x16x32_bf16 v[52:55], v[144:147], v[176:179], v[52:55]
	v_mfma_f32_16x16x32_bf16 v[48:51], v[168:171], v[176:179], v[48:51]
	v_mfma_f32_16x16x32_bf16 v[36:39], v[144:147], v[184:187], v[36:39]
	v_mfma_f32_16x16x32_bf16 v[32:35], v[168:171], v[184:187], v[32:35]
	v_mfma_f32_16x16x32_bf16 v[20:23], v[144:147], v[204:207], v[20:23]
	v_mfma_f32_16x16x32_bf16 v[16:19], v[168:171], v[204:207], v[16:19]
	v_mfma_f32_16x16x32_bf16 v[4:7], v[144:147], v[212:215], v[4:7]
	v_mfma_f32_16x16x32_bf16 v[0:3], v[168:171], v[212:215], v[0:3]
	v_mfma_f32_16x16x32_bf16 v[52:55], v[148:151], v[180:183], v[52:55]
	v_mfma_f32_16x16x32_bf16 v[48:51], v[172:175], v[180:183], v[48:51]
	v_mfma_f32_16x16x32_bf16 v[36:39], v[148:151], v[200:203], v[36:39]
	v_mfma_f32_16x16x32_bf16 v[32:35], v[172:175], v[200:203], v[32:35]
	v_mfma_f32_16x16x32_bf16 v[20:23], v[148:151], v[208:211], v[20:23]
	v_mfma_f32_16x16x32_bf16 v[16:19], v[172:175], v[208:211], v[16:19]
	v_mfma_f32_16x16x32_bf16 v[4:7], v[148:151], v[216:219], v[4:7]
	v_mfma_f32_16x16x32_bf16 v[0:3], v[172:175], v[216:219], v[0:3]
	s_barrier
	ds_read_b128 v[176:179], v195 offset:32768
	ds_read_b128 v[180:183], v195 offset:33792
	ds_read_b128 v[184:187], v195 offset:34816
	ds_read_b128 v[200:203], v195 offset:35840
	ds_read_b128 v[204:207], v195 offset:36864
	ds_read_b128 v[208:211], v195 offset:37888
	ds_read_b128 v[212:215], v195 offset:38912
	ds_read_b128 v[216:219], v195 offset:39936
	v_add_u32_e32 v140, s59, v191
	v_add_u32_e32 v172, s60, v191
	ds_read_b128 v[112:115], v140
	ds_read_b128 v[124:127], v140 offset:1024
	ds_read_b128 v[136:139], v140 offset:2048
	ds_read_b128 v[140:143], v140 offset:3072
	ds_read_b128 v[144:147], v172
	ds_read_b128 v[148:151], v172 offset:1024
	ds_read_b128 v[168:171], v172 offset:2048
	ds_read_b128 v[172:175], v172 offset:3072
	s_mov_b32 m0, s43
	s_nop 0
	global_load_lds_dwordx4 v152, s[36:37]
	s_mov_b32 m0, s44
	s_nop 0
	global_load_lds_dwordx4 v156, s[36:37]
	s_waitcnt vmcnt(8)
	s_waitcnt lgkmcnt(0)
	s_barrier
	s_waitcnt lgkmcnt(0)
	v_mfma_f32_16x16x32_bf16 v[132:135], v[112:115], v[176:179], v[132:135]
	v_mfma_f32_16x16x32_bf16 v[128:131], v[136:139], v[176:179], v[128:131]
	v_mfma_f32_16x16x32_bf16 v[108:111], v[112:115], v[184:187], v[108:111]
	v_mfma_f32_16x16x32_bf16 v[104:107], v[136:139], v[184:187], v[104:107]
	s_add_i32 s36, s59, s41
	v_mfma_f32_16x16x32_bf16 v[92:95], v[112:115], v[204:207], v[92:95]
	v_mfma_f32_16x16x32_bf16 v[88:91], v[136:139], v[204:207], v[88:91]
	v_mfma_f32_16x16x32_bf16 v[76:79], v[112:115], v[212:215], v[76:79]
	v_mfma_f32_16x16x32_bf16 v[72:75], v[136:139], v[212:215], v[72:75]
	s_add_u32 s34, s34, 0x100080
	v_mfma_f32_16x16x32_bf16 v[132:135], v[124:127], v[180:183], v[132:135]
	v_mfma_f32_16x16x32_bf16 v[128:131], v[140:143], v[180:183], v[128:131]
	v_mfma_f32_16x16x32_bf16 v[108:111], v[124:127], v[200:203], v[108:111]
	v_mfma_f32_16x16x32_bf16 v[104:107], v[140:143], v[200:203], v[104:107]
	s_addc_u32 s35, s35, 0
	v_mfma_f32_16x16x32_bf16 v[92:95], v[124:127], v[208:211], v[92:95]
	v_mfma_f32_16x16x32_bf16 v[88:91], v[140:143], v[208:211], v[88:91]
	v_mfma_f32_16x16x32_bf16 v[76:79], v[124:127], v[216:219], v[76:79]
	v_mfma_f32_16x16x32_bf16 v[72:75], v[140:143], v[216:219], v[72:75]
	v_mfma_f32_16x16x32_bf16 v[120:123], v[144:147], v[176:179], v[120:123]
	v_mfma_f32_16x16x32_bf16 v[116:119], v[168:171], v[176:179], v[116:119]
	v_mfma_f32_16x16x32_bf16 v[100:103], v[144:147], v[184:187], v[100:103]
	v_mfma_f32_16x16x32_bf16 v[96:99], v[168:171], v[184:187], v[96:99]
	v_mfma_f32_16x16x32_bf16 v[84:87], v[144:147], v[204:207], v[84:87]
	v_mfma_f32_16x16x32_bf16 v[80:83], v[168:171], v[204:207], v[80:83]
	v_mfma_f32_16x16x32_bf16 v[68:71], v[144:147], v[212:215], v[68:71]
	v_mfma_f32_16x16x32_bf16 v[64:67], v[168:171], v[212:215], v[64:67]
	v_mfma_f32_16x16x32_bf16 v[120:123], v[148:151], v[180:183], v[120:123]
	v_mfma_f32_16x16x32_bf16 v[116:119], v[172:175], v[180:183], v[116:119]
	v_mfma_f32_16x16x32_bf16 v[100:103], v[148:151], v[200:203], v[100:103]
	v_mfma_f32_16x16x32_bf16 v[96:99], v[172:175], v[200:203], v[96:99]
	v_mfma_f32_16x16x32_bf16 v[84:87], v[148:151], v[208:211], v[84:87]
	v_mfma_f32_16x16x32_bf16 v[80:83], v[172:175], v[208:211], v[80:83]
	v_mfma_f32_16x16x32_bf16 v[68:71], v[148:151], v[216:219], v[68:71]
	v_mfma_f32_16x16x32_bf16 v[64:67], v[172:175], v[216:219], v[64:67]
	s_barrier
	ds_read_b128 v[176:179], v195 offset:49152
	ds_read_b128 v[180:183], v195 offset:50176
	ds_read_b128 v[184:187], v195 offset:51200
	ds_read_b128 v[200:203], v195 offset:52224
	ds_read_b128 v[204:207], v195 offset:53248
	ds_read_b128 v[208:211], v195 offset:54272
	ds_read_b128 v[212:215], v195 offset:55296
	ds_read_b128 v[216:219], v195 offset:56320
	s_mov_b32 m0, s36
	s_nop 0
	global_load_lds_dwordx4 v154, s[98:99]
	s_add_i32 m0, s36, 0x2000
	s_add_i32 s36, s60, s41
	global_load_lds_dwordx4 v158, s[98:99]
	s_mov_b32 m0, s36
	s_nop 0
	global_load_lds_dwordx4 v154, s[34:35]
	s_add_i32 m0, s36, 0x2000
	s_nop 0
	global_load_lds_dwordx4 v158, s[34:35]
	s_mov_b32 m0, s46
	s_nop 0
	global_load_lds_dwordx4 v152, s[100:101]
	s_mov_b32 m0, s47
	s_nop 0
	global_load_lds_dwordx4 v156, s[100:101]
	s_waitcnt vmcnt(8)
	s_waitcnt lgkmcnt(0)
	s_barrier
	s_waitcnt lgkmcnt(0)
	v_mfma_f32_16x16x32_bf16 v[60:63], v[112:115], v[176:179], v[60:63]
	v_mfma_f32_16x16x32_bf16 v[56:59], v[136:139], v[176:179], v[56:59]
	v_mfma_f32_16x16x32_bf16 v[44:47], v[112:115], v[184:187], v[44:47]
	v_mfma_f32_16x16x32_bf16 v[40:43], v[136:139], v[184:187], v[40:43]
	v_mfma_f32_16x16x32_bf16 v[28:31], v[112:115], v[204:207], v[28:31]
	v_mfma_f32_16x16x32_bf16 v[24:27], v[136:139], v[204:207], v[24:27]
	v_mfma_f32_16x16x32_bf16 v[12:15], v[112:115], v[212:215], v[12:15]
	v_mfma_f32_16x16x32_bf16 v[8:11], v[136:139], v[212:215], v[8:11]
	v_mfma_f32_16x16x32_bf16 v[60:63], v[124:127], v[180:183], v[60:63]
	v_mfma_f32_16x16x32_bf16 v[56:59], v[140:143], v[180:183], v[56:59]
	v_mfma_f32_16x16x32_bf16 v[44:47], v[124:127], v[200:203], v[44:47]
	v_mfma_f32_16x16x32_bf16 v[40:43], v[140:143], v[200:203], v[40:43]
	v_mfma_f32_16x16x32_bf16 v[28:31], v[124:127], v[208:211], v[28:31]
	v_mfma_f32_16x16x32_bf16 v[24:27], v[140:143], v[208:211], v[24:27]
	v_mfma_f32_16x16x32_bf16 v[12:15], v[124:127], v[216:219], v[12:15]
	v_mfma_f32_16x16x32_bf16 v[8:11], v[140:143], v[216:219], v[8:11]
	v_mfma_f32_16x16x32_bf16 v[52:55], v[144:147], v[176:179], v[52:55]
	v_mfma_f32_16x16x32_bf16 v[48:51], v[168:171], v[176:179], v[48:51]
	v_mfma_f32_16x16x32_bf16 v[36:39], v[144:147], v[184:187], v[36:39]
	v_mfma_f32_16x16x32_bf16 v[32:35], v[168:171], v[184:187], v[32:35]
	v_mfma_f32_16x16x32_bf16 v[20:23], v[144:147], v[204:207], v[20:23]
	v_mfma_f32_16x16x32_bf16 v[16:19], v[168:171], v[204:207], v[16:19]
	v_mfma_f32_16x16x32_bf16 v[4:7], v[144:147], v[212:215], v[4:7]
	v_mfma_f32_16x16x32_bf16 v[0:3], v[168:171], v[212:215], v[0:3]
	v_mfma_f32_16x16x32_bf16 v[52:55], v[148:151], v[180:183], v[52:55]
	v_mfma_f32_16x16x32_bf16 v[48:51], v[172:175], v[180:183], v[48:51]
	v_mfma_f32_16x16x32_bf16 v[36:39], v[148:151], v[200:203], v[36:39]
	v_mfma_f32_16x16x32_bf16 v[32:35], v[172:175], v[200:203], v[32:35]
	v_mfma_f32_16x16x32_bf16 v[20:23], v[148:151], v[208:211], v[20:23]
	v_mfma_f32_16x16x32_bf16 v[16:19], v[172:175], v[208:211], v[16:19]
	v_mfma_f32_16x16x32_bf16 v[4:7], v[148:151], v[216:219], v[4:7]
	v_mfma_f32_16x16x32_bf16 v[0:3], v[172:175], v[216:219], v[0:3]
	s_barrier
	s_add_i32 s58, s58, 2
	s_add_u32 s56, s56, 0x100
	s_addc_u32 s57, s57, 0
	s_add_u32 s30, s30, 0x100
	s_addc_u32 s31, s31, 0
	s_cmp_gt_u32 s58, 61
	s_cbranch_scc0 .LBB0_451
	s_setprio 0
	s_and_b64 vcc, exec, s[16:17]
	s_cbranch_vccz .LBB0_454
	s_barrier
.LBB0_454:
	v_lshl_add_u32 v174, s26, 8, v190
	v_lshl_or_b32 v168, s28, 8, v192
	v_ashrrev_i32_e32 v169, 31, v168
	v_ashrrev_i32_e32 v175, 31, v174
	v_lshl_add_u64 v[172:173], v[168:169], 1, s[6:7]
	v_lshlrev_b64 v[112:113], 13, v[174:175]
	v_lshl_add_u64 v[170:171], v[174:175], 3, s[12:13]
	v_lshl_add_u64 v[188:189], v[172:173], 0, v[112:113]
	global_load_dwordx2 v[208:209], v[170:171], off
	global_load_dwordx2 v[232:233], v[170:171], off offset:128
	global_load_dwordx2 v[234:235], v[170:171], off offset:256
	global_load_dwordx2 v[236:237], v[170:171], off offset:384
	global_load_dwordx2 v[238:239], v[170:171], off offset:1024
	global_load_dwordx2 v[240:241], v[170:171], off offset:1152
	global_load_dwordx2 v[242:243], v[170:171], off offset:1280
	global_load_dwordx2 v[244:245], v[170:171], off offset:1408
	global_load_dwordx4 v[200:203], v[188:189], off
	v_or_b32_e32 v184, 16, v174
	v_or_b32_e32 v180, 32, v174
	v_or_b32_e32 v176, 48, v174
	v_ashrrev_i32_e32 v185, 31, v184
	v_ashrrev_i32_e32 v181, 31, v180
	v_ashrrev_i32_e32 v177, 31, v176
	v_lshlrev_b64 v[112:113], 12, v[174:175]
	v_lshlrev_b64 v[114:115], 13, v[184:185]
	v_lshlrev_b64 v[124:125], 13, v[180:181]
	v_lshlrev_b64 v[126:127], 13, v[176:177]
	v_lshl_add_u64 v[112:113], v[112:113], 0, v[168:169]
	v_lshl_add_u64 v[186:187], v[172:173], 0, v[114:115]
	v_lshl_add_u64 v[182:183], v[172:173], 0, v[124:125]
	v_lshl_add_u64 v[178:179], v[172:173], 0, v[126:127]
	v_lshl_add_u64 v[210:211], s[10:11], 0, v[112:113]
	global_load_dwordx4 v[204:207], v[188:189], off offset:256
	global_load_dwordx4 v[148:151], v[186:187], off
	global_load_dwordx4 v[144:147], v[186:187], off offset:256
	global_load_dwordx4 v[140:143], v[182:183], off
	global_load_dwordx4 v[136:139], v[182:183], off offset:256
	global_load_dwordx4 v[124:127], v[178:179], off
	global_load_dwordx4 v[112:115], v[178:179], off offset:256
	s_mov_b64 s[96:97], 0x100000
	v_lshl_add_u64 v[220:221], v[188:189], 0, s[96:97]
	global_load_dwordx4 v[220:223], v[220:221], off
	v_lshl_add_u64 v[224:225], v[188:189], 0, s[96:97]
	global_load_dwordx4 v[224:227], v[224:225], off offset:256
	v_lshl_add_u64 v[228:229], v[186:187], 0, s[96:97]
	global_load_dwordx4 v[228:231], v[228:229], off
	v_lshl_add_u64 v[246:247], v[186:187], 0, s[96:97]
	global_load_dwordx4 v[246:249], v[246:247], off offset:256
	v_lshl_add_u64 v[250:251], v[182:183], 0, s[96:97]
	global_load_dwordx4 v[250:253], v[250:251], off
	v_lshl_add_u64 v[216:217], v[182:183], 0, s[96:97]
	global_load_dwordx4 v[216:219], v[216:217], off offset:256
	s_waitcnt vmcnt(0)
	s_mov_b32 s94, 1
	v_ffbh_u32_e32 v199, v209
	v_min_u32_e32 v199, 32, v199
	v_lshlrev_b64 v[208:209], v199, v[208:209]
	v_min_u32_e32 v208, 1, v208
	v_or_b32_e32 v208, v209, v208
	v_cvt_f32_u32_e32 v208, v208
	v_lshlrev_b32_e32 v212, 16, v200
	v_and_b32_e32 v213, 0xffff0000, v200
	v_lshlrev_b32_e32 v200, 16, v201
	v_and_b32_e32 v201, 0xffff0000, v201
	v_lshlrev_b32_e32 v214, 16, v202
	v_and_b32_e32 v215, 0xffff0000, v202
	v_lshlrev_b32_e32 v202, 16, v203
	v_and_b32_e32 v203, 0xffff0000, v203
	v_pk_add_f32 v[134:135], v[134:135], v[200:201]
	v_pk_add_f32 v[132:133], v[132:133], v[212:213]
	v_pk_add_f32 v[200:201], v[130:131], v[202:203]
	v_pk_add_f32 v[202:203], v[128:129], v[214:215]
	v_sub_u32_e32 v199, 32, v199
	v_cvt_pk_bf16_f32 v128, v132, v133
	v_cvt_pk_bf16_f32 v129, v134, v135
	v_cvt_pk_bf16_f32 v130, v202, v203
	v_cvt_pk_bf16_f32 v131, v200, v201
	global_store_dwordx4 v[188:189], v[128:131], off
	v_mul_f32_e32 v212, v133, v133
	v_mul_f32_e32 v213, v135, v135
	v_ldexp_f32 v128, v208, v199
	v_fmamk_f32 v128, v128, 0x2f800000, v196
	v_rsq_f32_e32 v128, v128
	v_mul_f32_e32 v214, v203, v203
	v_fmac_f32_e32 v212, v132, v132
	v_fmac_f32_e32 v213, v134, v134
	v_fmac_f32_e32 v214, v202, v202
	v_add_f32_e32 v129, v212, v213
	v_mul_f32_e32 v199, 0x41ca3ab3, v128
	v_add_f32_e32 v130, v214, v129
	v_mul_f32_e32 v128, v199, v132
	v_mul_f32_e32 v129, v199, v133
	v_mul_f32_e32 v131, v199, v134
	v_mul_f32_e32 v132, v199, v135
	v_mul_f32_e32 v134, v199, v203
	v_mul_f32_e32 v133, v199, v202
	v_mul_f32_e32 v135, v199, v200
	v_mul_f32_e32 v202, v199, v201
	v_med3_f32 v128, v128, s52, v198
	v_med3_f32 v129, v129, s52, v198
	v_med3_f32 v132, v132, s52, v198
	v_med3_f32 v134, v134, s52, v198
	v_med3_f32 v131, v131, s52, v198
	v_med3_f32 v133, v133, s52, v198
	v_med3_f32 v135, v135, s52, v198
	v_med3_f32 v202, v202, s52, v198
	v_rndne_f32_e32 v128, v128
	v_rndne_f32_e32 v129, v129
	v_rndne_f32_e32 v132, v132
	v_rndne_f32_e32 v134, v134
	v_rndne_f32_e32 v131, v131
	v_rndne_f32_e32 v133, v133
	v_rndne_f32_e32 v135, v135
	v_rndne_f32_e32 v202, v202
	v_cvt_i32_f32_e32 v128, v128
	v_cvt_i32_f32_e32 v129, v129
	v_cvt_i32_f32_e32 v132, v132
	v_cvt_i32_f32_e32 v134, v134
	v_cvt_i32_f32_sdwa v131, v131 dst_sel:WORD_1 dst_unused:UNUSED_PAD src0_sel:DWORD
	v_cvt_i32_f32_e32 v133, v133
	v_cvt_i32_f32_sdwa v135, v135 dst_sel:WORD_1 dst_unused:UNUSED_PAD src0_sel:DWORD
	v_cvt_i32_f32_e32 v202, v202
	v_lshlrev_b32_e32 v129, 8, v129
	v_perm_b32 v128, v132, v128, s53
	v_lshlrev_b32_e32 v132, 8, v134
	v_and_b32_e32 v131, 0xff0000, v131
	v_and_b32_e32 v134, 0xff0000, v135
	v_perm_b32 v133, v202, v133, s53
	v_and_b32_e32 v129, 0xff00, v129
	v_and_b32_e32 v132, 0xff00, v132
	v_or3_b32 v128, v128, v129, v131
	v_or3_b32 v129, v133, v132, v134
	global_store_dwordx2 v[210:211], v[128:129], off
	v_mul_f32_e32 v128, v201, v201
	v_fmac_f32_e32 v128, v200, v200
	v_add_f32_e32 v200, v128, v130
	v_lshlrev_b32_e32 v128, 16, v204
	v_and_b32_e32 v129, 0xffff0000, v204
	v_lshlrev_b32_e32 v130, 16, v205
	v_and_b32_e32 v131, 0xffff0000, v205
	v_lshlrev_b32_e32 v132, 16, v206
	v_and_b32_e32 v133, 0xffff0000, v206
	v_lshlrev_b32_e32 v134, 16, v207
	v_and_b32_e32 v135, 0xffff0000, v207
	v_pk_add_f32 v[122:123], v[122:123], v[130:131]
	v_pk_add_f32 v[120:121], v[120:121], v[128:129]
	v_pk_add_f32 v[130:131], v[116:117], v[132:133]
	v_cvt_pk_bf16_f32 v116, v120, v121
	v_cvt_pk_bf16_f32 v117, v122, v123
	v_pk_add_f32 v[128:129], v[118:119], v[134:135]
	v_cvt_pk_bf16_f32 v118, v130, v131
	s_nop 0
	v_cvt_pk_bf16_f32 v119, v128, v129
	global_store_dwordx4 v[188:189], v[116:119], off offset:256
	s_nop 1
	v_mul_f32_e32 v117, v199, v121
	v_mul_f32_e32 v116, v199, v120
	v_mul_f32_e32 v118, v199, v122
	v_mul_f32_e32 v119, v199, v123
	v_med3_f32 v117, v117, s52, v198
	v_med3_f32 v116, v116, s52, v198
	v_rndne_f32_e32 v117, v117
	v_med3_f32 v118, v118, s52, v198
	v_med3_f32 v119, v119, s52, v198
	v_rndne_f32_e32 v116, v116
	v_cvt_i32_f32_e32 v117, v117
	v_rndne_f32_e32 v118, v118
	v_rndne_f32_e32 v119, v119
	v_cvt_i32_f32_e32 v116, v116
	v_cvt_i32_f32_sdwa v118, v118 dst_sel:WORD_1 dst_unused:UNUSED_PAD src0_sel:DWORD
	v_cvt_i32_f32_e32 v119, v119
	v_lshlrev_b32_e32 v117, 8, v117
	v_and_b32_e32 v117, 0xff00, v117
	v_and_b32_e32 v118, 0xff0000, v118
	v_perm_b32 v116, v119, v116, s53
	v_or3_b32 v132, v116, v117, v118
	v_mul_f32_e32 v117, v199, v131
	v_med3_f32 v117, v117, s52, v198
	v_rndne_f32_e32 v117, v117
	v_cvt_i32_f32_e32 v117, v117
	v_mul_f32_e32 v116, v199, v130
	v_med3_f32 v116, v116, s52, v198
	v_rndne_f32_e32 v116, v116
	v_mul_f32_e32 v118, v199, v128
	v_cvt_i32_f32_e32 v133, v116
	v_lshlrev_b32_e32 v116, 8, v117
	v_and_b32_e32 v134, 0xff00, v116
	v_med3_f32 v116, v118, s52, v198
	v_rndne_f32_e32 v117, v116
	v_mul_f32_e32 v116, v121, v121
	v_mul_f32_e32 v118, v123, v123
	v_fmac_f32_e32 v116, v120, v120
	v_fmac_f32_e32 v118, v122, v122
	v_add_f32_e32 v116, v116, v118
	v_mul_f32_e32 v118, v131, v131
	v_fmac_f32_e32 v118, v130, v130
	v_add_f32_e32 v116, v118, v116
	v_mul_f32_e32 v118, v129, v129
	v_fmac_f32_e32 v118, v128, v128
	v_add_f32_e32 v116, v118, v116
	v_and_b32_e32 v120, 64, v197
	v_add_f32_e32 v118, v200, v116
	v_xor_b32_e32 v116, 16, v197
	v_add_u32_e32 v120, 64, v120
	v_cmp_lt_i32_e32 vcc, v116, v120
	v_mul_f32_e32 v119, v199, v129
	v_cvt_i32_f32_sdwa v122, v117 dst_sel:WORD_1 dst_unused:UNUSED_PAD src0_sel:DWORD
	v_cndmask_b32_e32 v116, v197, v116, vcc
	v_lshlrev_b32_e32 v116, 2, v116
	ds_bpermute_b32 v121, v116, v118
	v_med3_f32 v117, v119, s52, v198
	v_rndne_f32_e32 v117, v117
	v_cvt_i32_f32_e32 v123, v117
	v_xor_b32_e32 v117, 32, v197
	v_cmp_lt_i32_e32 vcc, v117, v120
	s_waitcnt lgkmcnt(0)
	v_add_f32_e32 v118, v118, v121
	v_and_b32_e32 v120, 0xff0000, v122
	v_cndmask_b32_e32 v117, v197, v117, vcc
	v_lshlrev_b32_e32 v117, 2, v117
	ds_bpermute_b32 v119, v117, v118
	v_perm_b32 v121, v123, v133, s53
	v_or3_b32 v133, v121, v134, v120
	global_store_dwordx2 v[210:211], v[132:133], off offset:128
	s_and_saveexec_b64 s[26:27], s[2:3]
	s_cbranch_execz .LBB0_456
	s_waitcnt lgkmcnt(0)
	v_add_f32_e32 v118, v118, v119
	v_fma_f32 v118, v118, s54, 0.5
	v_trunc_f32_e32 v118, v118
	v_mul_f32_e32 v119, 0x2f800000, v118
	v_floor_f32_e32 v119, v119
	v_fmac_f32_e32 v118, 0xcf800000, v119
	v_cvt_u32_f32_e32 v118, v118
	v_cvt_u32_f32_e32 v119, v119
	v_lshl_add_u64 v[120:121], v[174:175], 3, s[8:9]
	global_atomic_add_x2 v[120:121], v[118:119], off

.LBB0_531:
	s_mov_b64 s[0:1], s[78:79]
	s_load_dword s0, s[0:1], 0xa8
	s_waitcnt lgkmcnt(0)
	s_cmp_gt_i32 s0, 5
	s_cbranch_scc1 .LBB0_557
	s_mov_b64 s[0:1], s[78:79]
	s_load_dword s0, s[0:1], 0xac
	s_waitcnt lgkmcnt(0)
	s_cmp_lt_i32 s0, 6
	s_cbranch_scc1 .LBB0_557
	s_mov_b32 s94, 0
	s_mov_b32 s95, -1
	s_mov_b64 s[0:1], s[78:79]
	s_mov_b32 s5, -1
	s_cmpk_gt_i32 s87, 0xfff
	s_cbranch_scc1 .LBB0_557
	s_ashr_i32 s33, s87, 31
	s_load_dwordx2 s[2:3], s[0:1], 0xa0
	s_lshr_b32 s0, s33, 29
	s_add_i32 s6, s87, s0
	s_and_b32 s0, s6, -8
	s_sub_i32 s7, s87, s0
	s_cmp_gt_i32 s7, -1
	s_cbranch_scc0 .LBB0_536
	s_lshl_b32 s4, s7, 9
	s_cbranch_execz .LBB0_537
	s_branch .LBB0_538

.Lsp_skip4:
.LBB0_550:
	ds_read_b128 v[144:147], v161
	ds_read_b128 v[148:151], v161 offset:1024
	ds_read_b128 v[170:173], v161 offset:2048
	ds_read_b128 v[174:177], v161 offset:3072
	ds_read_b128 v[178:181], v163
	ds_read_b128 v[182:185], v163 offset:1024
	ds_read_b128 v[186:189], v163 offset:2048
	ds_read_b128 v[190:193], v163 offset:3072
	ds_read_b128 v[194:197], v166
	ds_read_b128 v[198:201], v166 offset:1024
	ds_read_b128 v[202:205], v166 offset:2048
	ds_read_b128 v[206:209], v166 offset:3072
	ds_read_b128 v[210:213], v166 offset:4096
	ds_read_b128 v[214:217], v166 offset:5120
	ds_read_b128 v[218:221], v166 offset:6144
	ds_read_b128 v[222:225], v166 offset:7168
	s_add_u32 s6, s4, 0xfff80080
	s_addc_u32 s7, s5, -1
	s_cmp_eq_u32 s64, 28
	s_cselect_b32 s39, s1, s7
	s_cselect_b32 s38, s31, s6
	s_cselect_b32 s7, s29, s63
	s_cselect_b32 s6, s61, s62
	s_add_i32 m0, s45, 0xc000
	s_nop 0
	global_load_lds_dwordx4 v138, s[4:5]
	s_add_i32 m0, s45, 0xe000
	s_nop 0
	global_load_lds_dwordx4 v136, s[4:5]
	s_cmp_eq_u32 s94, 1
	s_cbranch_scc1 .Lrx5_0a
	s_waitcnt vmcnt(8)
	s_branch .Lrx5_0b
.Lrx5_0a:
	s_waitcnt vmcnt(24)
.Lrx5_0b:
	s_waitcnt lgkmcnt(0)
	s_barrier
	s_waitcnt lgkmcnt(0)
	v_mfma_i32_16x16x64_i8 v[124:127], v[144:147], v[194:197], v[124:127]
	v_mfma_i32_16x16x64_i8 v[120:123], v[170:173], v[194:197], v[120:123]
	v_mfma_i32_16x16x64_i8 v[108:111], v[144:147], v[202:205], v[108:111]
	v_mfma_i32_16x16x64_i8 v[104:107], v[170:173], v[202:205], v[104:107]
	s_add_u32 s98, s6, s16
	s_addc_u32 s99, s7, s17
	s_add_i32 s65, s53, s44
	v_mfma_i32_16x16x64_i8 v[92:95], v[144:147], v[210:213], v[92:95]
	s_add_u32 s100, s38, s16
	s_addc_u32 s101, s39, s17
	v_mfma_i32_16x16x64_i8 v[88:91], v[170:173], v[210:213], v[88:91]
	v_mfma_i32_16x16x64_i8 v[76:79], v[144:147], v[218:221], v[76:79]
	v_mfma_i32_16x16x64_i8 v[72:75], v[170:173], v[218:221], v[72:75]
	s_add_u32 s66, s6, 0x80000
	v_mfma_i32_16x16x64_i8 v[124:127], v[148:151], v[198:201], v[124:127]
	v_mfma_i32_16x16x64_i8 v[120:123], v[174:177], v[198:201], v[120:123]
	v_mfma_i32_16x16x64_i8 v[108:111], v[148:151], v[206:209], v[108:111]
	v_mfma_i32_16x16x64_i8 v[104:107], v[174:177], v[206:209], v[104:107]
	s_addc_u32 s67, s7, 0
	v_mfma_i32_16x16x64_i8 v[92:95], v[148:151], v[214:217], v[92:95]
	v_mfma_i32_16x16x64_i8 v[88:91], v[174:177], v[214:217], v[88:91]
	v_mfma_i32_16x16x64_i8 v[76:79], v[148:151], v[222:225], v[76:79]
	v_mfma_i32_16x16x64_i8 v[72:75], v[174:177], v[222:225], v[72:75]
	v_mfma_i32_16x16x64_i8 v[116:119], v[178:181], v[194:197], v[116:119]
	v_mfma_i32_16x16x64_i8 v[112:115], v[186:189], v[194:197], v[112:115]
	v_mfma_i32_16x16x64_i8 v[100:103], v[178:181], v[202:205], v[100:103]
	v_mfma_i32_16x16x64_i8 v[96:99], v[186:189], v[202:205], v[96:99]
	v_mfma_i32_16x16x64_i8 v[84:87], v[178:181], v[210:213], v[84:87]
	v_mfma_i32_16x16x64_i8 v[80:83], v[186:189], v[210:213], v[80:83]
	v_mfma_i32_16x16x64_i8 v[68:71], v[178:181], v[218:221], v[68:71]
	v_mfma_i32_16x16x64_i8 v[64:67], v[186:189], v[218:221], v[64:67]
	v_mfma_i32_16x16x64_i8 v[116:119], v[182:185], v[198:201], v[116:119]
	v_mfma_i32_16x16x64_i8 v[112:115], v[190:193], v[198:201], v[112:115]
	v_mfma_i32_16x16x64_i8 v[100:103], v[182:185], v[206:209], v[100:103]
	v_mfma_i32_16x16x64_i8 v[96:99], v[190:193], v[206:209], v[96:99]
	v_mfma_i32_16x16x64_i8 v[84:87], v[182:185], v[214:217], v[84:87]
	v_mfma_i32_16x16x64_i8 v[80:83], v[190:193], v[214:217], v[80:83]
	v_mfma_i32_16x16x64_i8 v[68:71], v[182:185], v[222:225], v[68:71]
	v_mfma_i32_16x16x64_i8 v[64:67], v[190:193], v[222:225], v[64:67]
	s_barrier
	ds_read_b128 v[194:197], v166 offset:16384
	ds_read_b128 v[198:201], v166 offset:17408
	ds_read_b128 v[202:205], v166 offset:18432
	ds_read_b128 v[206:209], v166 offset:19456
	ds_read_b128 v[210:213], v166 offset:20480
	ds_read_b128 v[214:217], v166 offset:21504
	ds_read_b128 v[218:221], v166 offset:22528
	ds_read_b128 v[222:225], v166 offset:23552
	s_mov_b32 m0, s65
	s_nop 0
	global_load_lds_dwordx4 v130, s[6:7]
	s_add_i32 m0, s65, 0x2000
	s_add_i32 s65, s54, s44
	global_load_lds_dwordx4 v134, s[6:7]
	s_mov_b32 m0, s65
	s_nop 0
	global_load_lds_dwordx4 v130, s[66:67]
	s_add_i32 m0, s65, 0x2000
	s_nop 0
	global_load_lds_dwordx4 v134, s[66:67]
	s_mov_b32 m0, s45
	s_nop 0
	global_load_lds_dwordx4 v128, s[38:39]
	s_mov_b32 m0, s46
	s_nop 0
	global_load_lds_dwordx4 v132, s[38:39]
	s_cmp_eq_u32 s94, 1
	s_cbranch_scc1 .Lrx5_1a
	s_waitcnt vmcnt(8)
	s_branch .Lrx5_1b

.Lrx5_1b:
	s_mov_b32 s94, 0
	s_waitcnt lgkmcnt(0)
	s_barrier
	s_waitcnt lgkmcnt(0)
	v_mfma_i32_16x16x64_i8 v[60:63], v[144:147], v[194:197], v[60:63]
	v_mfma_i32_16x16x64_i8 v[56:59], v[170:173], v[194:197], v[56:59]
	v_mfma_i32_16x16x64_i8 v[44:47], v[144:147], v[202:205], v[44:47]
	v_mfma_i32_16x16x64_i8 v[40:43], v[170:173], v[202:205], v[40:43]
	s_add_i32 s65, 0, 0x18000
	v_mfma_i32_16x16x64_i8 v[28:31], v[144:147], v[210:213], v[28:31]
	v_mfma_i32_16x16x64_i8 v[24:27], v[170:173], v[210:213], v[24:27]
	v_add_u32_e32 v154, s65, v157
	v_mfma_i32_16x16x64_i8 v[12:15], v[144:147], v[218:221], v[12:15]
	v_mfma_i32_16x16x64_i8 v[8:11], v[170:173], v[218:221], v[8:11]
	s_add_i32 s66, 0, 0x1c000
	v_mfma_i32_16x16x64_i8 v[60:63], v[148:151], v[198:201], v[60:63]
	v_mfma_i32_16x16x64_i8 v[56:59], v[174:177], v[198:201], v[56:59]
	s_add_u32 s38, s38, 0x80000
	v_mfma_i32_16x16x64_i8 v[44:47], v[148:151], v[206:209], v[44:47]
	v_mfma_i32_16x16x64_i8 v[40:43], v[174:177], v[206:209], v[40:43]
	s_addc_u32 s39, s39, 0
	v_mfma_i32_16x16x64_i8 v[28:31], v[148:151], v[214:217], v[28:31]
	v_mfma_i32_16x16x64_i8 v[24:27], v[174:177], v[214:217], v[24:27]
	v_mfma_i32_16x16x64_i8 v[12:15], v[148:151], v[222:225], v[12:15]
	v_mfma_i32_16x16x64_i8 v[8:11], v[174:177], v[222:225], v[8:11]
	v_mfma_i32_16x16x64_i8 v[52:55], v[178:181], v[194:197], v[52:55]
	v_mfma_i32_16x16x64_i8 v[48:51], v[186:189], v[194:197], v[48:51]
	v_mfma_i32_16x16x64_i8 v[36:39], v[178:181], v[202:205], v[36:39]
	v_mfma_i32_16x16x64_i8 v[32:35], v[186:189], v[202:205], v[32:35]
	v_mfma_i32_16x16x64_i8 v[20:23], v[178:181], v[210:213], v[20:23]
	v_mfma_i32_16x16x64_i8 v[16:19], v[186:189], v[210:213], v[16:19]
	v_mfma_i32_16x16x64_i8 v[4:7], v[178:181], v[218:221], v[4:7]
	v_mfma_i32_16x16x64_i8 v[0:3], v[186:189], v[218:221], v[0:3]
	v_mfma_i32_16x16x64_i8 v[52:55], v[182:185], v[198:201], v[52:55]
	v_mfma_i32_16x16x64_i8 v[48:51], v[190:193], v[198:201], v[48:51]
	v_mfma_i32_16x16x64_i8 v[36:39], v[182:185], v[206:209], v[36:39]
	v_mfma_i32_16x16x64_i8 v[32:35], v[190:193], v[206:209], v[32:35]
	v_mfma_i32_16x16x64_i8 v[20:23], v[182:185], v[214:217], v[20:23]
	v_mfma_i32_16x16x64_i8 v[16:19], v[190:193], v[214:217], v[16:19]
	v_mfma_i32_16x16x64_i8 v[4:7], v[182:185], v[222:225], v[4:7]
	v_mfma_i32_16x16x64_i8 v[0:3], v[190:193], v[222:225], v[0:3]
	s_barrier
	ds_read_b128 v[194:197], v166 offset:32768
	ds_read_b128 v[198:201], v166 offset:33792
	ds_read_b128 v[202:205], v166 offset:34816
	ds_read_b128 v[206:209], v166 offset:35840
	ds_read_b128 v[210:213], v166 offset:36864
	ds_read_b128 v[214:217], v166 offset:37888
	ds_read_b128 v[218:221], v166 offset:38912
	ds_read_b128 v[222:225], v166 offset:39936
	ds_read_b128 v[144:147], v154
	ds_read_b128 v[148:151], v154 offset:1024
	ds_read_b128 v[170:173], v154 offset:2048
	ds_read_b128 v[174:177], v154 offset:3072
	v_add_u32_e32 v154, s66, v157
	ds_read_b128 v[178:181], v154
	ds_read_b128 v[182:185], v154 offset:1024
	ds_read_b128 v[186:189], v154 offset:2048
	ds_read_b128 v[190:193], v154 offset:3072
	s_mov_b32 m0, s47
	s_nop 0
	global_load_lds_dwordx4 v128, s[38:39]
	s_mov_b32 m0, s48
	s_nop 0
	global_load_lds_dwordx4 v132, s[38:39]
	s_waitcnt vmcnt(8)
	s_waitcnt lgkmcnt(0)
	s_barrier
	s_waitcnt lgkmcnt(0)
	v_mfma_i32_16x16x64_i8 v[124:127], v[144:147], v[194:197], v[124:127]
	v_mfma_i32_16x16x64_i8 v[120:123], v[170:173], v[194:197], v[120:123]
	v_mfma_i32_16x16x64_i8 v[108:111], v[144:147], v[202:205], v[108:111]
	v_mfma_i32_16x16x64_i8 v[104:107], v[170:173], v[202:205], v[104:107]
	s_add_i32 s38, s65, s44
	v_mfma_i32_16x16x64_i8 v[92:95], v[144:147], v[210:213], v[92:95]
	v_mfma_i32_16x16x64_i8 v[88:91], v[170:173], v[210:213], v[88:91]
	v_mfma_i32_16x16x64_i8 v[76:79], v[144:147], v[218:221], v[76:79]
	v_mfma_i32_16x16x64_i8 v[72:75], v[170:173], v[218:221], v[72:75]
	s_add_u32 s6, s6, 0x80080
	v_mfma_i32_16x16x64_i8 v[124:127], v[148:151], v[198:201], v[124:127]
	v_mfma_i32_16x16x64_i8 v[120:123], v[174:177], v[198:201], v[120:123]
	v_mfma_i32_16x16x64_i8 v[108:111], v[148:151], v[206:209], v[108:111]
	v_mfma_i32_16x16x64_i8 v[104:107], v[174:177], v[206:209], v[104:107]
	s_addc_u32 s7, s7, 0
	v_mfma_i32_16x16x64_i8 v[92:95], v[148:151], v[214:217], v[92:95]
	v_mfma_i32_16x16x64_i8 v[88:91], v[174:177], v[214:217], v[88:91]
	v_mfma_i32_16x16x64_i8 v[76:79], v[148:151], v[222:225], v[76:79]
	v_mfma_i32_16x16x64_i8 v[72:75], v[174:177], v[222:225], v[72:75]
	v_mfma_i32_16x16x64_i8 v[116:119], v[178:181], v[194:197], v[116:119]
	v_mfma_i32_16x16x64_i8 v[112:115], v[186:189], v[194:197], v[112:115]
	v_mfma_i32_16x16x64_i8 v[100:103], v[178:181], v[202:205], v[100:103]
	v_mfma_i32_16x16x64_i8 v[96:99], v[186:189], v[202:205], v[96:99]
	v_mfma_i32_16x16x64_i8 v[84:87], v[178:181], v[210:213], v[84:87]
	v_mfma_i32_16x16x64_i8 v[80:83], v[186:189], v[210:213], v[80:83]
	v_mfma_i32_16x16x64_i8 v[68:71], v[178:181], v[218:221], v[68:71]
	v_mfma_i32_16x16x64_i8 v[64:67], v[186:189], v[218:221], v[64:67]
	v_mfma_i32_16x16x64_i8 v[116:119], v[182:185], v[198:201], v[116:119]
	v_mfma_i32_16x16x64_i8 v[112:115], v[190:193], v[198:201], v[112:115]
	v_mfma_i32_16x16x64_i8 v[100:103], v[182:185], v[206:209], v[100:103]
	v_mfma_i32_16x16x64_i8 v[96:99], v[190:193], v[206:209], v[96:99]
	v_mfma_i32_16x16x64_i8 v[84:87], v[182:185], v[214:217], v[84:87]
	v_mfma_i32_16x16x64_i8 v[80:83], v[190:193], v[214:217], v[80:83]
	v_mfma_i32_16x16x64_i8 v[68:71], v[182:185], v[222:225], v[68:71]
	v_mfma_i32_16x16x64_i8 v[64:67], v[190:193], v[222:225], v[64:67]
	s_barrier
	ds_read_b128 v[194:197], v166 offset:49152
	ds_read_b128 v[198:201], v166 offset:50176
	ds_read_b128 v[202:205], v166 offset:51200
	ds_read_b128 v[206:209], v166 offset:52224
	ds_read_b128 v[210:213], v166 offset:53248
	ds_read_b128 v[214:217], v166 offset:54272
	ds_read_b128 v[218:221], v166 offset:55296
	ds_read_b128 v[222:225], v166 offset:56320
	s_mov_b32 m0, s38
	s_nop 0
	global_load_lds_dwordx4 v130, s[98:99]
	s_add_i32 m0, s38, 0x2000
	s_add_i32 s38, s66, s44
	global_load_lds_dwordx4 v134, s[98:99]
	s_mov_b32 m0, s38
	s_nop 0
	global_load_lds_dwordx4 v130, s[6:7]
	s_add_i32 m0, s38, 0x2000
	s_nop 0
	global_load_lds_dwordx4 v134, s[6:7]
	s_mov_b32 m0, s50
	s_nop 0
	global_load_lds_dwordx4 v128, s[100:101]
	s_mov_b32 m0, s51
	s_nop 0
	global_load_lds_dwordx4 v132, s[100:101]
	s_waitcnt vmcnt(8)
	s_waitcnt lgkmcnt(0)
	s_barrier
	s_waitcnt lgkmcnt(0)
	v_mfma_i32_16x16x64_i8 v[60:63], v[144:147], v[194:197], v[60:63]
	v_mfma_i32_16x16x64_i8 v[56:59], v[170:173], v[194:197], v[56:59]
	v_mfma_i32_16x16x64_i8 v[44:47], v[144:147], v[202:205], v[44:47]
	v_mfma_i32_16x16x64_i8 v[40:43], v[170:173], v[202:205], v[40:43]
	v_mfma_i32_16x16x64_i8 v[28:31], v[144:147], v[210:213], v[28:31]
	v_mfma_i32_16x16x64_i8 v[24:27], v[170:173], v[210:213], v[24:27]
	v_mfma_i32_16x16x64_i8 v[12:15], v[144:147], v[218:221], v[12:15]
	v_mfma_i32_16x16x64_i8 v[8:11], v[170:173], v[218:221], v[8:11]
	v_mfma_i32_16x16x64_i8 v[60:63], v[148:151], v[198:201], v[60:63]
	v_mfma_i32_16x16x64_i8 v[56:59], v[174:177], v[198:201], v[56:59]
	v_mfma_i32_16x16x64_i8 v[44:47], v[148:151], v[206:209], v[44:47]
	v_mfma_i32_16x16x64_i8 v[40:43], v[174:177], v[206:209], v[40:43]
	v_mfma_i32_16x16x64_i8 v[28:31], v[148:151], v[214:217], v[28:31]
	v_mfma_i32_16x16x64_i8 v[24:27], v[174:177], v[214:217], v[24:27]
	v_mfma_i32_16x16x64_i8 v[12:15], v[148:151], v[222:225], v[12:15]
	v_mfma_i32_16x16x64_i8 v[8:11], v[174:177], v[222:225], v[8:11]
	v_mfma_i32_16x16x64_i8 v[52:55], v[178:181], v[194:197], v[52:55]
	v_mfma_i32_16x16x64_i8 v[48:51], v[186:189], v[194:197], v[48:51]
	v_mfma_i32_16x16x64_i8 v[36:39], v[178:181], v[202:205], v[36:39]
	v_mfma_i32_16x16x64_i8 v[32:35], v[186:189], v[202:205], v[32:35]
	v_mfma_i32_16x16x64_i8 v[20:23], v[178:181], v[210:213], v[20:23]
	v_mfma_i32_16x16x64_i8 v[16:19], v[186:189], v[210:213], v[16:19]
	v_mfma_i32_16x16x64_i8 v[4:7], v[178:181], v[218:221], v[4:7]
	v_mfma_i32_16x16x64_i8 v[0:3], v[186:189], v[218:221], v[0:3]
	v_mfma_i32_16x16x64_i8 v[52:55], v[182:185], v[198:201], v[52:55]
	v_mfma_i32_16x16x64_i8 v[48:51], v[190:193], v[198:201], v[48:51]
	v_mfma_i32_16x16x64_i8 v[36:39], v[182:185], v[206:209], v[36:39]
	v_mfma_i32_16x16x64_i8 v[32:35], v[190:193], v[206:209], v[32:35]
	v_mfma_i32_16x16x64_i8 v[20:23], v[182:185], v[214:217], v[20:23]
	v_mfma_i32_16x16x64_i8 v[16:19], v[190:193], v[214:217], v[16:19]
	v_mfma_i32_16x16x64_i8 v[4:7], v[182:185], v[222:225], v[4:7]
	v_mfma_i32_16x16x64_i8 v[0:3], v[190:193], v[222:225], v[0:3]
	s_barrier
	s_add_i32 s64, s64, 2
	s_add_u32 s62, s62, 0x100
	s_addc_u32 s63, s63, 0
	s_add_u32 s4, s4, 0x100
	s_addc_u32 s5, s5, 0
	s_cmp_gt_u32 s64, 29
	s_cbranch_scc0 .LBB0_550
	s_setprio 0
	s_and_b64 vcc, exec, s[18:19]
	s_cbranch_vccz .LBB0_553
	s_barrier

.Llean_p5:
	s_mov_b32 s94, 1
	v_lshl_add_u32 v144, s0, 8, v155
	v_mov_b32_e32 v145, 0
	v_lshl_or_b32 v148, s60, 8, v159
	v_mov_b32_e32 v149, 0
	v_mov_b32_e32 v146, 0x8100
	v_mad_u64_u32 v[146:147], s[96:97], v144, v146, 0
	v_lshlrev_b64 v[148:149], 1, v[148:149]
	v_lshl_add_u64 v[146:147], s[10:11], 0, v[146:147]
	v_lshl_add_u64 v[150:151], v[146:147], 0, v[148:149]
	v_cvt_f32_i32_e32 v124, v124
	v_cvt_f32_i32_e32 v125, v125
	v_cvt_f32_i32_e32 v126, v126
	v_cvt_f32_i32_e32 v127, v127
	v_cvt_f32_i32_e32 v120, v120
	v_cvt_f32_i32_e32 v121, v121
	v_cvt_f32_i32_e32 v122, v122
	v_cvt_f32_i32_e32 v123, v123
	v_pk_mul_f32 v[124:125], v[232:233], v[124:125] op_sel_hi:[0,1]
	v_pk_mul_f32 v[126:127], v[232:233], v[126:127] op_sel_hi:[0,1]
	v_pk_mul_f32 v[120:121], v[232:233], v[120:121] op_sel_hi:[0,1]
	v_pk_mul_f32 v[122:123], v[232:233], v[122:123] op_sel_hi:[0,1]
	v_max_f32_e32 v124, 0, v124
	v_max_f32_e32 v125, 0, v125
	v_max_f32_e32 v126, 0, v126
	v_max_f32_e32 v127, 0, v127
	v_max_f32_e32 v120, 0, v120
	v_max_f32_e32 v121, 0, v121
	v_max_f32_e32 v122, 0, v122
	v_max_f32_e32 v123, 0, v123
	v_pk_mul_f32 v[124:125], v[124:125], v[124:125]
	v_pk_mul_f32 v[126:127], v[126:127], v[126:127]
	v_pk_mul_f32 v[120:121], v[120:121], v[120:121]
	v_pk_mul_f32 v[122:123], v[122:123], v[122:123]
	v_cvt_pk_bf16_f32 v170, v124, v125
	v_cvt_pk_bf16_f32 v171, v126, v127
	v_cvt_pk_bf16_f32 v172, v120, v121
	v_cvt_pk_bf16_f32 v173, v122, v123
	global_store_dwordx4 v[150:151], v[170:173], off
	v_cvt_f32_i32_e32 v116, v116
	v_cvt_f32_i32_e32 v117, v117
	v_cvt_f32_i32_e32 v118, v118
	v_cvt_f32_i32_e32 v119, v119
	v_cvt_f32_i32_e32 v112, v112
	v_cvt_f32_i32_e32 v113, v113
	v_cvt_f32_i32_e32 v114, v114
	v_cvt_f32_i32_e32 v115, v115
	v_pk_mul_f32 v[116:117], v[232:233], v[116:117] op_sel_hi:[0,1]
	v_pk_mul_f32 v[118:119], v[232:233], v[118:119] op_sel_hi:[0,1]
	v_pk_mul_f32 v[112:113], v[232:233], v[112:113] op_sel_hi:[0,1]
	v_pk_mul_f32 v[114:115], v[232:233], v[114:115] op_sel_hi:[0,1]
	v_max_f32_e32 v116, 0, v116
	v_max_f32_e32 v117, 0, v117
	v_max_f32_e32 v118, 0, v118
	v_max_f32_e32 v119, 0, v119
	v_max_f32_e32 v112, 0, v112
	v_max_f32_e32 v113, 0, v113
	v_max_f32_e32 v114, 0, v114
	v_max_f32_e32 v115, 0, v115
	v_pk_mul_f32 v[116:117], v[116:117], v[116:117]
	v_pk_mul_f32 v[118:119], v[118:119], v[118:119]
	v_pk_mul_f32 v[112:113], v[112:113], v[112:113]
	v_pk_mul_f32 v[114:115], v[114:115], v[114:115]
	v_cvt_pk_bf16_f32 v174, v116, v117
	v_cvt_pk_bf16_f32 v175, v118, v119
	v_cvt_pk_bf16_f32 v176, v112, v113
	v_cvt_pk_bf16_f32 v177, v114, v115
	global_store_dwordx4 v[150:151], v[174:177], off offset:256
	v_add_co_u32_e32 v152, vcc, 0x81000, v150
	s_nop 1
	v_addc_co_u32_e32 v153, vcc, 0, v151, vcc
	v_cvt_f32_i32_e32 v108, v108
	v_cvt_f32_i32_e32 v109, v109
	v_cvt_f32_i32_e32 v110, v110
	v_cvt_f32_i32_e32 v111, v111
	v_cvt_f32_i32_e32 v104, v104
	v_cvt_f32_i32_e32 v105, v105
	v_cvt_f32_i32_e32 v106, v106
	v_cvt_f32_i32_e32 v107, v107
	v_pk_mul_f32 v[108:109], v[234:235], v[108:109] op_sel_hi:[0,1]
	v_pk_mul_f32 v[110:111], v[234:235], v[110:111] op_sel_hi:[0,1]
	v_pk_mul_f32 v[104:105], v[234:235], v[104:105] op_sel_hi:[0,1]
	v_pk_mul_f32 v[106:107], v[234:235], v[106:107] op_sel_hi:[0,1]
	v_max_f32_e32 v108, 0, v108
	v_max_f32_e32 v109, 0, v109
	v_max_f32_e32 v110, 0, v110
	v_max_f32_e32 v111, 0, v111
	v_max_f32_e32 v104, 0, v104
	v_max_f32_e32 v105, 0, v105
	v_max_f32_e32 v106, 0, v106
	v_max_f32_e32 v107, 0, v107
	v_pk_mul_f32 v[108:109], v[108:109], v[108:109]
	v_pk_mul_f32 v[110:111], v[110:111], v[110:111]
	v_pk_mul_f32 v[104:105], v[104:105], v[104:105]
	v_pk_mul_f32 v[106:107], v[106:107], v[106:107]
	v_cvt_pk_bf16_f32 v178, v108, v109
	v_cvt_pk_bf16_f32 v179, v110, v111
	v_cvt_pk_bf16_f32 v180, v104, v105
	v_cvt_pk_bf16_f32 v181, v106, v107
	global_store_dwordx4 v[152:153], v[178:181], off
	v_cvt_f32_i32_e32 v100, v100
	v_cvt_f32_i32_e32 v101, v101
	v_cvt_f32_i32_e32 v102, v102
	v_cvt_f32_i32_e32 v103, v103
	v_cvt_f32_i32_e32 v96, v96
	v_cvt_f32_i32_e32 v97, v97
	v_cvt_f32_i32_e32 v98, v98
	v_cvt_f32_i32_e32 v99, v99
	v_pk_mul_f32 v[100:101], v[234:235], v[100:101] op_sel_hi:[0,1]
	v_pk_mul_f32 v[102:103], v[234:235], v[102:103] op_sel_hi:[0,1]
	v_pk_mul_f32 v[96:97], v[234:235], v[96:97] op_sel_hi:[0,1]
	v_pk_mul_f32 v[98:99], v[234:235], v[98:99] op_sel_hi:[0,1]
	v_max_f32_e32 v100, 0, v100
	v_max_f32_e32 v101, 0, v101
	v_max_f32_e32 v102, 0, v102
	v_max_f32_e32 v103, 0, v103
	v_max_f32_e32 v96, 0, v96
	v_max_f32_e32 v97, 0, v97
	v_max_f32_e32 v98, 0, v98
	v_max_f32_e32 v99, 0, v99
	v_pk_mul_f32 v[100:101], v[100:101], v[100:101]
	v_pk_mul_f32 v[102:103], v[102:103], v[102:103]
	v_pk_mul_f32 v[96:97], v[96:97], v[96:97]
	v_pk_mul_f32 v[98:99], v[98:99], v[98:99]
	v_cvt_pk_bf16_f32 v182, v100, v101
	v_cvt_pk_bf16_f32 v183, v102, v103
	v_cvt_pk_bf16_f32 v184, v96, v97
	v_cvt_pk_bf16_f32 v185, v98, v99
	global_store_dwordx4 v[152:153], v[182:185], off offset:256
	v_add_co_u32_e32 v152, vcc, 0x102000, v150
	s_nop 1
	v_addc_co_u32_e32 v153, vcc, 0, v151, vcc
	v_cvt_f32_i32_e32 v92, v92
	v_cvt_f32_i32_e32 v93, v93
	v_cvt_f32_i32_e32 v94, v94
	v_cvt_f32_i32_e32 v95, v95
	v_cvt_f32_i32_e32 v88, v88
	v_cvt_f32_i32_e32 v89, v89
	v_cvt_f32_i32_e32 v90, v90
	v_cvt_f32_i32_e32 v91, v91
	v_pk_mul_f32 v[92:93], v[236:237], v[92:93] op_sel_hi:[0,1]
	v_pk_mul_f32 v[94:95], v[236:237], v[94:95] op_sel_hi:[0,1]
	v_pk_mul_f32 v[88:89], v[236:237], v[88:89] op_sel_hi:[0,1]
	v_pk_mul_f32 v[90:91], v[236:237], v[90:91] op_sel_hi:[0,1]
	v_max_f32_e32 v92, 0, v92
	v_max_f32_e32 v93, 0, v93
	v_max_f32_e32 v94, 0, v94
	v_max_f32_e32 v95, 0, v95
	v_max_f32_e32 v88, 0, v88
	v_max_f32_e32 v89, 0, v89
	v_max_f32_e32 v90, 0, v90
	v_max_f32_e32 v91, 0, v91
	v_pk_mul_f32 v[92:93], v[92:93], v[92:93]
	v_pk_mul_f32 v[94:95], v[94:95], v[94:95]
	v_pk_mul_f32 v[88:89], v[88:89], v[88:89]
	v_pk_mul_f32 v[90:91], v[90:91], v[90:91]
	v_cvt_pk_bf16_f32 v186, v92, v93
	v_cvt_pk_bf16_f32 v187, v94, v95
	v_cvt_pk_bf16_f32 v188, v88, v89
	v_cvt_pk_bf16_f32 v189, v90, v91
	global_store_dwordx4 v[152:153], v[186:189], off
	v_cvt_f32_i32_e32 v84, v84
	v_cvt_f32_i32_e32 v85, v85
	v_cvt_f32_i32_e32 v86, v86
	v_cvt_f32_i32_e32 v87, v87
	v_cvt_f32_i32_e32 v80, v80
	v_cvt_f32_i32_e32 v81, v81
	v_cvt_f32_i32_e32 v82, v82
	v_cvt_f32_i32_e32 v83, v83
	v_pk_mul_f32 v[84:85], v[236:237], v[84:85] op_sel_hi:[0,1]
	v_pk_mul_f32 v[86:87], v[236:237], v[86:87] op_sel_hi:[0,1]
	v_pk_mul_f32 v[80:81], v[236:237], v[80:81] op_sel_hi:[0,1]
	v_pk_mul_f32 v[82:83], v[236:237], v[82:83] op_sel_hi:[0,1]
	v_max_f32_e32 v84, 0, v84
	v_max_f32_e32 v85, 0, v85
	v_max_f32_e32 v86, 0, v86
	v_max_f32_e32 v87, 0, v87
	v_max_f32_e32 v80, 0, v80
	v_max_f32_e32 v81, 0, v81
	v_max_f32_e32 v82, 0, v82
	v_max_f32_e32 v83, 0, v83
	v_pk_mul_f32 v[84:85], v[84:85], v[84:85]
	v_pk_mul_f32 v[86:87], v[86:87], v[86:87]
	v_pk_mul_f32 v[80:81], v[80:81], v[80:81]
	v_pk_mul_f32 v[82:83], v[82:83], v[82:83]
	v_cvt_pk_bf16_f32 v190, v84, v85
	v_cvt_pk_bf16_f32 v191, v86, v87
	v_cvt_pk_bf16_f32 v192, v80, v81
	v_cvt_pk_bf16_f32 v193, v82, v83
	global_store_dwordx4 v[152:153], v[190:193], off offset:256
	v_add_co_u32_e32 v152, vcc, 0x183000, v150
	s_nop 1
	v_addc_co_u32_e32 v153, vcc, 0, v151, vcc
	v_cvt_f32_i32_e32 v76, v76
	v_cvt_f32_i32_e32 v77, v77
	v_cvt_f32_i32_e32 v78, v78
	v_cvt_f32_i32_e32 v79, v79
	v_cvt_f32_i32_e32 v72, v72
	v_cvt_f32_i32_e32 v73, v73
	v_cvt_f32_i32_e32 v74, v74
	v_cvt_f32_i32_e32 v75, v75
	v_pk_mul_f32 v[76:77], v[238:239], v[76:77] op_sel_hi:[0,1]
	v_pk_mul_f32 v[78:79], v[238:239], v[78:79] op_sel_hi:[0,1]
	v_pk_mul_f32 v[72:73], v[238:239], v[72:73] op_sel_hi:[0,1]
	v_pk_mul_f32 v[74:75], v[238:239], v[74:75] op_sel_hi:[0,1]
	v_max_f32_e32 v76, 0, v76
	v_max_f32_e32 v77, 0, v77
	v_max_f32_e32 v78, 0, v78
	v_max_f32_e32 v79, 0, v79
	v_max_f32_e32 v72, 0, v72
	v_max_f32_e32 v73, 0, v73
	v_max_f32_e32 v74, 0, v74
	v_max_f32_e32 v75, 0, v75
	v_pk_mul_f32 v[76:77], v[76:77], v[76:77]
	v_pk_mul_f32 v[78:79], v[78:79], v[78:79]
	v_pk_mul_f32 v[72:73], v[72:73], v[72:73]
	v_pk_mul_f32 v[74:75], v[74:75], v[74:75]
	v_cvt_pk_bf16_f32 v194, v76, v77
	v_cvt_pk_bf16_f32 v195, v78, v79
	v_cvt_pk_bf16_f32 v196, v72, v73
	v_cvt_pk_bf16_f32 v197, v74, v75
	global_store_dwordx4 v[152:153], v[194:197], off
	v_cvt_f32_i32_e32 v68, v68
	v_cvt_f32_i32_e32 v69, v69
	v_cvt_f32_i32_e32 v70, v70
	v_cvt_f32_i32_e32 v71, v71
	v_cvt_f32_i32_e32 v64, v64
	v_cvt_f32_i32_e32 v65, v65
	v_cvt_f32_i32_e32 v66, v66
	v_cvt_f32_i32_e32 v67, v67
	v_pk_mul_f32 v[68:69], v[238:239], v[68:69] op_sel_hi:[0,1]
	v_pk_mul_f32 v[70:71], v[238:239], v[70:71] op_sel_hi:[0,1]
	v_pk_mul_f32 v[64:65], v[238:239], v[64:65] op_sel_hi:[0,1]
	v_pk_mul_f32 v[66:67], v[238:239], v[66:67] op_sel_hi:[0,1]
	v_max_f32_e32 v68, 0, v68
	v_max_f32_e32 v69, 0, v69
	v_max_f32_e32 v70, 0, v70
	v_max_f32_e32 v71, 0, v71
	v_max_f32_e32 v64, 0, v64
	v_max_f32_e32 v65, 0, v65
	v_max_f32_e32 v66, 0, v66
	v_max_f32_e32 v67, 0, v67
	v_pk_mul_f32 v[68:69], v[68:69], v[68:69]
	v_pk_mul_f32 v[70:71], v[70:71], v[70:71]
	v_pk_mul_f32 v[64:65], v[64:65], v[64:65]
	v_pk_mul_f32 v[66:67], v[66:67], v[66:67]
	v_cvt_pk_bf16_f32 v198, v68, v69
	v_cvt_pk_bf16_f32 v199, v70, v71
	v_cvt_pk_bf16_f32 v200, v64, v65
	v_cvt_pk_bf16_f32 v201, v66, v67
	global_store_dwordx4 v[152:153], v[198:201], off offset:256
	v_add_co_u32_e32 v152, vcc, 0x408000, v150
	s_nop 1
	v_addc_co_u32_e32 v153, vcc, 0, v151, vcc
	v_cvt_f32_i32_e32 v60, v60
	v_cvt_f32_i32_e32 v61, v61
	v_cvt_f32_i32_e32 v62, v62
	v_cvt_f32_i32_e32 v63, v63
	v_cvt_f32_i32_e32 v56, v56
	v_cvt_f32_i32_e32 v57, v57
	v_cvt_f32_i32_e32 v58, v58
	v_cvt_f32_i32_e32 v59, v59
	v_pk_mul_f32 v[60:61], v[240:241], v[60:61] op_sel_hi:[0,1]
	v_pk_mul_f32 v[62:63], v[240:241], v[62:63] op_sel_hi:[0,1]
	v_pk_mul_f32 v[56:57], v[240:241], v[56:57] op_sel_hi:[0,1]
	v_pk_mul_f32 v[58:59], v[240:241], v[58:59] op_sel_hi:[0,1]
	v_max_f32_e32 v60, 0, v60
	v_max_f32_e32 v61, 0, v61
	v_max_f32_e32 v62, 0, v62
	v_max_f32_e32 v63, 0, v63
	v_max_f32_e32 v56, 0, v56
	v_max_f32_e32 v57, 0, v57
	v_max_f32_e32 v58, 0, v58
	v_max_f32_e32 v59, 0, v59
	v_pk_mul_f32 v[60:61], v[60:61], v[60:61]
	v_pk_mul_f32 v[62:63], v[62:63], v[62:63]
	v_pk_mul_f32 v[56:57], v[56:57], v[56:57]
	v_pk_mul_f32 v[58:59], v[58:59], v[58:59]
	v_cvt_pk_bf16_f32 v170, v60, v61
	v_cvt_pk_bf16_f32 v171, v62, v63
	v_cvt_pk_bf16_f32 v172, v56, v57
	v_cvt_pk_bf16_f32 v173, v58, v59
	global_store_dwordx4 v[152:153], v[170:173], off
	v_cvt_f32_i32_e32 v52, v52
	v_cvt_f32_i32_e32 v53, v53
	v_cvt_f32_i32_e32 v54, v54
	v_cvt_f32_i32_e32 v55, v55
	v_cvt_f32_i32_e32 v48, v48
	v_cvt_f32_i32_e32 v49, v49
	v_cvt_f32_i32_e32 v50, v50
	v_cvt_f32_i32_e32 v51, v51
	v_pk_mul_f32 v[52:53], v[240:241], v[52:53] op_sel_hi:[0,1]
	v_pk_mul_f32 v[54:55], v[240:241], v[54:55] op_sel_hi:[0,1]
	v_pk_mul_f32 v[48:49], v[240:241], v[48:49] op_sel_hi:[0,1]
	v_pk_mul_f32 v[50:51], v[240:241], v[50:51] op_sel_hi:[0,1]
	v_max_f32_e32 v52, 0, v52
	v_max_f32_e32 v53, 0, v53
	v_max_f32_e32 v54, 0, v54
	v_max_f32_e32 v55, 0, v55
	v_max_f32_e32 v48, 0, v48
	v_max_f32_e32 v49, 0, v49
	v_max_f32_e32 v50, 0, v50
	v_max_f32_e32 v51, 0, v51
	v_pk_mul_f32 v[52:53], v[52:53], v[52:53]
	v_pk_mul_f32 v[54:55], v[54:55], v[54:55]
	v_pk_mul_f32 v[48:49], v[48:49], v[48:49]
	v_pk_mul_f32 v[50:51], v[50:51], v[50:51]
	v_cvt_pk_bf16_f32 v174, v52, v53
	v_cvt_pk_bf16_f32 v175, v54, v55
	v_cvt_pk_bf16_f32 v176, v48, v49
	v_cvt_pk_bf16_f32 v177, v50, v51
	global_store_dwordx4 v[152:153], v[174:177], off offset:256
	v_add_co_u32_e32 v152, vcc, 0x489000, v150
	s_nop 1
	v_addc_co_u32_e32 v153, vcc, 0, v151, vcc
	v_cvt_f32_i32_e32 v44, v44
	v_cvt_f32_i32_e32 v45, v45
	v_cvt_f32_i32_e32 v46, v46
	v_cvt_f32_i32_e32 v47, v47
	v_cvt_f32_i32_e32 v40, v40
	v_cvt_f32_i32_e32 v41, v41
	v_cvt_f32_i32_e32 v42, v42
	v_cvt_f32_i32_e32 v43, v43
	v_pk_mul_f32 v[44:45], v[242:243], v[44:45] op_sel_hi:[0,1]
	v_pk_mul_f32 v[46:47], v[242:243], v[46:47] op_sel_hi:[0,1]
	v_pk_mul_f32 v[40:41], v[242:243], v[40:41] op_sel_hi:[0,1]
	v_pk_mul_f32 v[42:43], v[242:243], v[42:43] op_sel_hi:[0,1]
	v_max_f32_e32 v44, 0, v44
	v_max_f32_e32 v45, 0, v45
	v_max_f32_e32 v46, 0, v46
	v_max_f32_e32 v47, 0, v47
	v_max_f32_e32 v40, 0, v40
	v_max_f32_e32 v41, 0, v41
	v_max_f32_e32 v42, 0, v42
	v_max_f32_e32 v43, 0, v43
	v_pk_mul_f32 v[44:45], v[44:45], v[44:45]
	v_pk_mul_f32 v[46:47], v[46:47], v[46:47]
	v_pk_mul_f32 v[40:41], v[40:41], v[40:41]
	v_pk_mul_f32 v[42:43], v[42:43], v[42:43]
	v_cvt_pk_bf16_f32 v178, v44, v45
	v_cvt_pk_bf16_f32 v179, v46, v47
	v_cvt_pk_bf16_f32 v180, v40, v41
	v_cvt_pk_bf16_f32 v181, v42, v43
	global_store_dwordx4 v[152:153], v[178:181], off
	v_cvt_f32_i32_e32 v36, v36
	v_cvt_f32_i32_e32 v37, v37
	v_cvt_f32_i32_e32 v38, v38
	v_cvt_f32_i32_e32 v39, v39
	v_cvt_f32_i32_e32 v32, v32
	v_cvt_f32_i32_e32 v33, v33
	v_cvt_f32_i32_e32 v34, v34
	v_cvt_f32_i32_e32 v35, v35
	v_pk_mul_f32 v[36:37], v[242:243], v[36:37] op_sel_hi:[0,1]
	v_pk_mul_f32 v[38:39], v[242:243], v[38:39] op_sel_hi:[0,1]
	v_pk_mul_f32 v[32:33], v[242:243], v[32:33] op_sel_hi:[0,1]
	v_pk_mul_f32 v[34:35], v[242:243], v[34:35] op_sel_hi:[0,1]
	v_max_f32_e32 v36, 0, v36
	v_max_f32_e32 v37, 0, v37
	v_max_f32_e32 v38, 0, v38
	v_max_f32_e32 v39, 0, v39
	v_max_f32_e32 v32, 0, v32
	v_max_f32_e32 v33, 0, v33
	v_max_f32_e32 v34, 0, v34
	v_max_f32_e32 v35, 0, v35
	v_pk_mul_f32 v[36:37], v[36:37], v[36:37]
	v_pk_mul_f32 v[38:39], v[38:39], v[38:39]
	v_pk_mul_f32 v[32:33], v[32:33], v[32:33]
	v_pk_mul_f32 v[34:35], v[34:35], v[34:35]
	v_cvt_pk_bf16_f32 v182, v36, v37
	v_cvt_pk_bf16_f32 v183, v38, v39
	v_cvt_pk_bf16_f32 v184, v32, v33
	v_cvt_pk_bf16_f32 v185, v34, v35
	global_store_dwordx4 v[152:153], v[182:185], off offset:256
	v_add_co_u32_e32 v152, vcc, 0x50a000, v150
	s_nop 1
	v_addc_co_u32_e32 v153, vcc, 0, v151, vcc
	v_cvt_f32_i32_e32 v28, v28
	v_cvt_f32_i32_e32 v29, v29
	v_cvt_f32_i32_e32 v30, v30
	v_cvt_f32_i32_e32 v31, v31
	v_cvt_f32_i32_e32 v24, v24
	v_cvt_f32_i32_e32 v25, v25
	v_cvt_f32_i32_e32 v26, v26
	v_cvt_f32_i32_e32 v27, v27
	v_pk_mul_f32 v[28:29], v[244:245], v[28:29] op_sel_hi:[0,1]
	v_pk_mul_f32 v[30:31], v[244:245], v[30:31] op_sel_hi:[0,1]
	v_pk_mul_f32 v[24:25], v[244:245], v[24:25] op_sel_hi:[0,1]
	v_pk_mul_f32 v[26:27], v[244:245], v[26:27] op_sel_hi:[0,1]
	v_max_f32_e32 v28, 0, v28
	v_max_f32_e32 v29, 0, v29
	v_max_f32_e32 v30, 0, v30
	v_max_f32_e32 v31, 0, v31
	v_max_f32_e32 v24, 0, v24
	v_max_f32_e32 v25, 0, v25
	v_max_f32_e32 v26, 0, v26
	v_max_f32_e32 v27, 0, v27
	v_pk_mul_f32 v[28:29], v[28:29], v[28:29]
	v_pk_mul_f32 v[30:31], v[30:31], v[30:31]
	v_pk_mul_f32 v[24:25], v[24:25], v[24:25]
	v_pk_mul_f32 v[26:27], v[26:27], v[26:27]
	v_cvt_pk_bf16_f32 v186, v28, v29
	v_cvt_pk_bf16_f32 v187, v30, v31
	v_cvt_pk_bf16_f32 v188, v24, v25
	v_cvt_pk_bf16_f32 v189, v26, v27
	global_store_dwordx4 v[152:153], v[186:189], off
	v_cvt_f32_i32_e32 v20, v20
	v_cvt_f32_i32_e32 v21, v21
	v_cvt_f32_i32_e32 v22, v22
	v_cvt_f32_i32_e32 v23, v23
	v_cvt_f32_i32_e32 v16, v16
	v_cvt_f32_i32_e32 v17, v17
	v_cvt_f32_i32_e32 v18, v18
	v_cvt_f32_i32_e32 v19, v19
	v_pk_mul_f32 v[20:21], v[244:245], v[20:21] op_sel_hi:[0,1]
	v_pk_mul_f32 v[22:23], v[244:245], v[22:23] op_sel_hi:[0,1]
	v_pk_mul_f32 v[16:17], v[244:245], v[16:17] op_sel_hi:[0,1]
	v_pk_mul_f32 v[18:19], v[244:245], v[18:19] op_sel_hi:[0,1]
	v_max_f32_e32 v20, 0, v20
	v_max_f32_e32 v21, 0, v21
	v_max_f32_e32 v22, 0, v22
	v_max_f32_e32 v23, 0, v23
	v_max_f32_e32 v16, 0, v16
	v_max_f32_e32 v17, 0, v17
	v_max_f32_e32 v18, 0, v18
	v_max_f32_e32 v19, 0, v19
	v_pk_mul_f32 v[20:21], v[20:21], v[20:21]
	v_pk_mul_f32 v[22:23], v[22:23], v[22:23]
	v_pk_mul_f32 v[16:17], v[16:17], v[16:17]
	v_pk_mul_f32 v[18:19], v[18:19], v[18:19]
	v_cvt_pk_bf16_f32 v190, v20, v21
	v_cvt_pk_bf16_f32 v191, v22, v23
	v_cvt_pk_bf16_f32 v192, v16, v17
	v_cvt_pk_bf16_f32 v193, v18, v19
	global_store_dwordx4 v[152:153], v[190:193], off offset:256
	v_add_co_u32_e32 v152, vcc, 0x58b000, v150
	s_nop 1
	v_addc_co_u32_e32 v153, vcc, 0, v151, vcc
	v_cvt_f32_i32_e32 v12, v12
	v_cvt_f32_i32_e32 v13, v13
	v_cvt_f32_i32_e32 v14, v14
	v_cvt_f32_i32_e32 v15, v15
	v_cvt_f32_i32_e32 v8, v8
	v_cvt_f32_i32_e32 v9, v9
	v_cvt_f32_i32_e32 v10, v10
	v_cvt_f32_i32_e32 v11, v11
	v_pk_mul_f32 v[12:13], v[246:247], v[12:13] op_sel_hi:[0,1]
	v_pk_mul_f32 v[14:15], v[246:247], v[14:15] op_sel_hi:[0,1]
	v_pk_mul_f32 v[8:9], v[246:247], v[8:9] op_sel_hi:[0,1]
	v_pk_mul_f32 v[10:11], v[246:247], v[10:11] op_sel_hi:[0,1]
	v_max_f32_e32 v12, 0, v12
	v_max_f32_e32 v13, 0, v13
	v_max_f32_e32 v14, 0, v14
	v_max_f32_e32 v15, 0, v15
	v_max_f32_e32 v8, 0, v8
	v_max_f32_e32 v9, 0, v9
	v_max_f32_e32 v10, 0, v10
	v_max_f32_e32 v11, 0, v11
	v_pk_mul_f32 v[12:13], v[12:13], v[12:13]
	v_pk_mul_f32 v[14:15], v[14:15], v[14:15]
	v_pk_mul_f32 v[8:9], v[8:9], v[8:9]
	v_pk_mul_f32 v[10:11], v[10:11], v[10:11]
	v_cvt_pk_bf16_f32 v194, v12, v13
	v_cvt_pk_bf16_f32 v195, v14, v15
	v_cvt_pk_bf16_f32 v196, v8, v9
	v_cvt_pk_bf16_f32 v197, v10, v11
	global_store_dwordx4 v[152:153], v[194:197], off
	v_cvt_f32_i32_e32 v4, v4
	v_cvt_f32_i32_e32 v5, v5
	v_cvt_f32_i32_e32 v6, v6
	v_cvt_f32_i32_e32 v7, v7
	v_cvt_f32_i32_e32 v0, v0
	v_cvt_f32_i32_e32 v1, v1
	v_cvt_f32_i32_e32 v2, v2
	v_cvt_f32_i32_e32 v3, v3
	v_pk_mul_f32 v[4:5], v[246:247], v[4:5] op_sel_hi:[0,1]
	v_pk_mul_f32 v[6:7], v[246:247], v[6:7] op_sel_hi:[0,1]
	v_pk_mul_f32 v[0:1], v[246:247], v[0:1] op_sel_hi:[0,1]
	v_pk_mul_f32 v[2:3], v[246:247], v[2:3] op_sel_hi:[0,1]
	v_max_f32_e32 v4, 0, v4
	v_max_f32_e32 v5, 0, v5
	v_max_f32_e32 v6, 0, v6
	v_max_f32_e32 v7, 0, v7
	v_max_f32_e32 v0, 0, v0
	v_max_f32_e32 v1, 0, v1
	v_max_f32_e32 v2, 0, v2
	v_max_f32_e32 v3, 0, v3
	v_pk_mul_f32 v[4:5], v[4:5], v[4:5]
	v_pk_mul_f32 v[6:7], v[6:7], v[6:7]
	v_pk_mul_f32 v[0:1], v[0:1], v[0:1]
	v_pk_mul_f32 v[2:3], v[2:3], v[2:3]
	v_cvt_pk_bf16_f32 v198, v4, v5
	v_cvt_pk_bf16_f32 v199, v6, v7
	v_cvt_pk_bf16_f32 v200, v0, v1
	v_cvt_pk_bf16_f32 v201, v2, v3
	global_store_dwordx4 v[152:153], v[198:201], off offset:256
	s_andn2_b64 vcc, exec, s[2:3]
	s_mov_b64 s[0:1], -1
	s_cbranch_vccnz .LBB0_542
	s_branch .Ljoin_p5

.LBB0_614:
	s_mov_b64 s[0:1], s[78:79]
	s_load_dword s0, s[0:1], 0xa8
	s_waitcnt lgkmcnt(0)
	s_cmp_gt_i32 s0, 6
	s_cbranch_scc1 .LBB0_658
	s_mov_b64 s[0:1], s[78:79]
	s_load_dword s0, s[0:1], 0xac
	s_waitcnt lgkmcnt(0)
	s_cmp_lt_i32 s0, 7
	s_cbranch_scc1 .LBB0_658
	s_mov_b32 s94, 0
	s_mov_b64 s[0:1], s[78:79]
	s_load_dwordx2 s[2:3], s[0:1], 0xa0
	s_cmpk_lt_i32 s87, 0x400
	s_mov_b32 s6, -1
	s_cselect_b64 s[0:1], -1, 0
	s_cmpk_gt_i32 s87, 0x3ff
	s_cbranch_scc1 .LBB0_622
	s_ashr_i32 s4, s87, 31
	s_lshr_b32 s4, s4, 29
	s_add_i32 s7, s87, s4
	s_and_b32 s4, s7, -8
	s_sub_i32 s8, s87, s4
	s_cmp_gt_i32 s8, -1
	s_cbranch_scc0 .LBB0_619
	s_lshl_b32 s9, s8, 7
	s_cbranch_execz .LBB0_620
	s_branch .LBB0_621

.Lsp_skip5:
.LBB0_635:
	ds_read_b128 v[112:115], v193
	ds_read_b128 v[124:127], v193 offset:1024
	ds_read_b128 v[136:139], v193 offset:2048
	ds_read_b128 v[140:143], v193 offset:3072
	ds_read_b128 v[144:147], v194
	ds_read_b128 v[148:151], v194 offset:1024
	ds_read_b128 v[168:171], v194 offset:2048
	ds_read_b128 v[172:175], v194 offset:3072
	ds_read_b128 v[176:179], v195
	ds_read_b128 v[180:183], v195 offset:1024
	ds_read_b128 v[184:187], v195 offset:2048
	ds_read_b128 v[200:203], v195 offset:3072
	ds_read_b128 v[204:207], v195 offset:4096
	ds_read_b128 v[208:211], v195 offset:5120
	ds_read_b128 v[212:215], v195 offset:6144
	ds_read_b128 v[216:219], v195 offset:7168
	s_add_u32 s34, s30, 0xffbf8080
	s_addc_u32 s35, s31, -1
	s_cmpk_eq_i32 s58, 0xfc
	s_cselect_b32 s37, s21, s35
	s_cselect_b32 s36, s27, s34
	s_cselect_b32 s35, s19, s57
	s_cselect_b32 s34, s55, s56
	s_add_i32 m0, s29, 0xc000
	s_nop 0
	global_load_lds_dwordx4 v162, s[30:31]
	s_add_i32 m0, s29, 0xe000
	s_nop 0
	global_load_lds_dwordx4 v160, s[30:31]
	s_cmp_eq_u32 s94, 1
	s_cbranch_scc1 .Lrx6_0a
	s_waitcnt vmcnt(8)
	s_branch .Lrx6_0b

.Lrx6_0b:
	s_waitcnt lgkmcnt(0)
	s_barrier
	s_waitcnt lgkmcnt(0)
	v_mfma_f32_16x16x32_bf16 v[132:135], v[112:115], v[176:179], v[132:135]
	v_mfma_f32_16x16x32_bf16 v[128:131], v[136:139], v[176:179], v[128:131]
	v_mfma_f32_16x16x32_bf16 v[108:111], v[112:115], v[184:187], v[108:111]
	v_mfma_f32_16x16x32_bf16 v[104:107], v[136:139], v[184:187], v[104:107]
	s_add_u32 s98, s34, s14
	s_addc_u32 s99, s35, s15
	s_add_i32 s59, s50, s41
	v_mfma_f32_16x16x32_bf16 v[92:95], v[112:115], v[204:207], v[92:95]
	s_add_u32 s100, s36, s14
	s_addc_u32 s101, s37, s15
	v_mfma_f32_16x16x32_bf16 v[88:91], v[136:139], v[204:207], v[88:91]
	v_mfma_f32_16x16x32_bf16 v[76:79], v[112:115], v[212:215], v[76:79]
	v_mfma_f32_16x16x32_bf16 v[72:75], v[136:139], v[212:215], v[72:75]
	s_add_u32 s60, s34, 0x400000
	v_mfma_f32_16x16x32_bf16 v[132:135], v[124:127], v[180:183], v[132:135]
	v_mfma_f32_16x16x32_bf16 v[128:131], v[140:143], v[180:183], v[128:131]
	v_mfma_f32_16x16x32_bf16 v[108:111], v[124:127], v[200:203], v[108:111]
	v_mfma_f32_16x16x32_bf16 v[104:107], v[140:143], v[200:203], v[104:107]
	s_addc_u32 s61, s35, 0
	v_mfma_f32_16x16x32_bf16 v[92:95], v[124:127], v[208:211], v[92:95]
	v_mfma_f32_16x16x32_bf16 v[88:91], v[140:143], v[208:211], v[88:91]
	v_mfma_f32_16x16x32_bf16 v[76:79], v[124:127], v[216:219], v[76:79]
	v_mfma_f32_16x16x32_bf16 v[72:75], v[140:143], v[216:219], v[72:75]
	v_mfma_f32_16x16x32_bf16 v[120:123], v[144:147], v[176:179], v[120:123]
	v_mfma_f32_16x16x32_bf16 v[116:119], v[168:171], v[176:179], v[116:119]
	v_mfma_f32_16x16x32_bf16 v[100:103], v[144:147], v[184:187], v[100:103]
	v_mfma_f32_16x16x32_bf16 v[96:99], v[168:171], v[184:187], v[96:99]
	v_mfma_f32_16x16x32_bf16 v[84:87], v[144:147], v[204:207], v[84:87]
	v_mfma_f32_16x16x32_bf16 v[80:83], v[168:171], v[204:207], v[80:83]
	v_mfma_f32_16x16x32_bf16 v[68:71], v[144:147], v[212:215], v[68:71]
	v_mfma_f32_16x16x32_bf16 v[64:67], v[168:171], v[212:215], v[64:67]
	v_mfma_f32_16x16x32_bf16 v[120:123], v[148:151], v[180:183], v[120:123]
	v_mfma_f32_16x16x32_bf16 v[116:119], v[172:175], v[180:183], v[116:119]
	v_mfma_f32_16x16x32_bf16 v[100:103], v[148:151], v[200:203], v[100:103]
	v_mfma_f32_16x16x32_bf16 v[96:99], v[172:175], v[200:203], v[96:99]
	v_mfma_f32_16x16x32_bf16 v[84:87], v[148:151], v[208:211], v[84:87]
	v_mfma_f32_16x16x32_bf16 v[80:83], v[172:175], v[208:211], v[80:83]
	v_mfma_f32_16x16x32_bf16 v[68:71], v[148:151], v[216:219], v[68:71]
	v_mfma_f32_16x16x32_bf16 v[64:67], v[172:175], v[216:219], v[64:67]
	s_barrier
	ds_read_b128 v[176:179], v195 offset:16384
	ds_read_b128 v[180:183], v195 offset:17408
	ds_read_b128 v[184:187], v195 offset:18432
	ds_read_b128 v[200:203], v195 offset:19456
	ds_read_b128 v[204:207], v195 offset:20480
	ds_read_b128 v[208:211], v195 offset:21504
	ds_read_b128 v[212:215], v195 offset:22528
	ds_read_b128 v[216:219], v195 offset:23552
	s_mov_b32 m0, s59
	s_nop 0
	global_load_lds_dwordx4 v154, s[34:35]
	s_add_i32 m0, s59, 0x2000
	s_add_i32 s59, s51, s41
	global_load_lds_dwordx4 v158, s[34:35]
	s_mov_b32 m0, s59
	s_nop 0
	global_load_lds_dwordx4 v154, s[60:61]
	s_add_i32 m0, s59, 0x2000
	s_nop 0
	global_load_lds_dwordx4 v158, s[60:61]
	s_mov_b32 m0, s29
	s_nop 0
	global_load_lds_dwordx4 v152, s[36:37]
	s_mov_b32 m0, s42
	s_nop 0
	global_load_lds_dwordx4 v156, s[36:37]
	s_cmp_eq_u32 s94, 1
	s_cbranch_scc1 .Lrx6_1a
	s_waitcnt vmcnt(8)
	s_branch .Lrx6_1b

.Lrx6_1b:
	s_mov_b32 s94, 0
	s_waitcnt lgkmcnt(0)
	s_barrier
	s_waitcnt lgkmcnt(0)
	v_mfma_f32_16x16x32_bf16 v[60:63], v[112:115], v[176:179], v[60:63]
	v_mfma_f32_16x16x32_bf16 v[56:59], v[136:139], v[176:179], v[56:59]
	v_mfma_f32_16x16x32_bf16 v[44:47], v[112:115], v[184:187], v[44:47]
	v_mfma_f32_16x16x32_bf16 v[40:43], v[136:139], v[184:187], v[40:43]
	s_add_i32 s59, 0, 0x18000
	v_mfma_f32_16x16x32_bf16 v[28:31], v[112:115], v[204:207], v[28:31]
	v_mfma_f32_16x16x32_bf16 v[24:27], v[136:139], v[204:207], v[24:27]
	s_add_i32 s60, 0, 0x1c000
	v_mfma_f32_16x16x32_bf16 v[12:15], v[112:115], v[212:215], v[12:15]
	v_mfma_f32_16x16x32_bf16 v[8:11], v[136:139], v[212:215], v[8:11]
	s_add_u32 s36, s36, 0x408000
	v_mfma_f32_16x16x32_bf16 v[60:63], v[124:127], v[180:183], v[60:63]
	v_mfma_f32_16x16x32_bf16 v[56:59], v[140:143], v[180:183], v[56:59]
	s_addc_u32 s37, s37, 0
	v_mfma_f32_16x16x32_bf16 v[44:47], v[124:127], v[200:203], v[44:47]
	v_mfma_f32_16x16x32_bf16 v[40:43], v[140:143], v[200:203], v[40:43]
	v_mfma_f32_16x16x32_bf16 v[28:31], v[124:127], v[208:211], v[28:31]
	v_mfma_f32_16x16x32_bf16 v[24:27], v[140:143], v[208:211], v[24:27]
	v_mfma_f32_16x16x32_bf16 v[12:15], v[124:127], v[216:219], v[12:15]
	v_mfma_f32_16x16x32_bf16 v[8:11], v[140:143], v[216:219], v[8:11]
	v_mfma_f32_16x16x32_bf16 v[52:55], v[144:147], v[176:179], v[52:55]
	v_mfma_f32_16x16x32_bf16 v[48:51], v[168:171], v[176:179], v[48:51]
	v_mfma_f32_16x16x32_bf16 v[36:39], v[144:147], v[184:187], v[36:39]
	v_mfma_f32_16x16x32_bf16 v[32:35], v[168:171], v[184:187], v[32:35]
	v_mfma_f32_16x16x32_bf16 v[20:23], v[144:147], v[204:207], v[20:23]
	v_mfma_f32_16x16x32_bf16 v[16:19], v[168:171], v[204:207], v[16:19]
	v_mfma_f32_16x16x32_bf16 v[4:7], v[144:147], v[212:215], v[4:7]
	v_mfma_f32_16x16x32_bf16 v[0:3], v[168:171], v[212:215], v[0:3]
	v_mfma_f32_16x16x32_bf16 v[52:55], v[148:151], v[180:183], v[52:55]
	v_mfma_f32_16x16x32_bf16 v[48:51], v[172:175], v[180:183], v[48:51]
	v_mfma_f32_16x16x32_bf16 v[36:39], v[148:151], v[200:203], v[36:39]
	v_mfma_f32_16x16x32_bf16 v[32:35], v[172:175], v[200:203], v[32:35]
	v_mfma_f32_16x16x32_bf16 v[20:23], v[148:151], v[208:211], v[20:23]
	v_mfma_f32_16x16x32_bf16 v[16:19], v[172:175], v[208:211], v[16:19]
	v_mfma_f32_16x16x32_bf16 v[4:7], v[148:151], v[216:219], v[4:7]
	v_mfma_f32_16x16x32_bf16 v[0:3], v[172:175], v[216:219], v[0:3]
	s_barrier
	ds_read_b128 v[176:179], v195 offset:32768
	ds_read_b128 v[180:183], v195 offset:33792
	ds_read_b128 v[184:187], v195 offset:34816
	ds_read_b128 v[200:203], v195 offset:35840
	ds_read_b128 v[204:207], v195 offset:36864
	ds_read_b128 v[208:211], v195 offset:37888
	ds_read_b128 v[212:215], v195 offset:38912
	ds_read_b128 v[216:219], v195 offset:39936
	v_add_u32_e32 v140, s59, v191
	v_add_u32_e32 v172, s60, v191
	ds_read_b128 v[112:115], v140
	ds_read_b128 v[124:127], v140 offset:1024
	ds_read_b128 v[136:139], v140 offset:2048
	ds_read_b128 v[140:143], v140 offset:3072
	ds_read_b128 v[144:147], v172
	ds_read_b128 v[148:151], v172 offset:1024
	ds_read_b128 v[168:171], v172 offset:2048
	ds_read_b128 v[172:175], v172 offset:3072
	s_mov_b32 m0, s43
	s_nop 0
	global_load_lds_dwordx4 v152, s[36:37]
	s_mov_b32 m0, s44
	s_nop 0
	global_load_lds_dwordx4 v156, s[36:37]
	s_waitcnt vmcnt(8)
	s_waitcnt lgkmcnt(0)
	s_barrier
	s_waitcnt lgkmcnt(0)
	v_mfma_f32_16x16x32_bf16 v[132:135], v[112:115], v[176:179], v[132:135]
	v_mfma_f32_16x16x32_bf16 v[128:131], v[136:139], v[176:179], v[128:131]
	v_mfma_f32_16x16x32_bf16 v[108:111], v[112:115], v[184:187], v[108:111]
	v_mfma_f32_16x16x32_bf16 v[104:107], v[136:139], v[184:187], v[104:107]
	s_add_i32 s36, s59, s41
	v_mfma_f32_16x16x32_bf16 v[92:95], v[112:115], v[204:207], v[92:95]
	v_mfma_f32_16x16x32_bf16 v[88:91], v[136:139], v[204:207], v[88:91]
	v_mfma_f32_16x16x32_bf16 v[76:79], v[112:115], v[212:215], v[76:79]
	v_mfma_f32_16x16x32_bf16 v[72:75], v[136:139], v[212:215], v[72:75]
	s_add_u32 s34, s34, 0x400080
	v_mfma_f32_16x16x32_bf16 v[132:135], v[124:127], v[180:183], v[132:135]
	v_mfma_f32_16x16x32_bf16 v[128:131], v[140:143], v[180:183], v[128:131]
	v_mfma_f32_16x16x32_bf16 v[108:111], v[124:127], v[200:203], v[108:111]
	v_mfma_f32_16x16x32_bf16 v[104:107], v[140:143], v[200:203], v[104:107]
	s_addc_u32 s35, s35, 0
	v_mfma_f32_16x16x32_bf16 v[92:95], v[124:127], v[208:211], v[92:95]
	v_mfma_f32_16x16x32_bf16 v[88:91], v[140:143], v[208:211], v[88:91]
	v_mfma_f32_16x16x32_bf16 v[76:79], v[124:127], v[216:219], v[76:79]
	v_mfma_f32_16x16x32_bf16 v[72:75], v[140:143], v[216:219], v[72:75]
	v_mfma_f32_16x16x32_bf16 v[120:123], v[144:147], v[176:179], v[120:123]
	v_mfma_f32_16x16x32_bf16 v[116:119], v[168:171], v[176:179], v[116:119]
	v_mfma_f32_16x16x32_bf16 v[100:103], v[144:147], v[184:187], v[100:103]
	v_mfma_f32_16x16x32_bf16 v[96:99], v[168:171], v[184:187], v[96:99]
	v_mfma_f32_16x16x32_bf16 v[84:87], v[144:147], v[204:207], v[84:87]
	v_mfma_f32_16x16x32_bf16 v[80:83], v[168:171], v[204:207], v[80:83]
	v_mfma_f32_16x16x32_bf16 v[68:71], v[144:147], v[212:215], v[68:71]
	v_mfma_f32_16x16x32_bf16 v[64:67], v[168:171], v[212:215], v[64:67]
	v_mfma_f32_16x16x32_bf16 v[120:123], v[148:151], v[180:183], v[120:123]
	v_mfma_f32_16x16x32_bf16 v[116:119], v[172:175], v[180:183], v[116:119]
	v_mfma_f32_16x16x32_bf16 v[100:103], v[148:151], v[200:203], v[100:103]
	v_mfma_f32_16x16x32_bf16 v[96:99], v[172:175], v[200:203], v[96:99]
	v_mfma_f32_16x16x32_bf16 v[84:87], v[148:151], v[208:211], v[84:87]
	v_mfma_f32_16x16x32_bf16 v[80:83], v[172:175], v[208:211], v[80:83]
	v_mfma_f32_16x16x32_bf16 v[68:71], v[148:151], v[216:219], v[68:71]
	v_mfma_f32_16x16x32_bf16 v[64:67], v[172:175], v[216:219], v[64:67]
	s_barrier
	ds_read_b128 v[176:179], v195 offset:49152
	ds_read_b128 v[180:183], v195 offset:50176
	ds_read_b128 v[184:187], v195 offset:51200
	ds_read_b128 v[200:203], v195 offset:52224
	ds_read_b128 v[204:207], v195 offset:53248
	ds_read_b128 v[208:211], v195 offset:54272
	ds_read_b128 v[212:215], v195 offset:55296
	ds_read_b128 v[216:219], v195 offset:56320
	s_mov_b32 m0, s36
	s_nop 0
	global_load_lds_dwordx4 v154, s[98:99]
	s_add_i32 m0, s36, 0x2000
	s_add_i32 s36, s60, s41
	global_load_lds_dwordx4 v158, s[98:99]
	s_mov_b32 m0, s36
	s_nop 0
	global_load_lds_dwordx4 v154, s[34:35]
	s_add_i32 m0, s36, 0x2000
	s_nop 0
	global_load_lds_dwordx4 v158, s[34:35]
	s_mov_b32 m0, s46
	s_nop 0
	global_load_lds_dwordx4 v152, s[100:101]
	s_mov_b32 m0, s47
	s_nop 0
	global_load_lds_dwordx4 v156, s[100:101]
	s_waitcnt vmcnt(8)
	s_waitcnt lgkmcnt(0)
	s_barrier
	s_waitcnt lgkmcnt(0)
	v_mfma_f32_16x16x32_bf16 v[60:63], v[112:115], v[176:179], v[60:63]
	v_mfma_f32_16x16x32_bf16 v[56:59], v[136:139], v[176:179], v[56:59]
	v_mfma_f32_16x16x32_bf16 v[44:47], v[112:115], v[184:187], v[44:47]
	v_mfma_f32_16x16x32_bf16 v[40:43], v[136:139], v[184:187], v[40:43]
	v_mfma_f32_16x16x32_bf16 v[28:31], v[112:115], v[204:207], v[28:31]
	v_mfma_f32_16x16x32_bf16 v[24:27], v[136:139], v[204:207], v[24:27]
	v_mfma_f32_16x16x32_bf16 v[12:15], v[112:115], v[212:215], v[12:15]
	v_mfma_f32_16x16x32_bf16 v[8:11], v[136:139], v[212:215], v[8:11]
	v_mfma_f32_16x16x32_bf16 v[60:63], v[124:127], v[180:183], v[60:63]
	v_mfma_f32_16x16x32_bf16 v[56:59], v[140:143], v[180:183], v[56:59]
	v_mfma_f32_16x16x32_bf16 v[44:47], v[124:127], v[200:203], v[44:47]
	v_mfma_f32_16x16x32_bf16 v[40:43], v[140:143], v[200:203], v[40:43]
	v_mfma_f32_16x16x32_bf16 v[28:31], v[124:127], v[208:211], v[28:31]
	v_mfma_f32_16x16x32_bf16 v[24:27], v[140:143], v[208:211], v[24:27]
	v_mfma_f32_16x16x32_bf16 v[12:15], v[124:127], v[216:219], v[12:15]
	v_mfma_f32_16x16x32_bf16 v[8:11], v[140:143], v[216:219], v[8:11]
	v_mfma_f32_16x16x32_bf16 v[52:55], v[144:147], v[176:179], v[52:55]
	v_mfma_f32_16x16x32_bf16 v[48:51], v[168:171], v[176:179], v[48:51]
	v_mfma_f32_16x16x32_bf16 v[36:39], v[144:147], v[184:187], v[36:39]
	v_mfma_f32_16x16x32_bf16 v[32:35], v[168:171], v[184:187], v[32:35]
	v_mfma_f32_16x16x32_bf16 v[20:23], v[144:147], v[204:207], v[20:23]
	v_mfma_f32_16x16x32_bf16 v[16:19], v[168:171], v[204:207], v[16:19]
	v_mfma_f32_16x16x32_bf16 v[4:7], v[144:147], v[212:215], v[4:7]
	v_mfma_f32_16x16x32_bf16 v[0:3], v[168:171], v[212:215], v[0:3]
	v_mfma_f32_16x16x32_bf16 v[52:55], v[148:151], v[180:183], v[52:55]
	v_mfma_f32_16x16x32_bf16 v[48:51], v[172:175], v[180:183], v[48:51]
	v_mfma_f32_16x16x32_bf16 v[36:39], v[148:151], v[200:203], v[36:39]
	v_mfma_f32_16x16x32_bf16 v[32:35], v[172:175], v[200:203], v[32:35]
	v_mfma_f32_16x16x32_bf16 v[20:23], v[148:151], v[208:211], v[20:23]
	v_mfma_f32_16x16x32_bf16 v[16:19], v[172:175], v[208:211], v[16:19]
	v_mfma_f32_16x16x32_bf16 v[4:7], v[148:151], v[216:219], v[4:7]
	v_mfma_f32_16x16x32_bf16 v[0:3], v[172:175], v[216:219], v[0:3]
	s_barrier
	s_add_i32 s58, s58, 2
	s_add_u32 s56, s56, 0x100
	s_addc_u32 s57, s57, 0
	s_add_u32 s30, s30, 0x100
	s_addc_u32 s31, s31, 0
	s_cmpk_gt_u32 s58, 0xfd
	s_cbranch_scc0 .LBB0_635
	s_setprio 0
	s_and_b64 vcc, exec, s[16:17]
	s_cbranch_vccz .LBB0_638
	s_barrier
.LBB0_638:
	v_lshl_add_u32 v174, s26, 8, v190
	v_lshl_or_b32 v168, s28, 8, v192
	v_ashrrev_i32_e32 v169, 31, v168
	v_ashrrev_i32_e32 v175, 31, v174
	v_lshl_add_u64 v[172:173], v[168:169], 1, s[6:7]
	v_lshlrev_b64 v[112:113], 13, v[174:175]
	v_lshl_add_u64 v[170:171], v[174:175], 3, s[8:9]
	v_lshl_add_u64 v[188:189], v[172:173], 0, v[112:113]
	global_load_dwordx2 v[208:209], v[170:171], off
	global_load_dwordx2 v[232:233], v[170:171], off offset:128
	global_load_dwordx2 v[234:235], v[170:171], off offset:256
	global_load_dwordx2 v[236:237], v[170:171], off offset:384
	global_load_dwordx2 v[238:239], v[170:171], off offset:1024
	global_load_dwordx2 v[240:241], v[170:171], off offset:1152
	global_load_dwordx2 v[242:243], v[170:171], off offset:1280
	global_load_dwordx2 v[244:245], v[170:171], off offset:1408
	global_load_dwordx4 v[200:203], v[188:189], off
	v_or_b32_e32 v184, 16, v174
	v_or_b32_e32 v180, 32, v174
	v_or_b32_e32 v176, 48, v174
	v_ashrrev_i32_e32 v185, 31, v184
	v_ashrrev_i32_e32 v181, 31, v180
	v_ashrrev_i32_e32 v177, 31, v176
	v_lshlrev_b64 v[112:113], 12, v[174:175]
	v_lshlrev_b64 v[114:115], 13, v[184:185]
	v_lshlrev_b64 v[124:125], 13, v[180:181]
	v_lshlrev_b64 v[126:127], 13, v[176:177]
	v_lshl_add_u64 v[112:113], v[112:113], 0, v[168:169]
	v_lshl_add_u64 v[186:187], v[172:173], 0, v[114:115]
	v_lshl_add_u64 v[182:183], v[172:173], 0, v[124:125]
	v_lshl_add_u64 v[178:179], v[172:173], 0, v[126:127]
	v_lshl_add_u64 v[210:211], s[12:13], 0, v[112:113]
	global_load_dwordx4 v[204:207], v[188:189], off offset:256
	global_load_dwordx4 v[148:151], v[186:187], off
	global_load_dwordx4 v[144:147], v[186:187], off offset:256
	global_load_dwordx4 v[140:143], v[182:183], off
	global_load_dwordx4 v[136:139], v[182:183], off offset:256
	global_load_dwordx4 v[124:127], v[178:179], off
	global_load_dwordx4 v[112:115], v[178:179], off offset:256
	s_mov_b64 s[96:97], 0x100000
	v_lshl_add_u64 v[220:221], v[188:189], 0, s[96:97]
	global_load_dwordx4 v[220:223], v[220:221], off
	v_lshl_add_u64 v[224:225], v[188:189], 0, s[96:97]
	global_load_dwordx4 v[224:227], v[224:225], off offset:256
	v_lshl_add_u64 v[228:229], v[186:187], 0, s[96:97]
	global_load_dwordx4 v[228:231], v[228:229], off
	v_lshl_add_u64 v[246:247], v[186:187], 0, s[96:97]
	global_load_dwordx4 v[246:249], v[246:247], off offset:256
	v_lshl_add_u64 v[250:251], v[182:183], 0, s[96:97]
	global_load_dwordx4 v[250:253], v[250:251], off
	v_lshl_add_u64 v[216:217], v[182:183], 0, s[96:97]
	global_load_dwordx4 v[216:219], v[216:217], off offset:256
	s_waitcnt vmcnt(0)
	s_mov_b32 s94, 1
	v_ffbh_u32_e32 v199, v209
	v_min_u32_e32 v199, 32, v199
	v_lshlrev_b64 v[208:209], v199, v[208:209]
	v_min_u32_e32 v208, 1, v208
	v_or_b32_e32 v208, v209, v208
	v_cvt_f32_u32_e32 v208, v208
	v_lshlrev_b32_e32 v212, 16, v200
	v_and_b32_e32 v213, 0xffff0000, v200
	v_lshlrev_b32_e32 v200, 16, v201
	v_and_b32_e32 v201, 0xffff0000, v201
	v_lshlrev_b32_e32 v214, 16, v202
	v_and_b32_e32 v215, 0xffff0000, v202
	v_lshlrev_b32_e32 v202, 16, v203
	v_and_b32_e32 v203, 0xffff0000, v203
	v_pk_add_f32 v[134:135], v[134:135], v[200:201]
	v_pk_add_f32 v[132:133], v[132:133], v[212:213]
	v_pk_add_f32 v[200:201], v[130:131], v[202:203]
	v_pk_add_f32 v[202:203], v[128:129], v[214:215]
	v_sub_u32_e32 v199, 32, v199
	v_cvt_pk_bf16_f32 v128, v132, v133
	v_cvt_pk_bf16_f32 v129, v134, v135
	v_cvt_pk_bf16_f32 v130, v202, v203
	v_cvt_pk_bf16_f32 v131, v200, v201
	global_store_dwordx4 v[188:189], v[128:131], off
	v_mul_f32_e32 v212, v133, v133
	v_mul_f32_e32 v213, v135, v135
	v_ldexp_f32 v128, v208, v199
	v_fmamk_f32 v128, v128, 0x2f800000, v196
	v_rsq_f32_e32 v128, v128
	v_mul_f32_e32 v214, v203, v203
	v_fmac_f32_e32 v212, v132, v132
	v_fmac_f32_e32 v213, v134, v134
	v_fmac_f32_e32 v214, v202, v202
	v_add_f32_e32 v129, v212, v213
	v_mul_f32_e32 v199, 0x41b56db7, v128
	v_add_f32_e32 v130, v214, v129
	v_mul_f32_e32 v128, v199, v132
	v_mul_f32_e32 v129, v199, v133
	v_mul_f32_e32 v131, v199, v134
	v_mul_f32_e32 v132, v199, v135
	v_mul_f32_e32 v134, v199, v203
	v_mul_f32_e32 v133, v199, v202
	v_mul_f32_e32 v135, v199, v200
	v_mul_f32_e32 v202, v199, v201
	v_med3_f32 v128, v128, s52, v198
	v_med3_f32 v129, v129, s52, v198
	v_med3_f32 v132, v132, s52, v198
	v_med3_f32 v134, v134, s52, v198
	v_med3_f32 v131, v131, s52, v198
	v_med3_f32 v133, v133, s52, v198
	v_med3_f32 v135, v135, s52, v198
	v_med3_f32 v202, v202, s52, v198
	v_rndne_f32_e32 v128, v128
	v_rndne_f32_e32 v129, v129
	v_rndne_f32_e32 v132, v132
	v_rndne_f32_e32 v134, v134
	v_rndne_f32_e32 v131, v131
	v_rndne_f32_e32 v133, v133
	v_rndne_f32_e32 v135, v135
	v_rndne_f32_e32 v202, v202
	v_cvt_i32_f32_e32 v128, v128
	v_cvt_i32_f32_e32 v129, v129
	v_cvt_i32_f32_e32 v132, v132
	v_cvt_i32_f32_e32 v134, v134
	v_cvt_i32_f32_sdwa v131, v131 dst_sel:WORD_1 dst_unused:UNUSED_PAD src0_sel:DWORD
	v_cvt_i32_f32_e32 v133, v133
	v_cvt_i32_f32_sdwa v135, v135 dst_sel:WORD_1 dst_unused:UNUSED_PAD src0_sel:DWORD
	v_cvt_i32_f32_e32 v202, v202
	v_lshlrev_b32_e32 v129, 8, v129
	v_perm_b32 v128, v132, v128, s53
	v_lshlrev_b32_e32 v132, 8, v134
	v_and_b32_e32 v131, 0xff0000, v131
	v_and_b32_e32 v134, 0xff0000, v135
	v_perm_b32 v133, v202, v133, s53
	v_and_b32_e32 v129, 0xff00, v129
	v_and_b32_e32 v132, 0xff00, v132
	v_or3_b32 v128, v128, v129, v131
	v_or3_b32 v129, v133, v132, v134
	global_store_dwordx2 v[210:211], v[128:129], off
	v_mul_f32_e32 v128, v201, v201
	v_fmac_f32_e32 v128, v200, v200
	v_add_f32_e32 v200, v128, v130
	v_lshlrev_b32_e32 v128, 16, v204
	v_and_b32_e32 v129, 0xffff0000, v204
	v_lshlrev_b32_e32 v130, 16, v205
	v_and_b32_e32 v131, 0xffff0000, v205
	v_lshlrev_b32_e32 v132, 16, v206
	v_and_b32_e32 v133, 0xffff0000, v206
	v_lshlrev_b32_e32 v134, 16, v207
	v_and_b32_e32 v135, 0xffff0000, v207
	v_pk_add_f32 v[122:123], v[122:123], v[130:131]
	v_pk_add_f32 v[120:121], v[120:121], v[128:129]
	v_pk_add_f32 v[130:131], v[116:117], v[132:133]
	v_cvt_pk_bf16_f32 v116, v120, v121
	v_cvt_pk_bf16_f32 v117, v122, v123
	v_pk_add_f32 v[128:129], v[118:119], v[134:135]
	v_cvt_pk_bf16_f32 v118, v130, v131
	s_nop 0
	v_cvt_pk_bf16_f32 v119, v128, v129
	global_store_dwordx4 v[188:189], v[116:119], off offset:256
	s_nop 1
	v_mul_f32_e32 v117, v199, v121
	v_mul_f32_e32 v116, v199, v120
	v_mul_f32_e32 v118, v199, v122
	v_mul_f32_e32 v119, v199, v123
	v_med3_f32 v117, v117, s52, v198
	v_med3_f32 v116, v116, s52, v198
	v_rndne_f32_e32 v117, v117
	v_med3_f32 v118, v118, s52, v198
	v_med3_f32 v119, v119, s52, v198
	v_rndne_f32_e32 v116, v116
	v_cvt_i32_f32_e32 v117, v117
	v_rndne_f32_e32 v118, v118
	v_rndne_f32_e32 v119, v119
	v_cvt_i32_f32_e32 v116, v116
	v_cvt_i32_f32_sdwa v118, v118 dst_sel:WORD_1 dst_unused:UNUSED_PAD src0_sel:DWORD
	v_cvt_i32_f32_e32 v119, v119
	v_lshlrev_b32_e32 v117, 8, v117
	v_and_b32_e32 v117, 0xff00, v117
	v_and_b32_e32 v118, 0xff0000, v118
	v_perm_b32 v116, v119, v116, s53
	v_or3_b32 v132, v116, v117, v118
	v_mul_f32_e32 v117, v199, v131
	v_med3_f32 v117, v117, s52, v198
	v_rndne_f32_e32 v117, v117
	v_cvt_i32_f32_e32 v117, v117
	v_mul_f32_e32 v116, v199, v130
	v_med3_f32 v116, v116, s52, v198
	v_rndne_f32_e32 v116, v116
	v_mul_f32_e32 v118, v199, v128
	v_cvt_i32_f32_e32 v133, v116
	v_lshlrev_b32_e32 v116, 8, v117
	v_and_b32_e32 v134, 0xff00, v116
	v_med3_f32 v116, v118, s52, v198
	v_rndne_f32_e32 v117, v116
	v_mul_f32_e32 v116, v121, v121
	v_mul_f32_e32 v118, v123, v123
	v_fmac_f32_e32 v116, v120, v120
	v_fmac_f32_e32 v118, v122, v122
	v_add_f32_e32 v116, v116, v118
	v_mul_f32_e32 v118, v131, v131
	v_fmac_f32_e32 v118, v130, v130
	v_add_f32_e32 v116, v118, v116
	v_mul_f32_e32 v118, v129, v129
	v_fmac_f32_e32 v118, v128, v128
	v_add_f32_e32 v116, v118, v116
	v_and_b32_e32 v120, 64, v197
	v_add_f32_e32 v118, v200, v116
	v_xor_b32_e32 v116, 16, v197
	v_add_u32_e32 v120, 64, v120
	v_cmp_lt_i32_e32 vcc, v116, v120
	v_mul_f32_e32 v119, v199, v129
	v_cvt_i32_f32_sdwa v122, v117 dst_sel:WORD_1 dst_unused:UNUSED_PAD src0_sel:DWORD
	v_cndmask_b32_e32 v116, v197, v116, vcc
	v_lshlrev_b32_e32 v116, 2, v116
	ds_bpermute_b32 v121, v116, v118
	v_med3_f32 v117, v119, s52, v198
	v_rndne_f32_e32 v117, v117
	v_cvt_i32_f32_e32 v123, v117
	v_xor_b32_e32 v117, 32, v197
	v_cmp_lt_i32_e32 vcc, v117, v120
	s_waitcnt lgkmcnt(0)
	v_add_f32_e32 v118, v118, v121
	v_and_b32_e32 v120, 0xff0000, v122
	v_cndmask_b32_e32 v117, v197, v117, vcc
	v_lshlrev_b32_e32 v117, 2, v117
	ds_bpermute_b32 v119, v117, v118
	v_perm_b32 v121, v123, v133, s53
	v_or3_b32 v133, v121, v134, v120
	global_store_dwordx2 v[210:211], v[132:133], off offset:128
	s_and_saveexec_b64 s[26:27], s[2:3]
	s_cbranch_execz .LBB0_640
	s_waitcnt lgkmcnt(0)
	v_add_f32_e32 v118, v118, v119
	v_fma_f32 v118, v118, s54, 0.5
	v_trunc_f32_e32 v118, v118
	v_mul_f32_e32 v119, 0x2f800000, v118
	v_floor_f32_e32 v119, v119
	v_fmac_f32_e32 v118, 0xcf800000, v119
	v_cvt_u32_f32_e32 v118, v118
	v_cvt_u32_f32_e32 v119, v119
	v_lshl_add_u64 v[120:121], v[174:175], 3, s[10:11]
	global_atomic_add_x2 v[120:121], v[118:119], off

.LBB0_715:
	s_mov_b64 s[0:1], s[78:79]
	s_load_dword s0, s[0:1], 0xa8
	s_waitcnt lgkmcnt(0)
	s_cmp_gt_i32 s0, 7
	s_cbranch_scc1 .LBB0_733
	s_mov_b64 s[0:1], s[78:79]
	s_load_dword s0, s[0:1], 0xac
	s_waitcnt lgkmcnt(0)
	s_cmp_lt_i32 s0, 8
	s_cbranch_scc1 .LBB0_733
	s_mov_b32 s94, 0
	s_mov_b32 s95, -1
	s_mov_b64 s[0:1], s[78:79]
	s_mov_b32 s4, -1
	s_cmpk_gt_i32 s87, 0x9ff
	s_cbranch_scc1 .LBB0_733
	s_load_dwordx2 s[2:3], s[0:1], 0xa0
	v_mbcnt_lo_u32_b32 v0, s4, 0
	v_mbcnt_hi_u32_b32 v9, s4, v0
	s_mov_b32 s0, 0xfffe0
	s_movk_i32 s37, 0x141
	s_waitcnt lgkmcnt(0)
	s_add_u32 s30, s2, 0x38400000
	s_addc_u32 s31, s3, 0
	s_add_u32 s33, s2, 0x8a00000
	s_addc_u32 s34, s3, 0
	s_lshl_b32 s35, s81, 10
	v_lshl_add_u32 v0, v9, 4, s35
	v_add_u32_e32 v1, 0x2000, v0
	v_ashrrev_i32_e32 v2, 31, v1
	v_lshrrev_b32_e32 v2, 22, v2
	v_add_u32_e32 v2, v1, v2
	v_ashrrev_i32_e32 v8, 10, v2
	v_mul_i32_i24_e32 v2, 0x400, v8
	v_sub_u32_e32 v1, v1, v2
	v_lshrrev_b32_e32 v2, 4, v1
	v_bitop3_b32 v1, v2, v1, 32 bitop3:0x6c
	v_ashrrev_i32_e32 v2, 31, v1
	v_lshrrev_b32_e32 v2, 26, v2
	v_add_u32_e32 v2, v1, v2
	v_ashrrev_i32_e32 v10, 6, v2
	v_lshlrev_b32_e32 v3, 3, v8
	v_and_b32_e32 v2, 0xffc0, v2
	v_and_b32_e32 v3, -16, v3
	v_sub_u32_e32 v1, v1, v2
	v_add_u32_e32 v3, v10, v3
	v_lshrrev_b16_e32 v2, 7, v1
	v_and_b32_e32 v4, 3, v10
	v_lshrrev_b32_e32 v5, 2, v3
	v_lshlrev_b32_e32 v6, 1, v3
	v_and_b32_e32 v2, 1, v2
	v_and_or_b32 v4, v3, s0, v4
	v_and_b32_e32 v5, 4, v5
	v_and_b32_e32 v6, 24, v6
	v_add_u16_e32 v1, v1, v2
	v_mov_b32_e32 v2, 1
	v_or3_b32 v4, v4, v5, v6
	v_lshlrev_b32_e32 v5, 5, v8
	v_ashrrev_i16_sdwa v1, v2, sext(v1) dst_sel:DWORD dst_unused:UNUSED_PAD src0_sel:DWORD src1_sel:BYTE_0
	v_and_b32_e32 v5, 32, v5
	v_bfe_i32 v11, v1, 0, 16
	v_add_lshl_u32 v1, v5, v11, 1
	v_lshl_add_u32 v128, v4, 12, v1
	v_lshl_add_u32 v130, v3, 12, v1
	v_ashrrev_i32_e32 v1, 31, v0
	v_lshrrev_b32_e32 v1, 22, v1
	v_add_u32_e32 v1, v0, v1
	v_ashrrev_i32_e32 v12, 10, v1
	v_mul_i32_i24_e32 v1, 0x400, v12
	v_sub_u32_e32 v0, v0, v1
	v_lshrrev_b32_e32 v1, 4, v0
	v_bitop3_b32 v0, v1, v0, 32 bitop3:0x6c
	v_ashrrev_i32_e32 v1, 31, v0
	v_lshrrev_b32_e32 v1, 26, v1
	v_add_u32_e32 v1, v0, v1
	v_lshlrev_b32_e32 v3, 3, v12
	v_ashrrev_i32_e32 v13, 6, v1
	v_and_b32_e32 v3, -16, v3
	v_add_u32_e32 v3, v13, v3
	v_and_b32_e32 v4, 3, v13
	s_ashr_i32 s36, s87, 31
	v_and_or_b32 v4, v3, s0, v4
	s_lshr_b32 s0, s36, 29
	s_add_i32 s0, s87, s0
	s_ashr_i32 s1, s0, 3
	s_and_b32 s0, s0, -8
	s_lshr_b32 s19, s92, 8
	s_sub_i32 s0, s87, s0
	s_cmp_lt_i32 s0, 0
	s_cselect_b32 s4, s37, 0x140
	s_mul_i32 s0, s4, s0
	s_add_i32 s0, s0, s1
	s_mul_hi_i32 s1, s0, 0x66666667
	s_lshr_b32 s4, s1, 31
	s_ashr_i32 s1, s1, 7
	s_add_i32 s1, s1, s4
	s_lshl_b32 s4, s1, 3
	s_mulk_i32 s1, 0x140
	s_sub_i32 s0, s0, s1
	s_sext_i32_i16 s1, s0
	s_bfe_u32 s1, s1, 0x3001c
	s_add_i32 s1, s0, s1
	s_sext_i32_i16 s5, s1
	s_and_b32 s1, s1, 0xfff8
	s_sub_i32 s0, s0, s1
	s_sext_i32_i16 s0, s0
	v_lshrrev_b32_e32 v5, 2, v3
	v_lshlrev_b32_e32 v6, 1, v3
	v_and_b32_e32 v1, 0xc0, v1
	s_lshr_b32 s18, s5, 3
	s_add_i32 s0, s4, s0
	v_and_b32_e32 v5, 4, v5
	v_and_b32_e32 v6, 24, v6
	v_sub_u32_e32 v0, v0, v1
	s_ashr_i32 s1, s0, 31
	s_bfe_i64 s[4:5], s[18:19], 0x100000
	v_or3_b32 v4, v4, v5, v6
	v_lshlrev_b32_e32 v5, 5, v12
	v_ashrrev_i16_sdwa v0, v2, sext(v0) dst_sel:DWORD dst_unused:UNUSED_PAD src0_sel:DWORD src1_sel:BYTE_0
	s_lshl_b64 s[6:7], s[0:1], 20
	s_lshl_b64 s[4:5], s[4:5], 20
	v_and_b32_e32 v5, 32, v5
	v_bfe_i32 v14, v0, 0, 16
	s_add_u32 s4, s33, s4
	v_add_lshl_u32 v0, v5, v14, 1
	s_addc_u32 s5, s34, s5
	s_add_i32 s38, s35, 0
	v_lshl_add_u32 v132, v4, 12, v0
	s_add_i32 m0, s38, 0x10000
	v_lshl_add_u32 v134, v3, 12, v0
	global_load_lds_dwordx4 v132, s[4:5]
	s_add_i32 m0, s38, 0x12000
	s_add_u32 s8, s4, 0x80000
	global_load_lds_dwordx4 v128, s[4:5]
	s_addc_u32 s9, s5, 0
	s_add_i32 m0, s38, 0x14000
	v_mov_b32_e32 v133, 0
	global_load_lds_dwordx4 v132, s[8:9]
	s_add_i32 m0, s38, 0x16000
	s_add_u32 s6, s30, s6
	s_addc_u32 s7, s31, s7
	s_add_i32 s39, s38, 0x2000
	global_load_lds_dwordx4 v128, s[8:9]
	s_mov_b32 m0, s38
	s_add_u32 s8, s6, 0x80000
	global_load_lds_dwordx4 v134, s[6:7]
	s_mov_b32 m0, s39
	s_addc_u32 s9, s7, 0
	s_add_i32 s40, s38, 0x4000
	global_load_lds_dwordx4 v130, s[6:7]
	s_mov_b32 m0, s40
	s_add_i32 s41, s38, 0x6000
	global_load_lds_dwordx4 v134, s[8:9]
	s_mov_b32 m0, s41
	v_mov_b32_e32 v129, v133
	global_load_lds_dwordx4 v130, s[8:9]
	v_mov_b32_e32 v135, v133
	v_mov_b32_e32 v131, v133
	s_cmp_eq_u32 s19, 1
	s_mov_b32 s42, 0
	v_lshl_add_u64 v[6:7], s[4:5], 0, v[132:133]
	v_lshl_add_u64 v[4:5], s[4:5], 0, v[128:129]
	v_lshl_add_u64 v[0:1], s[6:7], 0, v[134:135]
	s_cselect_b64 s[8:9], -1, 0
	s_cmp_lg_u32 s19, 1
	v_lshl_add_u64 v[2:3], s[6:7], 0, v[130:131]
	s_cbranch_scc1 .LBB0_720
	s_barrier

.Lsp_skip6:
.LBB0_726:
	ds_read_b128 v[144:147], v161
	ds_read_b128 v[148:151], v161 offset:1024
	ds_read_b128 v[168:171], v161 offset:2048
	ds_read_b128 v[172:175], v161 offset:3072
	ds_read_b128 v[176:179], v163
	ds_read_b128 v[180:183], v163 offset:1024
	ds_read_b128 v[184:187], v163 offset:2048
	ds_read_b128 v[188:191], v163 offset:3072
	ds_read_b128 v[192:195], v165
	ds_read_b128 v[196:199], v165 offset:1024
	ds_read_b128 v[200:203], v165 offset:2048
	ds_read_b128 v[204:207], v165 offset:3072
	ds_read_b128 v[208:211], v165 offset:4096
	ds_read_b128 v[212:215], v165 offset:5120
	ds_read_b128 v[216:219], v165 offset:6144
	ds_read_b128 v[220:223], v165 offset:7168
	s_add_u32 s6, s4, 0xfff80080
	s_addc_u32 s7, s5, -1
	s_cmp_eq_u32 s54, 28
	s_cselect_b32 s29, s1, s7
	s_cselect_b32 s28, s23, s6
	s_cselect_b32 s7, s21, s53
	s_cselect_b32 s6, s51, s52
	s_add_i32 m0, s38, 0xc000
	s_nop 0
	global_load_lds_dwordx4 v138, s[4:5]
	s_add_i32 m0, s38, 0xe000
	s_nop 0
	global_load_lds_dwordx4 v136, s[4:5]
	s_cmp_eq_u32 s94, 1
	s_cbranch_scc1 .Lrx7_0a
	s_waitcnt vmcnt(8)
	s_branch .Lrx7_0b

.Lrx7_0b:
	s_waitcnt lgkmcnt(0)
	s_barrier
	s_waitcnt lgkmcnt(0)
	v_mfma_i32_16x16x64_i8 v[124:127], v[144:147], v[192:195], v[124:127]
	v_mfma_i32_16x16x64_i8 v[120:123], v[168:171], v[192:195], v[120:123]
	v_mfma_i32_16x16x64_i8 v[108:111], v[144:147], v[200:203], v[108:111]
	v_mfma_i32_16x16x64_i8 v[104:107], v[168:171], v[200:203], v[104:107]
	s_add_u32 s98, s6, s16
	s_addc_u32 s99, s7, s17
	s_add_i32 s55, s46, s35
	v_mfma_i32_16x16x64_i8 v[92:95], v[144:147], v[208:211], v[92:95]
	s_add_u32 s100, s28, s16
	s_addc_u32 s101, s29, s17
	v_mfma_i32_16x16x64_i8 v[88:91], v[168:171], v[208:211], v[88:91]
	v_mfma_i32_16x16x64_i8 v[76:79], v[144:147], v[216:219], v[76:79]
	v_mfma_i32_16x16x64_i8 v[72:75], v[168:171], v[216:219], v[72:75]
	s_add_u32 s56, s6, 0x80000
	v_mfma_i32_16x16x64_i8 v[124:127], v[148:151], v[196:199], v[124:127]
	v_mfma_i32_16x16x64_i8 v[120:123], v[172:175], v[196:199], v[120:123]
	v_mfma_i32_16x16x64_i8 v[108:111], v[148:151], v[204:207], v[108:111]
	v_mfma_i32_16x16x64_i8 v[104:107], v[172:175], v[204:207], v[104:107]
	s_addc_u32 s57, s7, 0
	v_mfma_i32_16x16x64_i8 v[92:95], v[148:151], v[212:215], v[92:95]
	v_mfma_i32_16x16x64_i8 v[88:91], v[172:175], v[212:215], v[88:91]
	v_mfma_i32_16x16x64_i8 v[76:79], v[148:151], v[220:223], v[76:79]
	v_mfma_i32_16x16x64_i8 v[72:75], v[172:175], v[220:223], v[72:75]
	v_mfma_i32_16x16x64_i8 v[116:119], v[176:179], v[192:195], v[116:119]
	v_mfma_i32_16x16x64_i8 v[112:115], v[184:187], v[192:195], v[112:115]
	v_mfma_i32_16x16x64_i8 v[100:103], v[176:179], v[200:203], v[100:103]
	v_mfma_i32_16x16x64_i8 v[96:99], v[184:187], v[200:203], v[96:99]
	v_mfma_i32_16x16x64_i8 v[84:87], v[176:179], v[208:211], v[84:87]
	v_mfma_i32_16x16x64_i8 v[80:83], v[184:187], v[208:211], v[80:83]
	v_mfma_i32_16x16x64_i8 v[68:71], v[176:179], v[216:219], v[68:71]
	v_mfma_i32_16x16x64_i8 v[64:67], v[184:187], v[216:219], v[64:67]
	v_mfma_i32_16x16x64_i8 v[116:119], v[180:183], v[196:199], v[116:119]
	v_mfma_i32_16x16x64_i8 v[112:115], v[188:191], v[196:199], v[112:115]
	v_mfma_i32_16x16x64_i8 v[100:103], v[180:183], v[204:207], v[100:103]
	v_mfma_i32_16x16x64_i8 v[96:99], v[188:191], v[204:207], v[96:99]
	v_mfma_i32_16x16x64_i8 v[84:87], v[180:183], v[212:215], v[84:87]
	v_mfma_i32_16x16x64_i8 v[80:83], v[188:191], v[212:215], v[80:83]
	v_mfma_i32_16x16x64_i8 v[68:71], v[180:183], v[220:223], v[68:71]
	v_mfma_i32_16x16x64_i8 v[64:67], v[188:191], v[220:223], v[64:67]
	s_barrier
	ds_read_b128 v[192:195], v165 offset:16384
	ds_read_b128 v[196:199], v165 offset:17408
	ds_read_b128 v[200:203], v165 offset:18432
	ds_read_b128 v[204:207], v165 offset:19456
	ds_read_b128 v[208:211], v165 offset:20480
	ds_read_b128 v[212:215], v165 offset:21504
	ds_read_b128 v[216:219], v165 offset:22528
	ds_read_b128 v[220:223], v165 offset:23552
	s_mov_b32 m0, s55
	s_nop 0
	global_load_lds_dwordx4 v132, s[6:7]
	s_add_i32 m0, s55, 0x2000
	s_add_i32 s55, s47, s35
	global_load_lds_dwordx4 v128, s[6:7]
	s_mov_b32 m0, s55
	s_nop 0
	global_load_lds_dwordx4 v132, s[56:57]
	s_add_i32 m0, s55, 0x2000
	s_nop 0
	global_load_lds_dwordx4 v128, s[56:57]
	s_mov_b32 m0, s38
	s_nop 0
	global_load_lds_dwordx4 v134, s[28:29]
	s_mov_b32 m0, s39
	s_nop 0
	global_load_lds_dwordx4 v130, s[28:29]
	s_cmp_eq_u32 s94, 1
	s_cbranch_scc1 .Lrx7_1a
	s_waitcnt vmcnt(8)
	s_branch .Lrx7_1b

.Lrx7_1b:
	s_mov_b32 s94, 0
	s_waitcnt lgkmcnt(0)
	s_barrier
	s_waitcnt lgkmcnt(0)
	v_mfma_i32_16x16x64_i8 v[60:63], v[144:147], v[192:195], v[60:63]
	v_mfma_i32_16x16x64_i8 v[56:59], v[168:171], v[192:195], v[56:59]
	v_mfma_i32_16x16x64_i8 v[44:47], v[144:147], v[200:203], v[44:47]
	v_mfma_i32_16x16x64_i8 v[40:43], v[168:171], v[200:203], v[40:43]
	s_add_i32 s55, 0, 0x18000
	v_mfma_i32_16x16x64_i8 v[28:31], v[144:147], v[208:211], v[28:31]
	v_mfma_i32_16x16x64_i8 v[24:27], v[168:171], v[208:211], v[24:27]
	v_add_u32_e32 v154, s55, v157
	v_mfma_i32_16x16x64_i8 v[12:15], v[144:147], v[216:219], v[12:15]
	v_mfma_i32_16x16x64_i8 v[8:11], v[168:171], v[216:219], v[8:11]
	s_add_i32 s56, 0, 0x1c000
	v_mfma_i32_16x16x64_i8 v[60:63], v[148:151], v[196:199], v[60:63]
	v_mfma_i32_16x16x64_i8 v[56:59], v[172:175], v[196:199], v[56:59]
	s_add_u32 s28, s28, 0x80000
	v_mfma_i32_16x16x64_i8 v[44:47], v[148:151], v[204:207], v[44:47]
	v_mfma_i32_16x16x64_i8 v[40:43], v[172:175], v[204:207], v[40:43]
	s_addc_u32 s29, s29, 0
	v_mfma_i32_16x16x64_i8 v[28:31], v[148:151], v[212:215], v[28:31]
	v_mfma_i32_16x16x64_i8 v[24:27], v[172:175], v[212:215], v[24:27]
	v_mfma_i32_16x16x64_i8 v[12:15], v[148:151], v[220:223], v[12:15]
	v_mfma_i32_16x16x64_i8 v[8:11], v[172:175], v[220:223], v[8:11]
	v_mfma_i32_16x16x64_i8 v[52:55], v[176:179], v[192:195], v[52:55]
	v_mfma_i32_16x16x64_i8 v[48:51], v[184:187], v[192:195], v[48:51]
	v_mfma_i32_16x16x64_i8 v[36:39], v[176:179], v[200:203], v[36:39]
	v_mfma_i32_16x16x64_i8 v[32:35], v[184:187], v[200:203], v[32:35]
	v_mfma_i32_16x16x64_i8 v[20:23], v[176:179], v[208:211], v[20:23]
	v_mfma_i32_16x16x64_i8 v[16:19], v[184:187], v[208:211], v[16:19]
	v_mfma_i32_16x16x64_i8 v[4:7], v[176:179], v[216:219], v[4:7]
	v_mfma_i32_16x16x64_i8 v[0:3], v[184:187], v[216:219], v[0:3]
	v_mfma_i32_16x16x64_i8 v[52:55], v[180:183], v[196:199], v[52:55]
	v_mfma_i32_16x16x64_i8 v[48:51], v[188:191], v[196:199], v[48:51]
	v_mfma_i32_16x16x64_i8 v[36:39], v[180:183], v[204:207], v[36:39]
	v_mfma_i32_16x16x64_i8 v[32:35], v[188:191], v[204:207], v[32:35]
	v_mfma_i32_16x16x64_i8 v[20:23], v[180:183], v[212:215], v[20:23]
	v_mfma_i32_16x16x64_i8 v[16:19], v[188:191], v[212:215], v[16:19]
	v_mfma_i32_16x16x64_i8 v[4:7], v[180:183], v[220:223], v[4:7]
	v_mfma_i32_16x16x64_i8 v[0:3], v[188:191], v[220:223], v[0:3]
	s_barrier
	ds_read_b128 v[192:195], v165 offset:32768
	ds_read_b128 v[196:199], v165 offset:33792
	ds_read_b128 v[200:203], v165 offset:34816
	ds_read_b128 v[204:207], v165 offset:35840
	ds_read_b128 v[208:211], v165 offset:36864
	ds_read_b128 v[212:215], v165 offset:37888
	ds_read_b128 v[216:219], v165 offset:38912
	ds_read_b128 v[220:223], v165 offset:39936
	ds_read_b128 v[144:147], v154
	ds_read_b128 v[148:151], v154 offset:1024
	ds_read_b128 v[168:171], v154 offset:2048
	ds_read_b128 v[172:175], v154 offset:3072
	v_add_u32_e32 v154, s56, v157
	ds_read_b128 v[176:179], v154
	ds_read_b128 v[180:183], v154 offset:1024
	ds_read_b128 v[184:187], v154 offset:2048
	ds_read_b128 v[188:191], v154 offset:3072
	s_mov_b32 m0, s40
	s_nop 0
	global_load_lds_dwordx4 v134, s[28:29]
	s_mov_b32 m0, s41
	s_nop 0
	global_load_lds_dwordx4 v130, s[28:29]
	s_waitcnt vmcnt(8)
	s_waitcnt lgkmcnt(0)
	s_barrier
	s_waitcnt lgkmcnt(0)
	v_mfma_i32_16x16x64_i8 v[124:127], v[144:147], v[192:195], v[124:127]
	v_mfma_i32_16x16x64_i8 v[120:123], v[168:171], v[192:195], v[120:123]
	v_mfma_i32_16x16x64_i8 v[108:111], v[144:147], v[200:203], v[108:111]
	v_mfma_i32_16x16x64_i8 v[104:107], v[168:171], v[200:203], v[104:107]
	s_add_i32 s28, s55, s35
	v_mfma_i32_16x16x64_i8 v[92:95], v[144:147], v[208:211], v[92:95]
	v_mfma_i32_16x16x64_i8 v[88:91], v[168:171], v[208:211], v[88:91]
	v_mfma_i32_16x16x64_i8 v[76:79], v[144:147], v[216:219], v[76:79]
	v_mfma_i32_16x16x64_i8 v[72:75], v[168:171], v[216:219], v[72:75]
	s_add_u32 s6, s6, 0x80080
	v_mfma_i32_16x16x64_i8 v[124:127], v[148:151], v[196:199], v[124:127]
	v_mfma_i32_16x16x64_i8 v[120:123], v[172:175], v[196:199], v[120:123]
	v_mfma_i32_16x16x64_i8 v[108:111], v[148:151], v[204:207], v[108:111]
	v_mfma_i32_16x16x64_i8 v[104:107], v[172:175], v[204:207], v[104:107]
	s_addc_u32 s7, s7, 0
	v_mfma_i32_16x16x64_i8 v[92:95], v[148:151], v[212:215], v[92:95]
	v_mfma_i32_16x16x64_i8 v[88:91], v[172:175], v[212:215], v[88:91]
	v_mfma_i32_16x16x64_i8 v[76:79], v[148:151], v[220:223], v[76:79]
	v_mfma_i32_16x16x64_i8 v[72:75], v[172:175], v[220:223], v[72:75]
	v_mfma_i32_16x16x64_i8 v[116:119], v[176:179], v[192:195], v[116:119]
	v_mfma_i32_16x16x64_i8 v[112:115], v[184:187], v[192:195], v[112:115]
	v_mfma_i32_16x16x64_i8 v[100:103], v[176:179], v[200:203], v[100:103]
	v_mfma_i32_16x16x64_i8 v[96:99], v[184:187], v[200:203], v[96:99]
	v_mfma_i32_16x16x64_i8 v[84:87], v[176:179], v[208:211], v[84:87]
	v_mfma_i32_16x16x64_i8 v[80:83], v[184:187], v[208:211], v[80:83]
	v_mfma_i32_16x16x64_i8 v[68:71], v[176:179], v[216:219], v[68:71]
	v_mfma_i32_16x16x64_i8 v[64:67], v[184:187], v[216:219], v[64:67]
	v_mfma_i32_16x16x64_i8 v[116:119], v[180:183], v[196:199], v[116:119]
	v_mfma_i32_16x16x64_i8 v[112:115], v[188:191], v[196:199], v[112:115]
	v_mfma_i32_16x16x64_i8 v[100:103], v[180:183], v[204:207], v[100:103]
	v_mfma_i32_16x16x64_i8 v[96:99], v[188:191], v[204:207], v[96:99]
	v_mfma_i32_16x16x64_i8 v[84:87], v[180:183], v[212:215], v[84:87]
	v_mfma_i32_16x16x64_i8 v[80:83], v[188:191], v[212:215], v[80:83]
	v_mfma_i32_16x16x64_i8 v[68:71], v[180:183], v[220:223], v[68:71]
	v_mfma_i32_16x16x64_i8 v[64:67], v[188:191], v[220:223], v[64:67]
	s_barrier
	ds_read_b128 v[192:195], v165 offset:49152
	ds_read_b128 v[196:199], v165 offset:50176
	ds_read_b128 v[200:203], v165 offset:51200
	ds_read_b128 v[204:207], v165 offset:52224
	ds_read_b128 v[208:211], v165 offset:53248
	ds_read_b128 v[212:215], v165 offset:54272
	ds_read_b128 v[216:219], v165 offset:55296
	ds_read_b128 v[220:223], v165 offset:56320
	s_mov_b32 m0, s28
	s_nop 0
	global_load_lds_dwordx4 v132, s[98:99]
	s_add_i32 m0, s28, 0x2000
	s_add_i32 s28, s56, s35
	global_load_lds_dwordx4 v128, s[98:99]
	s_mov_b32 m0, s28
	s_nop 0
	global_load_lds_dwordx4 v132, s[6:7]
	s_add_i32 m0, s28, 0x2000
	s_nop 0
	global_load_lds_dwordx4 v128, s[6:7]
	s_mov_b32 m0, s43
	s_nop 0
	global_load_lds_dwordx4 v134, s[100:101]
	s_mov_b32 m0, s44
	s_nop 0
	global_load_lds_dwordx4 v130, s[100:101]
	s_waitcnt vmcnt(8)
	s_waitcnt lgkmcnt(0)
	s_barrier
	s_waitcnt lgkmcnt(0)
	v_mfma_i32_16x16x64_i8 v[60:63], v[144:147], v[192:195], v[60:63]
	v_mfma_i32_16x16x64_i8 v[56:59], v[168:171], v[192:195], v[56:59]
	v_mfma_i32_16x16x64_i8 v[44:47], v[144:147], v[200:203], v[44:47]
	v_mfma_i32_16x16x64_i8 v[40:43], v[168:171], v[200:203], v[40:43]
	v_mfma_i32_16x16x64_i8 v[28:31], v[144:147], v[208:211], v[28:31]
	v_mfma_i32_16x16x64_i8 v[24:27], v[168:171], v[208:211], v[24:27]
	v_mfma_i32_16x16x64_i8 v[12:15], v[144:147], v[216:219], v[12:15]
	v_mfma_i32_16x16x64_i8 v[8:11], v[168:171], v[216:219], v[8:11]
	v_mfma_i32_16x16x64_i8 v[60:63], v[148:151], v[196:199], v[60:63]
	v_mfma_i32_16x16x64_i8 v[56:59], v[172:175], v[196:199], v[56:59]
	v_mfma_i32_16x16x64_i8 v[44:47], v[148:151], v[204:207], v[44:47]
	v_mfma_i32_16x16x64_i8 v[40:43], v[172:175], v[204:207], v[40:43]
	v_mfma_i32_16x16x64_i8 v[28:31], v[148:151], v[212:215], v[28:31]
	v_mfma_i32_16x16x64_i8 v[24:27], v[172:175], v[212:215], v[24:27]
	v_mfma_i32_16x16x64_i8 v[12:15], v[148:151], v[220:223], v[12:15]
	v_mfma_i32_16x16x64_i8 v[8:11], v[172:175], v[220:223], v[8:11]
	v_mfma_i32_16x16x64_i8 v[52:55], v[176:179], v[192:195], v[52:55]
	v_mfma_i32_16x16x64_i8 v[48:51], v[184:187], v[192:195], v[48:51]
	v_mfma_i32_16x16x64_i8 v[36:39], v[176:179], v[200:203], v[36:39]
	v_mfma_i32_16x16x64_i8 v[32:35], v[184:187], v[200:203], v[32:35]
	v_mfma_i32_16x16x64_i8 v[20:23], v[176:179], v[208:211], v[20:23]
	v_mfma_i32_16x16x64_i8 v[16:19], v[184:187], v[208:211], v[16:19]
	v_mfma_i32_16x16x64_i8 v[4:7], v[176:179], v[216:219], v[4:7]
	v_mfma_i32_16x16x64_i8 v[0:3], v[184:187], v[216:219], v[0:3]
	v_mfma_i32_16x16x64_i8 v[52:55], v[180:183], v[196:199], v[52:55]
	v_mfma_i32_16x16x64_i8 v[48:51], v[188:191], v[196:199], v[48:51]
	v_mfma_i32_16x16x64_i8 v[36:39], v[180:183], v[204:207], v[36:39]
	v_mfma_i32_16x16x64_i8 v[32:35], v[188:191], v[204:207], v[32:35]
	v_mfma_i32_16x16x64_i8 v[20:23], v[180:183], v[212:215], v[20:23]
	v_mfma_i32_16x16x64_i8 v[16:19], v[188:191], v[212:215], v[16:19]
	v_mfma_i32_16x16x64_i8 v[4:7], v[180:183], v[220:223], v[4:7]
	v_mfma_i32_16x16x64_i8 v[0:3], v[188:191], v[220:223], v[0:3]
	s_barrier
	s_add_i32 s54, s54, 2
	s_add_u32 s52, s52, 0x100
	s_addc_u32 s53, s53, 0
	s_add_u32 s4, s4, 0x100
	s_addc_u32 s5, s5, 0
	s_cmp_gt_u32 s54, 29
	s_cbranch_scc0 .LBB0_726
	s_setprio 0
	s_and_b64 vcc, exec, s[18:19]
	s_cbranch_vccz .LBB0_729
	s_barrier

.Llean_p7:
	s_mov_b32 s94, 1
	v_lshl_add_u32 v144, s0, 8, v155
	v_mov_b32_e32 v145, 0
	v_lshl_or_b32 v148, s50, 8, v159
	v_mov_b32_e32 v149, 0
	v_mov_b32_e32 v146, 0x5000
	v_mad_u64_u32 v[146:147], s[96:97], v144, v146, 0
	v_lshlrev_b64 v[148:149], 1, v[148:149]
	v_lshl_add_u64 v[146:147], s[10:11], 0, v[146:147]
	v_lshl_add_u64 v[150:151], v[146:147], 0, v[148:149]
	v_cvt_f32_i32_e32 v124, v124
	v_cvt_f32_i32_e32 v125, v125
	v_cvt_f32_i32_e32 v126, v126
	v_cvt_f32_i32_e32 v127, v127
	v_cvt_f32_i32_e32 v120, v120
	v_cvt_f32_i32_e32 v121, v121
	v_cvt_f32_i32_e32 v122, v122
	v_cvt_f32_i32_e32 v123, v123
	v_pk_mul_f32 v[124:125], v[232:233], v[124:125] op_sel_hi:[0,1]
	v_pk_mul_f32 v[126:127], v[232:233], v[126:127] op_sel_hi:[0,1]
	v_pk_mul_f32 v[120:121], v[232:233], v[120:121] op_sel_hi:[0,1]
	v_pk_mul_f32 v[122:123], v[232:233], v[122:123] op_sel_hi:[0,1]
	v_cvt_pk_bf16_f32 v170, v124, v125
	v_cvt_pk_bf16_f32 v171, v126, v127
	v_cvt_pk_bf16_f32 v172, v120, v121
	v_cvt_pk_bf16_f32 v173, v122, v123
	global_store_dwordx4 v[150:151], v[170:173], off
	v_cvt_f32_i32_e32 v116, v116
	v_cvt_f32_i32_e32 v117, v117
	v_cvt_f32_i32_e32 v118, v118
	v_cvt_f32_i32_e32 v119, v119
	v_cvt_f32_i32_e32 v112, v112
	v_cvt_f32_i32_e32 v113, v113
	v_cvt_f32_i32_e32 v114, v114
	v_cvt_f32_i32_e32 v115, v115
	v_pk_mul_f32 v[116:117], v[232:233], v[116:117] op_sel_hi:[0,1]
	v_pk_mul_f32 v[118:119], v[232:233], v[118:119] op_sel_hi:[0,1]
	v_pk_mul_f32 v[112:113], v[232:233], v[112:113] op_sel_hi:[0,1]
	v_pk_mul_f32 v[114:115], v[232:233], v[114:115] op_sel_hi:[0,1]
	v_cvt_pk_bf16_f32 v174, v116, v117
	v_cvt_pk_bf16_f32 v175, v118, v119
	v_cvt_pk_bf16_f32 v176, v112, v113
	v_cvt_pk_bf16_f32 v177, v114, v115
	global_store_dwordx4 v[150:151], v[174:177], off offset:256
	v_add_co_u32_e32 v152, vcc, 0x50000, v150
	s_nop 1
	v_addc_co_u32_e32 v153, vcc, 0, v151, vcc
	v_cvt_f32_i32_e32 v108, v108
	v_cvt_f32_i32_e32 v109, v109
	v_cvt_f32_i32_e32 v110, v110
	v_cvt_f32_i32_e32 v111, v111
	v_cvt_f32_i32_e32 v104, v104
	v_cvt_f32_i32_e32 v105, v105
	v_cvt_f32_i32_e32 v106, v106
	v_cvt_f32_i32_e32 v107, v107
	v_pk_mul_f32 v[108:109], v[234:235], v[108:109] op_sel_hi:[0,1]
	v_pk_mul_f32 v[110:111], v[234:235], v[110:111] op_sel_hi:[0,1]
	v_pk_mul_f32 v[104:105], v[234:235], v[104:105] op_sel_hi:[0,1]
	v_pk_mul_f32 v[106:107], v[234:235], v[106:107] op_sel_hi:[0,1]
	v_cvt_pk_bf16_f32 v178, v108, v109
	v_cvt_pk_bf16_f32 v179, v110, v111
	v_cvt_pk_bf16_f32 v180, v104, v105
	v_cvt_pk_bf16_f32 v181, v106, v107
	global_store_dwordx4 v[152:153], v[178:181], off
	v_cvt_f32_i32_e32 v100, v100
	v_cvt_f32_i32_e32 v101, v101
	v_cvt_f32_i32_e32 v102, v102
	v_cvt_f32_i32_e32 v103, v103
	v_cvt_f32_i32_e32 v96, v96
	v_cvt_f32_i32_e32 v97, v97
	v_cvt_f32_i32_e32 v98, v98
	v_cvt_f32_i32_e32 v99, v99
	v_pk_mul_f32 v[100:101], v[234:235], v[100:101] op_sel_hi:[0,1]
	v_pk_mul_f32 v[102:103], v[234:235], v[102:103] op_sel_hi:[0,1]
	v_pk_mul_f32 v[96:97], v[234:235], v[96:97] op_sel_hi:[0,1]
	v_pk_mul_f32 v[98:99], v[234:235], v[98:99] op_sel_hi:[0,1]
	v_cvt_pk_bf16_f32 v182, v100, v101
	v_cvt_pk_bf16_f32 v183, v102, v103
	v_cvt_pk_bf16_f32 v184, v96, v97
	v_cvt_pk_bf16_f32 v185, v98, v99
	global_store_dwordx4 v[152:153], v[182:185], off offset:256
	v_add_co_u32_e32 v152, vcc, 0xa0000, v150
	s_nop 1
	v_addc_co_u32_e32 v153, vcc, 0, v151, vcc
	v_cvt_f32_i32_e32 v92, v92
	v_cvt_f32_i32_e32 v93, v93
	v_cvt_f32_i32_e32 v94, v94
	v_cvt_f32_i32_e32 v95, v95
	v_cvt_f32_i32_e32 v88, v88
	v_cvt_f32_i32_e32 v89, v89
	v_cvt_f32_i32_e32 v90, v90
	v_cvt_f32_i32_e32 v91, v91
	v_pk_mul_f32 v[92:93], v[236:237], v[92:93] op_sel_hi:[0,1]
	v_pk_mul_f32 v[94:95], v[236:237], v[94:95] op_sel_hi:[0,1]
	v_pk_mul_f32 v[88:89], v[236:237], v[88:89] op_sel_hi:[0,1]
	v_pk_mul_f32 v[90:91], v[236:237], v[90:91] op_sel_hi:[0,1]
	v_cvt_pk_bf16_f32 v186, v92, v93
	v_cvt_pk_bf16_f32 v187, v94, v95
	v_cvt_pk_bf16_f32 v188, v88, v89
	v_cvt_pk_bf16_f32 v189, v90, v91
	global_store_dwordx4 v[152:153], v[186:189], off
	v_cvt_f32_i32_e32 v84, v84
	v_cvt_f32_i32_e32 v85, v85
	v_cvt_f32_i32_e32 v86, v86
	v_cvt_f32_i32_e32 v87, v87
	v_cvt_f32_i32_e32 v80, v80
	v_cvt_f32_i32_e32 v81, v81
	v_cvt_f32_i32_e32 v82, v82
	v_cvt_f32_i32_e32 v83, v83
	v_pk_mul_f32 v[84:85], v[236:237], v[84:85] op_sel_hi:[0,1]
	v_pk_mul_f32 v[86:87], v[236:237], v[86:87] op_sel_hi:[0,1]
	v_pk_mul_f32 v[80:81], v[236:237], v[80:81] op_sel_hi:[0,1]
	v_pk_mul_f32 v[82:83], v[236:237], v[82:83] op_sel_hi:[0,1]
	v_cvt_pk_bf16_f32 v190, v84, v85
	v_cvt_pk_bf16_f32 v191, v86, v87
	v_cvt_pk_bf16_f32 v192, v80, v81
	v_cvt_pk_bf16_f32 v193, v82, v83
	global_store_dwordx4 v[152:153], v[190:193], off offset:256
	v_add_co_u32_e32 v152, vcc, 0xf0000, v150
	s_nop 1
	v_addc_co_u32_e32 v153, vcc, 0, v151, vcc
	v_cvt_f32_i32_e32 v76, v76
	v_cvt_f32_i32_e32 v77, v77
	v_cvt_f32_i32_e32 v78, v78
	v_cvt_f32_i32_e32 v79, v79
	v_cvt_f32_i32_e32 v72, v72
	v_cvt_f32_i32_e32 v73, v73
	v_cvt_f32_i32_e32 v74, v74
	v_cvt_f32_i32_e32 v75, v75
	v_pk_mul_f32 v[76:77], v[238:239], v[76:77] op_sel_hi:[0,1]
	v_pk_mul_f32 v[78:79], v[238:239], v[78:79] op_sel_hi:[0,1]
	v_pk_mul_f32 v[72:73], v[238:239], v[72:73] op_sel_hi:[0,1]
	v_pk_mul_f32 v[74:75], v[238:239], v[74:75] op_sel_hi:[0,1]
	v_cvt_pk_bf16_f32 v194, v76, v77
	v_cvt_pk_bf16_f32 v195, v78, v79
	v_cvt_pk_bf16_f32 v196, v72, v73
	v_cvt_pk_bf16_f32 v197, v74, v75
	global_store_dwordx4 v[152:153], v[194:197], off
	v_cvt_f32_i32_e32 v68, v68
	v_cvt_f32_i32_e32 v69, v69
	v_cvt_f32_i32_e32 v70, v70
	v_cvt_f32_i32_e32 v71, v71
	v_cvt_f32_i32_e32 v64, v64
	v_cvt_f32_i32_e32 v65, v65
	v_cvt_f32_i32_e32 v66, v66
	v_cvt_f32_i32_e32 v67, v67
	v_pk_mul_f32 v[68:69], v[238:239], v[68:69] op_sel_hi:[0,1]
	v_pk_mul_f32 v[70:71], v[238:239], v[70:71] op_sel_hi:[0,1]
	v_pk_mul_f32 v[64:65], v[238:239], v[64:65] op_sel_hi:[0,1]
	v_pk_mul_f32 v[66:67], v[238:239], v[66:67] op_sel_hi:[0,1]
	v_cvt_pk_bf16_f32 v198, v68, v69
	v_cvt_pk_bf16_f32 v199, v70, v71
	v_cvt_pk_bf16_f32 v200, v64, v65
	v_cvt_pk_bf16_f32 v201, v66, v67
	global_store_dwordx4 v[152:153], v[198:201], off offset:256
	v_add_co_u32_e32 v152, vcc, 0x280000, v150
	s_nop 1
	v_addc_co_u32_e32 v153, vcc, 0, v151, vcc
	v_cvt_f32_i32_e32 v60, v60
	v_cvt_f32_i32_e32 v61, v61
	v_cvt_f32_i32_e32 v62, v62
	v_cvt_f32_i32_e32 v63, v63
	v_cvt_f32_i32_e32 v56, v56
	v_cvt_f32_i32_e32 v57, v57
	v_cvt_f32_i32_e32 v58, v58
	v_cvt_f32_i32_e32 v59, v59
	v_pk_mul_f32 v[60:61], v[240:241], v[60:61] op_sel_hi:[0,1]
	v_pk_mul_f32 v[62:63], v[240:241], v[62:63] op_sel_hi:[0,1]
	v_pk_mul_f32 v[56:57], v[240:241], v[56:57] op_sel_hi:[0,1]
	v_pk_mul_f32 v[58:59], v[240:241], v[58:59] op_sel_hi:[0,1]
	v_cvt_pk_bf16_f32 v170, v60, v61
	v_cvt_pk_bf16_f32 v171, v62, v63
	v_cvt_pk_bf16_f32 v172, v56, v57
	v_cvt_pk_bf16_f32 v173, v58, v59
	global_store_dwordx4 v[152:153], v[170:173], off
	v_cvt_f32_i32_e32 v52, v52
	v_cvt_f32_i32_e32 v53, v53
	v_cvt_f32_i32_e32 v54, v54
	v_cvt_f32_i32_e32 v55, v55
	v_cvt_f32_i32_e32 v48, v48
	v_cvt_f32_i32_e32 v49, v49
	v_cvt_f32_i32_e32 v50, v50
	v_cvt_f32_i32_e32 v51, v51
	v_pk_mul_f32 v[52:53], v[240:241], v[52:53] op_sel_hi:[0,1]
	v_pk_mul_f32 v[54:55], v[240:241], v[54:55] op_sel_hi:[0,1]
	v_pk_mul_f32 v[48:49], v[240:241], v[48:49] op_sel_hi:[0,1]
	v_pk_mul_f32 v[50:51], v[240:241], v[50:51] op_sel_hi:[0,1]
	v_cvt_pk_bf16_f32 v174, v52, v53
	v_cvt_pk_bf16_f32 v175, v54, v55
	v_cvt_pk_bf16_f32 v176, v48, v49
	v_cvt_pk_bf16_f32 v177, v50, v51
	global_store_dwordx4 v[152:153], v[174:177], off offset:256
	v_add_co_u32_e32 v152, vcc, 0x2d0000, v150
	s_nop 1
	v_addc_co_u32_e32 v153, vcc, 0, v151, vcc
	v_cvt_f32_i32_e32 v44, v44
	v_cvt_f32_i32_e32 v45, v45
	v_cvt_f32_i32_e32 v46, v46
	v_cvt_f32_i32_e32 v47, v47
	v_cvt_f32_i32_e32 v40, v40
	v_cvt_f32_i32_e32 v41, v41
	v_cvt_f32_i32_e32 v42, v42
	v_cvt_f32_i32_e32 v43, v43
	v_pk_mul_f32 v[44:45], v[242:243], v[44:45] op_sel_hi:[0,1]
	v_pk_mul_f32 v[46:47], v[242:243], v[46:47] op_sel_hi:[0,1]
	v_pk_mul_f32 v[40:41], v[242:243], v[40:41] op_sel_hi:[0,1]
	v_pk_mul_f32 v[42:43], v[242:243], v[42:43] op_sel_hi:[0,1]
	v_cvt_pk_bf16_f32 v178, v44, v45
	v_cvt_pk_bf16_f32 v179, v46, v47
	v_cvt_pk_bf16_f32 v180, v40, v41
	v_cvt_pk_bf16_f32 v181, v42, v43
	global_store_dwordx4 v[152:153], v[178:181], off
	v_cvt_f32_i32_e32 v36, v36
	v_cvt_f32_i32_e32 v37, v37
	v_cvt_f32_i32_e32 v38, v38
	v_cvt_f32_i32_e32 v39, v39
	v_cvt_f32_i32_e32 v32, v32
	v_cvt_f32_i32_e32 v33, v33
	v_cvt_f32_i32_e32 v34, v34
	v_cvt_f32_i32_e32 v35, v35
	v_pk_mul_f32 v[36:37], v[242:243], v[36:37] op_sel_hi:[0,1]
	v_pk_mul_f32 v[38:39], v[242:243], v[38:39] op_sel_hi:[0,1]
	v_pk_mul_f32 v[32:33], v[242:243], v[32:33] op_sel_hi:[0,1]
	v_pk_mul_f32 v[34:35], v[242:243], v[34:35] op_sel_hi:[0,1]
	v_cvt_pk_bf16_f32 v182, v36, v37
	v_cvt_pk_bf16_f32 v183, v38, v39
	v_cvt_pk_bf16_f32 v184, v32, v33
	v_cvt_pk_bf16_f32 v185, v34, v35
	global_store_dwordx4 v[152:153], v[182:185], off offset:256
	v_add_co_u32_e32 v152, vcc, 0x320000, v150
	s_nop 1
	v_addc_co_u32_e32 v153, vcc, 0, v151, vcc
	v_cvt_f32_i32_e32 v28, v28
	v_cvt_f32_i32_e32 v29, v29
	v_cvt_f32_i32_e32 v30, v30
	v_cvt_f32_i32_e32 v31, v31
	v_cvt_f32_i32_e32 v24, v24
	v_cvt_f32_i32_e32 v25, v25
	v_cvt_f32_i32_e32 v26, v26
	v_cvt_f32_i32_e32 v27, v27
	v_pk_mul_f32 v[28:29], v[244:245], v[28:29] op_sel_hi:[0,1]
	v_pk_mul_f32 v[30:31], v[244:245], v[30:31] op_sel_hi:[0,1]
	v_pk_mul_f32 v[24:25], v[244:245], v[24:25] op_sel_hi:[0,1]
	v_pk_mul_f32 v[26:27], v[244:245], v[26:27] op_sel_hi:[0,1]
	v_cvt_pk_bf16_f32 v186, v28, v29
	v_cvt_pk_bf16_f32 v187, v30, v31
	v_cvt_pk_bf16_f32 v188, v24, v25
	v_cvt_pk_bf16_f32 v189, v26, v27
	global_store_dwordx4 v[152:153], v[186:189], off
	v_cvt_f32_i32_e32 v20, v20
	v_cvt_f32_i32_e32 v21, v21
	v_cvt_f32_i32_e32 v22, v22
	v_cvt_f32_i32_e32 v23, v23
	v_cvt_f32_i32_e32 v16, v16
	v_cvt_f32_i32_e32 v17, v17
	v_cvt_f32_i32_e32 v18, v18
	v_cvt_f32_i32_e32 v19, v19
	v_pk_mul_f32 v[20:21], v[244:245], v[20:21] op_sel_hi:[0,1]
	v_pk_mul_f32 v[22:23], v[244:245], v[22:23] op_sel_hi:[0,1]
	v_pk_mul_f32 v[16:17], v[244:245], v[16:17] op_sel_hi:[0,1]
	v_pk_mul_f32 v[18:19], v[244:245], v[18:19] op_sel_hi:[0,1]
	v_cvt_pk_bf16_f32 v190, v20, v21
	v_cvt_pk_bf16_f32 v191, v22, v23
	v_cvt_pk_bf16_f32 v192, v16, v17
	v_cvt_pk_bf16_f32 v193, v18, v19
	global_store_dwordx4 v[152:153], v[190:193], off offset:256
	v_add_co_u32_e32 v152, vcc, 0x370000, v150
	s_nop 1
	v_addc_co_u32_e32 v153, vcc, 0, v151, vcc
	v_cvt_f32_i32_e32 v12, v12
	v_cvt_f32_i32_e32 v13, v13
	v_cvt_f32_i32_e32 v14, v14
	v_cvt_f32_i32_e32 v15, v15
	v_cvt_f32_i32_e32 v8, v8
	v_cvt_f32_i32_e32 v9, v9
	v_cvt_f32_i32_e32 v10, v10
	v_cvt_f32_i32_e32 v11, v11
	v_pk_mul_f32 v[12:13], v[246:247], v[12:13] op_sel_hi:[0,1]
	v_pk_mul_f32 v[14:15], v[246:247], v[14:15] op_sel_hi:[0,1]
	v_pk_mul_f32 v[8:9], v[246:247], v[8:9] op_sel_hi:[0,1]
	v_pk_mul_f32 v[10:11], v[246:247], v[10:11] op_sel_hi:[0,1]
	v_cvt_pk_bf16_f32 v194, v12, v13
	v_cvt_pk_bf16_f32 v195, v14, v15
	v_cvt_pk_bf16_f32 v196, v8, v9
	v_cvt_pk_bf16_f32 v197, v10, v11
	global_store_dwordx4 v[152:153], v[194:197], off
	v_cvt_f32_i32_e32 v4, v4
	v_cvt_f32_i32_e32 v5, v5
	v_cvt_f32_i32_e32 v6, v6
	v_cvt_f32_i32_e32 v7, v7
	v_cvt_f32_i32_e32 v0, v0
	v_cvt_f32_i32_e32 v1, v1
	v_cvt_f32_i32_e32 v2, v2
	v_cvt_f32_i32_e32 v3, v3
	v_pk_mul_f32 v[4:5], v[246:247], v[4:5] op_sel_hi:[0,1]
	v_pk_mul_f32 v[6:7], v[246:247], v[6:7] op_sel_hi:[0,1]
	v_pk_mul_f32 v[0:1], v[246:247], v[0:1] op_sel_hi:[0,1]
	v_pk_mul_f32 v[2:3], v[246:247], v[2:3] op_sel_hi:[0,1]
	v_cvt_pk_bf16_f32 v198, v4, v5
	v_cvt_pk_bf16_f32 v199, v6, v7
	v_cvt_pk_bf16_f32 v200, v0, v1
	v_cvt_pk_bf16_f32 v201, v2, v3
	global_store_dwordx4 v[152:153], v[198:201], off offset:256
	s_andn2_b64 vcc, exec, s[2:3]
	s_mov_b64 s[0:1], -1
	s_cbranch_vccnz .LBB0_722
	s_branch .Ljoin_p7

.LBB0_1234:
	s_mov_b64 s[0:1], s[78:79]
	s_load_dword s0, s[0:1], 0xa8
	s_waitcnt lgkmcnt(0)
	s_cmp_gt_i32 s0, 10
	s_cbranch_scc1 .LBB0_1278
	s_mov_b64 s[0:1], s[78:79]
	s_load_dword s0, s[0:1], 0xac
	s_waitcnt lgkmcnt(0)
	s_cmp_lt_i32 s0, 11
	s_cbranch_scc1 .LBB0_1278
	s_mov_b32 s94, 0
	s_mov_b64 s[0:1], s[78:79]
	s_load_dwordx2 s[2:3], s[0:1], 0xa0
	s_cmpk_lt_i32 s87, 0x400
	s_mov_b32 s6, -1
	s_cselect_b64 s[0:1], -1, 0
	s_cmpk_gt_i32 s87, 0x3ff
	s_cbranch_scc1 .LBB0_1242
	s_ashr_i32 s4, s87, 31
	s_lshr_b32 s4, s4, 29
	s_add_i32 s7, s87, s4
	s_and_b32 s4, s7, -8
	s_sub_i32 s8, s87, s4
	s_cmp_gt_i32 s8, -1
	s_cbranch_scc0 .LBB0_1239
	s_lshl_b32 s9, s8, 7
	s_cbranch_execz .LBB0_1240
	s_branch .LBB0_1241

.Lsp_skip7:
.LBB0_1255:
	ds_read_b128 v[16:19], v193
	ds_read_b128 v[20:23], v193 offset:1024
	ds_read_b128 v[24:27], v193 offset:2048
	ds_read_b128 v[28:31], v193 offset:3072
	ds_read_b128 v[0:3], v194
	ds_read_b128 v[4:7], v194 offset:1024
	ds_read_b128 v[8:11], v194 offset:2048
	ds_read_b128 v[12:15], v194 offset:3072
	ds_read_b128 v[176:179], v195
	ds_read_b128 v[180:183], v195 offset:1024
	ds_read_b128 v[200:203], v195 offset:2048
	ds_read_b128 v[204:207], v195 offset:3072
	ds_read_b128 v[208:211], v195 offset:4096
	ds_read_b128 v[212:215], v195 offset:5120
	ds_read_b128 v[216:219], v195 offset:6144
	ds_read_b128 v[220:223], v195 offset:7168
	s_waitcnt lgkmcnt(0)
	s_add_u32 s36, s34, 0xfffc0080
	s_addc_u32 s37, s35, -1
	s_cmp_eq_u32 s59, 12
	s_cselect_b32 s39, s23, s37
	s_cselect_b32 s38, s29, s36
	s_cselect_b32 s37, s21, s58
	s_cselect_b32 s36, s56, s57
	v_lshl_add_u64 v[184:185], s[34:35], 0, v[170:171]
	s_add_i32 m0, s31, 0xc000
	s_nop 0
	global_load_lds_dwordx4 v[184:185], off
	v_lshl_add_u64 v[184:185], s[34:35], 0, v[168:169]
	s_add_i32 m0, s31, 0xe000
	s_nop 0
	global_load_lds_dwordx4 v[184:185], off
	s_cmp_eq_u32 s94, 1
	s_cbranch_scc1 .Lrx10_0a
	s_waitcnt vmcnt(8)
	s_branch .Lrx10_0b

.Lrx10_0b:
	s_waitcnt lgkmcnt(0)
	s_barrier
	s_waitcnt lgkmcnt(0)
	v_mfma_scale_f32_16x16x128_f8f6f4 v[156:159], v[16:23], v[176:183], v[156:159], v196, v196 op_sel_hi:[0,0,0]
	v_mfma_scale_f32_16x16x128_f8f6f4 v[152:155], v[24:31], v[176:183], v[152:155], v196, v196 op_sel_hi:[0,0,0]
	v_mfma_scale_f32_16x16x128_f8f6f4 v[140:143], v[16:23], v[200:207], v[140:143], v196, v196 op_sel_hi:[0,0,0]
	v_mfma_scale_f32_16x16x128_f8f6f4 v[136:139], v[24:31], v[200:207], v[136:139], v196, v196 op_sel_hi:[0,0,0]
	v_mfma_scale_f32_16x16x128_f8f6f4 v[124:127], v[16:23], v[208:215], v[124:127], v196, v196 op_sel_hi:[0,0,0]
	v_mfma_scale_f32_16x16x128_f8f6f4 v[120:123], v[24:31], v[208:215], v[120:123], v196, v196 op_sel_hi:[0,0,0]
	v_mfma_scale_f32_16x16x128_f8f6f4 v[108:111], v[16:23], v[216:223], v[108:111], v196, v196 op_sel_hi:[0,0,0]
	v_mfma_scale_f32_16x16x128_f8f6f4 v[104:107], v[24:31], v[216:223], v[104:107], v196, v196 op_sel_hi:[0,0,0]
	v_mfma_scale_f32_16x16x128_f8f6f4 v[148:151], v[0:7], v[176:183], v[148:151], v196, v196 op_sel_hi:[0,0,0]
	v_mfma_scale_f32_16x16x128_f8f6f4 v[144:147], v[8:15], v[176:183], v[144:147], v196, v196 op_sel_hi:[0,0,0]
	v_mfma_scale_f32_16x16x128_f8f6f4 v[132:135], v[0:7], v[200:207], v[132:135], v196, v196 op_sel_hi:[0,0,0]
	v_mfma_scale_f32_16x16x128_f8f6f4 v[128:131], v[8:15], v[200:207], v[128:131], v196, v196 op_sel_hi:[0,0,0]
	v_mfma_scale_f32_16x16x128_f8f6f4 v[116:119], v[0:7], v[208:215], v[116:119], v196, v196 op_sel_hi:[0,0,0]
	v_mfma_scale_f32_16x16x128_f8f6f4 v[112:115], v[8:15], v[208:215], v[112:115], v196, v196 op_sel_hi:[0,0,0]
	v_mfma_scale_f32_16x16x128_f8f6f4 v[100:103], v[0:7], v[216:223], v[100:103], v196, v196 op_sel_hi:[0,0,0]
	v_mfma_scale_f32_16x16x128_f8f6f4 v[96:99], v[8:15], v[216:223], v[96:99], v196, v196 op_sel_hi:[0,0,0]
	s_barrier
	ds_read_b128 v[200:203], v195 offset:16384
	ds_read_b128 v[204:207], v195 offset:17408
	ds_read_b128 v[208:211], v195 offset:18432
	ds_read_b128 v[212:215], v195 offset:19456
	ds_read_b128 v[216:219], v195 offset:20480
	ds_read_b128 v[220:223], v195 offset:21504
	ds_read_b128 v[224:227], v195 offset:22528
	ds_read_b128 v[228:231], v195 offset:23552
	s_add_i32 s60, s51, s42
	v_lshl_add_u64 v[176:177], s[36:37], 0, v[162:163]
	s_mov_b32 m0, s60
	s_nop 0
	global_load_lds_dwordx4 v[176:177], off
	s_add_i32 m0, s60, 0x2000
	s_add_u32 s60, s36, 0x40000
	v_lshl_add_u64 v[178:179], s[36:37], 0, v[166:167]
	s_addc_u32 s61, s37, 0
	s_add_i32 s62, s52, s42
	global_load_lds_dwordx4 v[178:179], off
	v_lshl_add_u64 v[180:181], s[60:61], 0, v[162:163]
	s_mov_b32 m0, s62
	v_lshl_add_u64 v[182:183], s[38:39], 0, v[164:165]
	global_load_lds_dwordx4 v[180:181], off
	v_lshl_add_u64 v[180:181], s[60:61], 0, v[166:167]
	s_add_i32 m0, s62, 0x2000
	s_nop 0
	global_load_lds_dwordx4 v[180:181], off
	v_lshl_add_u64 v[180:181], s[38:39], 0, v[160:161]
	s_mov_b32 m0, s31
	s_nop 0
	global_load_lds_dwordx4 v[180:181], off
	s_mov_b32 m0, s43
	s_nop 0
	global_load_lds_dwordx4 v[182:183], off
	s_cmp_eq_u32 s94, 1
	s_cbranch_scc1 .Lrx10_1a
	s_waitcnt vmcnt(8)
	s_branch .Lrx10_1b

.Lrx10_1b:
	s_mov_b32 s94, 0
	s_waitcnt lgkmcnt(0)
	s_barrier
	s_waitcnt lgkmcnt(0)
	v_mfma_scale_f32_16x16x128_f8f6f4 v[92:95], v[16:23], v[200:207], v[92:95], v196, v196 op_sel_hi:[0,0,0]
	v_mfma_scale_f32_16x16x128_f8f6f4 v[88:91], v[24:31], v[200:207], v[88:91], v196, v196 op_sel_hi:[0,0,0]
	v_mfma_scale_f32_16x16x128_f8f6f4 v[76:79], v[16:23], v[208:215], v[76:79], v196, v196 op_sel_hi:[0,0,0]
	v_mfma_scale_f32_16x16x128_f8f6f4 v[72:75], v[24:31], v[208:215], v[72:75], v196, v196 op_sel_hi:[0,0,0]
	v_mfma_scale_f32_16x16x128_f8f6f4 v[60:63], v[16:23], v[216:223], v[60:63], v196, v196 op_sel_hi:[0,0,0]
	v_mfma_scale_f32_16x16x128_f8f6f4 v[56:59], v[24:31], v[216:223], v[56:59], v196, v196 op_sel_hi:[0,0,0]
	v_mfma_scale_f32_16x16x128_f8f6f4 v[44:47], v[16:23], v[224:231], v[44:47], v196, v196 op_sel_hi:[0,0,0]
	v_mfma_scale_f32_16x16x128_f8f6f4 v[40:43], v[24:31], v[224:231], v[40:43], v196, v196 op_sel_hi:[0,0,0]
	v_mfma_scale_f32_16x16x128_f8f6f4 v[84:87], v[0:7], v[200:207], v[84:87], v196, v196 op_sel_hi:[0,0,0]
	v_mfma_scale_f32_16x16x128_f8f6f4 v[80:83], v[8:15], v[200:207], v[80:83], v196, v196 op_sel_hi:[0,0,0]
	v_mfma_scale_f32_16x16x128_f8f6f4 v[68:71], v[0:7], v[208:215], v[68:71], v196, v196 op_sel_hi:[0,0,0]
	v_mfma_scale_f32_16x16x128_f8f6f4 v[64:67], v[8:15], v[208:215], v[64:67], v196, v196 op_sel_hi:[0,0,0]
	v_mfma_scale_f32_16x16x128_f8f6f4 v[52:55], v[0:7], v[216:223], v[52:55], v196, v196 op_sel_hi:[0,0,0]
	v_mfma_scale_f32_16x16x128_f8f6f4 v[48:51], v[8:15], v[216:223], v[48:51], v196, v196 op_sel_hi:[0,0,0]
	v_mfma_scale_f32_16x16x128_f8f6f4 v[36:39], v[0:7], v[224:231], v[36:39], v196, v196 op_sel_hi:[0,0,0]
	v_mfma_scale_f32_16x16x128_f8f6f4 v[32:35], v[8:15], v[224:231], v[32:35], v196, v196 op_sel_hi:[0,0,0]
	s_barrier
	ds_read_b128 v[200:203], v195 offset:32768
	ds_read_b128 v[204:207], v195 offset:33792
	ds_read_b128 v[208:211], v195 offset:34816
	ds_read_b128 v[212:215], v195 offset:35840
	ds_read_b128 v[216:219], v195 offset:36864
	ds_read_b128 v[220:223], v195 offset:37888
	ds_read_b128 v[224:227], v195 offset:38912
	ds_read_b128 v[228:231], v195 offset:39936
	s_add_i32 s60, 0, 0x18000
	s_add_i32 s61, 0, 0x1c000
	v_add_u32_e32 v12, s60, v191
	v_add_u32_e32 v28, s61, v191
	ds_read_b128 v[0:3], v12
	ds_read_b128 v[4:7], v12 offset:1024
	ds_read_b128 v[8:11], v12 offset:2048
	ds_read_b128 v[12:15], v12 offset:3072
	ds_read_b128 v[16:19], v28
	ds_read_b128 v[20:23], v28 offset:1024
	ds_read_b128 v[24:27], v28 offset:2048
	ds_read_b128 v[28:31], v28 offset:3072
	s_add_u32 s38, s38, 0x40000
	s_addc_u32 s39, s39, 0
	s_mov_b32 m0, s44
	v_lshl_add_u64 v[184:185], s[38:39], 0, v[160:161]
	global_load_lds_dwordx4 v[184:185], off
	v_lshl_add_u64 v[184:185], s[38:39], 0, v[164:165]
	s_mov_b32 m0, s45
	s_nop 0
	global_load_lds_dwordx4 v[184:185], off
	s_waitcnt vmcnt(8)
	s_waitcnt lgkmcnt(0)
	s_barrier
	s_waitcnt lgkmcnt(0)
	v_mfma_scale_f32_16x16x128_f8f6f4 v[156:159], v[0:7], v[200:207], v[156:159], v196, v196 op_sel_hi:[0,0,0]
	v_mfma_scale_f32_16x16x128_f8f6f4 v[152:155], v[8:15], v[200:207], v[152:155], v196, v196 op_sel_hi:[0,0,0]
	v_mfma_scale_f32_16x16x128_f8f6f4 v[140:143], v[0:7], v[208:215], v[140:143], v196, v196 op_sel_hi:[0,0,0]
	v_mfma_scale_f32_16x16x128_f8f6f4 v[136:139], v[8:15], v[208:215], v[136:139], v196, v196 op_sel_hi:[0,0,0]
	v_mfma_scale_f32_16x16x128_f8f6f4 v[124:127], v[0:7], v[216:223], v[124:127], v196, v196 op_sel_hi:[0,0,0]
	v_mfma_scale_f32_16x16x128_f8f6f4 v[120:123], v[8:15], v[216:223], v[120:123], v196, v196 op_sel_hi:[0,0,0]
	v_mfma_scale_f32_16x16x128_f8f6f4 v[108:111], v[0:7], v[224:231], v[108:111], v196, v196 op_sel_hi:[0,0,0]
	v_mfma_scale_f32_16x16x128_f8f6f4 v[104:107], v[8:15], v[224:231], v[104:107], v196, v196 op_sel_hi:[0,0,0]
	v_mfma_scale_f32_16x16x128_f8f6f4 v[148:151], v[16:23], v[200:207], v[148:151], v196, v196 op_sel_hi:[0,0,0]
	v_mfma_scale_f32_16x16x128_f8f6f4 v[144:147], v[24:31], v[200:207], v[144:147], v196, v196 op_sel_hi:[0,0,0]
	v_mfma_scale_f32_16x16x128_f8f6f4 v[132:135], v[16:23], v[208:215], v[132:135], v196, v196 op_sel_hi:[0,0,0]
	v_mfma_scale_f32_16x16x128_f8f6f4 v[128:131], v[24:31], v[208:215], v[128:131], v196, v196 op_sel_hi:[0,0,0]
	v_mfma_scale_f32_16x16x128_f8f6f4 v[116:119], v[16:23], v[216:223], v[116:119], v196, v196 op_sel_hi:[0,0,0]
	v_mfma_scale_f32_16x16x128_f8f6f4 v[112:115], v[24:31], v[216:223], v[112:115], v196, v196 op_sel_hi:[0,0,0]
	v_mfma_scale_f32_16x16x128_f8f6f4 v[100:103], v[16:23], v[224:231], v[100:103], v196, v196 op_sel_hi:[0,0,0]
	v_mfma_scale_f32_16x16x128_f8f6f4 v[96:99], v[24:31], v[224:231], v[96:99], v196, v196 op_sel_hi:[0,0,0]
	s_barrier
	ds_read_b128 v[200:203], v195 offset:49152
	ds_read_b128 v[204:207], v195 offset:50176
	ds_read_b128 v[208:211], v195 offset:51200
	ds_read_b128 v[212:215], v195 offset:52224
	ds_read_b128 v[216:219], v195 offset:53248
	ds_read_b128 v[220:223], v195 offset:54272
	ds_read_b128 v[224:227], v195 offset:55296
	ds_read_b128 v[228:231], v195 offset:56320
	s_add_i32 s38, s60, s42
	v_lshl_add_u64 v[176:177], v[176:177], 0, s[14:15]
	s_mov_b32 m0, s38
	s_nop 0
	global_load_lds_dwordx4 v[176:177], off
	s_add_i32 m0, s38, 0x2000
	s_add_u32 s36, s36, 0x40080
	v_lshl_add_u64 v[176:177], v[178:179], 0, s[14:15]
	s_addc_u32 s37, s37, 0
	s_add_i32 s38, s61, s42
	global_load_lds_dwordx4 v[176:177], off
	v_lshl_add_u64 v[176:177], s[36:37], 0, v[162:163]
	s_mov_b32 m0, s38
	s_nop 0
	global_load_lds_dwordx4 v[176:177], off
	v_lshl_add_u64 v[176:177], s[36:37], 0, v[166:167]
	s_add_i32 m0, s38, 0x2000
	s_nop 0
	global_load_lds_dwordx4 v[176:177], off
	v_lshl_add_u64 v[176:177], v[180:181], 0, s[14:15]
	s_mov_b32 m0, s47
	s_nop 0
	global_load_lds_dwordx4 v[176:177], off
	v_lshl_add_u64 v[176:177], v[182:183], 0, s[14:15]
	s_mov_b32 m0, s48
	s_nop 0
	global_load_lds_dwordx4 v[176:177], off
	s_waitcnt vmcnt(8)
	s_waitcnt lgkmcnt(0)
	s_barrier
	s_waitcnt lgkmcnt(0)
	v_mfma_scale_f32_16x16x128_f8f6f4 v[92:95], v[0:7], v[200:207], v[92:95], v196, v196 op_sel_hi:[0,0,0]
	v_mfma_scale_f32_16x16x128_f8f6f4 v[88:91], v[8:15], v[200:207], v[88:91], v196, v196 op_sel_hi:[0,0,0]
	v_mfma_scale_f32_16x16x128_f8f6f4 v[76:79], v[0:7], v[208:215], v[76:79], v196, v196 op_sel_hi:[0,0,0]
	v_mfma_scale_f32_16x16x128_f8f6f4 v[72:75], v[8:15], v[208:215], v[72:75], v196, v196 op_sel_hi:[0,0,0]
	v_mfma_scale_f32_16x16x128_f8f6f4 v[60:63], v[0:7], v[216:223], v[60:63], v196, v196 op_sel_hi:[0,0,0]
	v_mfma_scale_f32_16x16x128_f8f6f4 v[56:59], v[8:15], v[216:223], v[56:59], v196, v196 op_sel_hi:[0,0,0]
	v_mfma_scale_f32_16x16x128_f8f6f4 v[44:47], v[0:7], v[224:231], v[44:47], v196, v196 op_sel_hi:[0,0,0]
	v_mfma_scale_f32_16x16x128_f8f6f4 v[40:43], v[8:15], v[224:231], v[40:43], v196, v196 op_sel_hi:[0,0,0]
	v_mfma_scale_f32_16x16x128_f8f6f4 v[84:87], v[16:23], v[200:207], v[84:87], v196, v196 op_sel_hi:[0,0,0]
	v_mfma_scale_f32_16x16x128_f8f6f4 v[80:83], v[24:31], v[200:207], v[80:83], v196, v196 op_sel_hi:[0,0,0]
	v_mfma_scale_f32_16x16x128_f8f6f4 v[68:71], v[16:23], v[208:215], v[68:71], v196, v196 op_sel_hi:[0,0,0]
	v_mfma_scale_f32_16x16x128_f8f6f4 v[64:67], v[24:31], v[208:215], v[64:67], v196, v196 op_sel_hi:[0,0,0]
	v_mfma_scale_f32_16x16x128_f8f6f4 v[52:55], v[16:23], v[216:223], v[52:55], v196, v196 op_sel_hi:[0,0,0]
	v_mfma_scale_f32_16x16x128_f8f6f4 v[48:51], v[24:31], v[216:223], v[48:51], v196, v196 op_sel_hi:[0,0,0]
	v_mfma_scale_f32_16x16x128_f8f6f4 v[36:39], v[16:23], v[224:231], v[36:39], v196, v196 op_sel_hi:[0,0,0]
	v_mfma_scale_f32_16x16x128_f8f6f4 v[32:35], v[24:31], v[224:231], v[32:35], v196, v196 op_sel_hi:[0,0,0]
	s_barrier
	s_add_i32 s59, s59, 2
	s_add_u32 s57, s57, 0x100
	s_addc_u32 s58, s58, 0
	s_add_u32 s34, s34, 0x100
	s_addc_u32 s35, s35, 0
	s_cmp_gt_u32 s59, 13
	s_cbranch_scc0 .LBB0_1255
	s_setprio 0
	s_and_b64 vcc, exec, s[16:17]
	s_cbranch_vccz .LBB0_1258
	s_barrier
.LBB0_1258:
	v_lshl_add_u32 v30, s28, 8, v190
	v_lshl_or_b32 v24, s30, 8, v192
	v_ashrrev_i32_e32 v25, 31, v24
	v_ashrrev_i32_e32 v31, 31, v30
	s_nop 7
	s_nop 7
	s_nop 7
	v_lshl_add_u64 v[28:29], v[24:25], 1, s[6:7]
	v_lshlrev_b64 v[0:1], 13, v[30:31]
	v_lshl_add_u64 v[26:27], v[30:31], 3, s[12:13]
	v_lshl_add_u64 v[188:189], v[28:29], 0, v[0:1]
	global_load_dwordx2 v[208:209], v[26:27], off
	global_load_dwordx2 v[232:233], v[26:27], off offset:128
	global_load_dwordx2 v[234:235], v[26:27], off offset:256
	global_load_dwordx2 v[236:237], v[26:27], off offset:384
	global_load_dwordx2 v[238:239], v[26:27], off offset:1024
	global_load_dwordx2 v[240:241], v[26:27], off offset:1152
	global_load_dwordx2 v[242:243], v[26:27], off offset:1280
	global_load_dwordx2 v[244:245], v[26:27], off offset:1408
	global_load_dwordx4 v[200:203], v[188:189], off
	v_or_b32_e32 v184, 16, v30
	v_or_b32_e32 v180, 32, v30
	v_or_b32_e32 v176, 48, v30
	v_ashrrev_i32_e32 v185, 31, v184
	v_ashrrev_i32_e32 v181, 31, v180
	v_ashrrev_i32_e32 v177, 31, v176
	v_lshlrev_b64 v[0:1], 12, v[30:31]
	v_lshlrev_b64 v[2:3], 13, v[184:185]
	v_lshlrev_b64 v[4:5], 13, v[180:181]
	v_lshlrev_b64 v[6:7], 13, v[176:177]
	v_lshl_add_u64 v[0:1], v[0:1], 0, v[24:25]
	v_lshl_add_u64 v[186:187], v[28:29], 0, v[2:3]
	v_lshl_add_u64 v[182:183], v[28:29], 0, v[4:5]
	v_lshl_add_u64 v[178:179], v[28:29], 0, v[6:7]
	v_lshl_add_u64 v[210:211], s[10:11], 0, v[0:1]
	global_load_dwordx4 v[204:207], v[188:189], off offset:256
	global_load_dwordx4 v[20:23], v[186:187], off
	global_load_dwordx4 v[16:19], v[186:187], off offset:256
	global_load_dwordx4 v[12:15], v[182:183], off
	global_load_dwordx4 v[8:11], v[182:183], off offset:256
	global_load_dwordx4 v[4:7], v[178:179], off
	global_load_dwordx4 v[0:3], v[178:179], off offset:256
	s_mov_b64 s[96:97], 0x100000
	v_lshl_add_u64 v[220:221], v[188:189], 0, s[96:97]
	global_load_dwordx4 v[220:223], v[220:221], off
	v_lshl_add_u64 v[224:225], v[188:189], 0, s[96:97]
	global_load_dwordx4 v[224:227], v[224:225], off offset:256
	v_lshl_add_u64 v[228:229], v[186:187], 0, s[96:97]
	global_load_dwordx4 v[228:231], v[228:229], off
	v_lshl_add_u64 v[246:247], v[186:187], 0, s[96:97]
	global_load_dwordx4 v[246:249], v[246:247], off offset:256
	v_lshl_add_u64 v[250:251], v[182:183], 0, s[96:97]
	global_load_dwordx4 v[250:253], v[250:251], off
	s_waitcnt vmcnt(0)
	s_mov_b32 s94, 1
	v_ffbh_u32_e32 v216, v209
	v_min_u32_e32 v216, 32, v216
	v_lshlrev_b64 v[208:209], v216, v[208:209]
	v_min_u32_e32 v208, 1, v208
	v_or_b32_e32 v208, v209, v208
	v_cvt_f32_u32_e32 v208, v208
	v_lshlrev_b32_e32 v212, 16, v200
	v_and_b32_e32 v213, 0xffff0000, v200
	v_lshlrev_b32_e32 v200, 16, v201
	v_and_b32_e32 v201, 0xffff0000, v201
	v_lshlrev_b32_e32 v214, 16, v202
	v_and_b32_e32 v215, 0xffff0000, v202
	v_lshlrev_b32_e32 v202, 16, v203
	v_and_b32_e32 v203, 0xffff0000, v203
	v_pk_fma_f32 v[158:159], v[158:159], s[18:19], v[200:201] op_sel_hi:[1,0,1]
	v_pk_fma_f32 v[156:157], v[156:157], s[18:19], v[212:213] op_sel_hi:[1,0,1]
	v_pk_fma_f32 v[200:201], v[154:155], s[18:19], v[202:203] op_sel_hi:[1,0,1]
	v_pk_fma_f32 v[202:203], v[152:153], s[18:19], v[214:215] op_sel_hi:[1,0,1]
	v_sub_u32_e32 v212, 32, v216
	v_cvt_pk_bf16_f32 v152, v156, v157
	v_cvt_pk_bf16_f32 v153, v158, v159
	v_cvt_pk_bf16_f32 v154, v202, v203
	v_cvt_pk_bf16_f32 v155, v200, v201
	global_store_dwordx4 v[188:189], v[152:155], off
	v_mul_f32_e32 v213, v157, v157
	v_mul_f32_e32 v214, v159, v159
	v_ldexp_f32 v152, v208, v212
	v_fmamk_f32 v152, v152, 0x2f800000, v197
	v_rsq_f32_e32 v152, v152
	v_mul_f32_e32 v209, v203, v203
	v_fmac_f32_e32 v213, v156, v156
	v_fmac_f32_e32 v214, v158, v158
	v_mul_f32_e32 v208, 0x41fe0000, v152
	v_mul_f32_e32 v152, v208, v156
	v_mul_f32_e32 v153, v208, v157
	v_mul_f32_e32 v155, v208, v158
	v_mul_f32_e32 v156, v208, v159
	v_mul_f32_e32 v158, v208, v203
	v_fmac_f32_e32 v209, v202, v202
	v_mul_f32_e32 v157, v208, v202
	v_mul_f32_e32 v159, v208, v200
	v_mul_f32_e32 v202, v208, v201
	v_med3_f32 v152, v152, s53, v199
	v_med3_f32 v153, v153, s53, v199
	v_med3_f32 v156, v156, s53, v199
	v_med3_f32 v158, v158, s53, v199
	v_med3_f32 v155, v155, s53, v199
	v_med3_f32 v157, v157, s53, v199
	v_med3_f32 v159, v159, s53, v199
	v_med3_f32 v202, v202, s53, v199
	v_rndne_f32_e32 v152, v152
	v_rndne_f32_e32 v153, v153
	v_rndne_f32_e32 v156, v156
	v_rndne_f32_e32 v158, v158
	v_rndne_f32_e32 v155, v155
	v_rndne_f32_e32 v157, v157
	v_rndne_f32_e32 v159, v159
	v_rndne_f32_e32 v202, v202
	v_cvt_i32_f32_e32 v152, v152
	v_cvt_i32_f32_e32 v153, v153
	v_cvt_i32_f32_e32 v156, v156
	v_cvt_i32_f32_e32 v158, v158
	v_cvt_i32_f32_sdwa v155, v155 dst_sel:WORD_1 dst_unused:UNUSED_PAD src0_sel:DWORD
	v_cvt_i32_f32_e32 v157, v157
	v_cvt_i32_f32_sdwa v159, v159 dst_sel:WORD_1 dst_unused:UNUSED_PAD src0_sel:DWORD
	v_cvt_i32_f32_e32 v202, v202
	v_lshlrev_b32_e32 v153, 8, v153
	v_perm_b32 v152, v156, v152, s54
	v_lshlrev_b32_e32 v156, 8, v158
	v_and_b32_e32 v155, 0xff0000, v155
	v_and_b32_e32 v158, 0xff0000, v159
	v_perm_b32 v157, v202, v157, s54
	v_and_b32_e32 v153, 0xff00, v153
	v_and_b32_e32 v156, 0xff00, v156
	v_or3_b32 v152, v152, v153, v155
	v_or3_b32 v153, v157, v156, v158
	v_add_f32_e32 v154, v213, v214
	global_store_dwordx2 v[210:211], v[152:153], off
	v_mul_f32_e32 v153, v201, v201
	v_add_f32_e32 v152, v209, v154
	v_fmac_f32_e32 v153, v200, v200
	v_add_f32_e32 v200, v153, v152
	v_lshlrev_b32_e32 v152, 16, v204
	v_and_b32_e32 v153, 0xffff0000, v204
	v_lshlrev_b32_e32 v154, 16, v205
	v_and_b32_e32 v155, 0xffff0000, v205
	v_lshlrev_b32_e32 v156, 16, v206
	v_and_b32_e32 v157, 0xffff0000, v206
	v_lshlrev_b32_e32 v158, 16, v207
	v_and_b32_e32 v159, 0xffff0000, v207
	v_pk_fma_f32 v[150:151], v[150:151], s[18:19], v[154:155] op_sel_hi:[1,0,1]
	v_pk_fma_f32 v[148:149], v[148:149], s[18:19], v[152:153] op_sel_hi:[1,0,1]
	v_pk_fma_f32 v[154:155], v[144:145], s[18:19], v[156:157] op_sel_hi:[1,0,1]
	v_cvt_pk_bf16_f32 v144, v148, v149
	v_cvt_pk_bf16_f32 v145, v150, v151
	v_pk_fma_f32 v[152:153], v[146:147], s[18:19], v[158:159] op_sel_hi:[1,0,1]
	v_cvt_pk_bf16_f32 v146, v154, v155
	s_nop 0
	v_cvt_pk_bf16_f32 v147, v152, v153
	global_store_dwordx4 v[188:189], v[144:147], off offset:256
	s_nop 1
	v_mul_f32_e32 v145, v208, v149
	v_mul_f32_e32 v144, v208, v148
	v_mul_f32_e32 v146, v208, v150
	v_mul_f32_e32 v147, v208, v151
	v_med3_f32 v145, v145, s53, v199
	v_med3_f32 v144, v144, s53, v199
	v_rndne_f32_e32 v145, v145
	v_med3_f32 v146, v146, s53, v199
	v_med3_f32 v147, v147, s53, v199
	v_rndne_f32_e32 v144, v144
	v_cvt_i32_f32_e32 v145, v145
	v_rndne_f32_e32 v146, v146
	v_rndne_f32_e32 v147, v147
	v_cvt_i32_f32_e32 v144, v144
	v_cvt_i32_f32_sdwa v146, v146 dst_sel:WORD_1 dst_unused:UNUSED_PAD src0_sel:DWORD
	v_cvt_i32_f32_e32 v147, v147
	v_lshlrev_b32_e32 v145, 8, v145
	v_and_b32_e32 v145, 0xff00, v145
	v_and_b32_e32 v146, 0xff0000, v146
	v_perm_b32 v144, v147, v144, s54
	v_or3_b32 v156, v144, v145, v146
	v_mul_f32_e32 v145, v208, v155
	v_med3_f32 v145, v145, s53, v199
	v_rndne_f32_e32 v145, v145
	v_cvt_i32_f32_e32 v145, v145
	v_mul_f32_e32 v144, v208, v154
	v_med3_f32 v144, v144, s53, v199
	v_rndne_f32_e32 v144, v144
	v_mul_f32_e32 v146, v208, v152
	v_cvt_i32_f32_e32 v157, v144
	v_lshlrev_b32_e32 v144, 8, v145
	v_and_b32_e32 v158, 0xff00, v144
	v_med3_f32 v144, v146, s53, v199
	v_rndne_f32_e32 v145, v144
	v_mul_f32_e32 v144, v149, v149
	v_mul_f32_e32 v146, v151, v151
	v_fmac_f32_e32 v144, v148, v148
	v_fmac_f32_e32 v146, v150, v150
	v_add_f32_e32 v144, v144, v146
	v_mul_f32_e32 v146, v155, v155
	v_fmac_f32_e32 v146, v154, v154
	v_add_f32_e32 v144, v146, v144
	v_mul_f32_e32 v146, v153, v153
	v_fmac_f32_e32 v146, v152, v152
	v_add_f32_e32 v144, v146, v144
	v_and_b32_e32 v148, 64, v198
	v_add_f32_e32 v146, v200, v144
	v_xor_b32_e32 v144, 16, v198
	v_add_u32_e32 v148, 64, v148
	v_cmp_lt_i32_e32 vcc, v144, v148
	v_mul_f32_e32 v147, v208, v153
	v_cvt_i32_f32_sdwa v150, v145 dst_sel:WORD_1 dst_unused:UNUSED_PAD src0_sel:DWORD
	v_cndmask_b32_e32 v144, v198, v144, vcc
	v_lshlrev_b32_e32 v144, 2, v144
	ds_bpermute_b32 v149, v144, v146
	v_med3_f32 v145, v147, s53, v199
	v_rndne_f32_e32 v145, v145
	v_cvt_i32_f32_e32 v151, v145
	v_xor_b32_e32 v145, 32, v198
	v_cmp_lt_i32_e32 vcc, v145, v148
	s_waitcnt lgkmcnt(0)
	v_add_f32_e32 v146, v146, v149
	v_and_b32_e32 v148, 0xff0000, v150
	v_cndmask_b32_e32 v145, v198, v145, vcc
	v_lshlrev_b32_e32 v145, 2, v145
	ds_bpermute_b32 v147, v145, v146
	v_perm_b32 v149, v151, v157, s54
	v_or3_b32 v157, v149, v158, v148
	global_store_dwordx2 v[210:211], v[156:157], off offset:128
	s_and_saveexec_b64 s[28:29], s[2:3]
	s_cbranch_execz .LBB0_1260
	s_waitcnt lgkmcnt(0)
	v_add_f32_e32 v146, v146, v147
	v_fma_f32 v146, v146, s55, 0.5
	v_trunc_f32_e32 v146, v146
	v_mul_f32_e32 v147, 0x2f800000, v146
	v_floor_f32_e32 v147, v147
	v_fmac_f32_e32 v146, 0xcf800000, v147
	v_cvt_u32_f32_e32 v146, v146
	v_cvt_u32_f32_e32 v147, v147
	v_lshl_add_u64 v[148:149], v[30:31], 3, s[8:9]
	global_atomic_add_x2 v[148:149], v[146:147], off

.LBB0_1335:
	s_mov_b64 s[0:1], s[78:79]
	s_load_dword s0, s[0:1], 0xa8
	s_waitcnt lgkmcnt(0)
	s_cmp_gt_i32 s0, 11
	s_cbranch_scc1 .LBB0_1763
	s_mov_b64 s[0:1], s[78:79]
	s_load_dword s0, s[0:1], 0xac
	s_waitcnt lgkmcnt(0)
	s_cmp_lt_i32 s0, 12
	s_cbranch_scc1 .LBB0_1763
	s_mov_b32 s94, 0
	s_mov_b32 s95, -1
	s_mov_b64 s[0:1], s[78:79]
	s_load_dwordx2 s[2:3], s[0:1], 0xa0
	s_cmpk_lt_i32 s87, 0x1000
	s_mov_b32 s6, -1
	s_cselect_b64 s[4:5], -1, 0
	s_cmpk_gt_i32 s87, 0xfff
	s_cbranch_scc1 .LBB0_1343
	s_ashr_i32 s0, s87, 31
	s_lshr_b32 s0, s0, 29
	s_add_i32 s7, s87, s0
	s_and_b32 s0, s7, -8
	s_sub_i32 s8, s87, s0
	s_cmp_gt_i32 s8, -1
	s_cbranch_scc0 .LBB0_1340
	s_lshl_b32 s9, s8, 9
	s_cbranch_execz .LBB0_1341
	s_branch .LBB0_1342

.Lsp_skip8:
.LBB0_1356:
	ds_read_b128 v[144:147], v180
	ds_read_b128 v[148:151], v180 offset:1024
	ds_read_b128 v[152:155], v180 offset:2048
	ds_read_b128 v[156:159], v180 offset:3072
	ds_read_b128 v[160:163], v181
	ds_read_b128 v[164:167], v181 offset:1024
	ds_read_b128 v[168:171], v181 offset:2048
	ds_read_b128 v[172:175], v181 offset:3072
	ds_read_b128 v[186:189], v182
	ds_read_b128 v[190:193], v182 offset:1024
	ds_read_b128 v[194:197], v182 offset:2048
	ds_read_b128 v[198:201], v182 offset:3072
	ds_read_b128 v[202:205], v182 offset:4096
	ds_read_b128 v[206:209], v182 offset:5120
	ds_read_b128 v[210:213], v182 offset:6144
	ds_read_b128 v[214:217], v182 offset:7168
	s_add_u32 s34, s30, 0xfff80080
	s_addc_u32 s35, s31, -1
	s_cmp_eq_u32 s58, 28
	s_cselect_b32 s37, s1, s35
	s_cselect_b32 s36, s23, s34
	s_cselect_b32 s35, s21, s57
	s_cselect_b32 s34, s29, s33
	s_add_i32 m0, s43, 0xc000
	s_nop 0
	global_load_lds_dwordx4 v138, s[30:31]
	s_add_i32 m0, s43, 0xe000
	s_nop 0
	global_load_lds_dwordx4 v136, s[30:31]
	s_cmp_eq_u32 s94, 1
	s_cbranch_scc1 .Lrx11_0a
	s_waitcnt vmcnt(8)
	s_branch .Lrx11_0b

.Lrx11_0b:
	s_waitcnt lgkmcnt(0)
	s_barrier
	s_waitcnt lgkmcnt(0)
	v_mfma_i32_16x16x64_i8 v[124:127], v[144:147], v[186:189], v[124:127]
	v_mfma_i32_16x16x64_i8 v[120:123], v[152:155], v[186:189], v[120:123]
	v_mfma_i32_16x16x64_i8 v[108:111], v[144:147], v[194:197], v[108:111]
	v_mfma_i32_16x16x64_i8 v[104:107], v[152:155], v[194:197], v[104:107]
	s_add_u32 s98, s34, s16
	s_addc_u32 s99, s35, s17
	s_add_i32 s59, s52, s42
	v_mfma_i32_16x16x64_i8 v[92:95], v[144:147], v[202:205], v[92:95]
	s_add_u32 s100, s36, s16
	s_addc_u32 s101, s37, s17
	v_mfma_i32_16x16x64_i8 v[88:91], v[152:155], v[202:205], v[88:91]
	v_mfma_i32_16x16x64_i8 v[76:79], v[144:147], v[210:213], v[76:79]
	v_mfma_i32_16x16x64_i8 v[72:75], v[152:155], v[210:213], v[72:75]
	s_add_u32 s60, s34, 0x80000
	v_mfma_i32_16x16x64_i8 v[124:127], v[148:151], v[190:193], v[124:127]
	v_mfma_i32_16x16x64_i8 v[120:123], v[156:159], v[190:193], v[120:123]
	v_mfma_i32_16x16x64_i8 v[108:111], v[148:151], v[198:201], v[108:111]
	v_mfma_i32_16x16x64_i8 v[104:107], v[156:159], v[198:201], v[104:107]
	s_addc_u32 s61, s35, 0
	v_mfma_i32_16x16x64_i8 v[92:95], v[148:151], v[206:209], v[92:95]
	v_mfma_i32_16x16x64_i8 v[88:91], v[156:159], v[206:209], v[88:91]
	v_mfma_i32_16x16x64_i8 v[76:79], v[148:151], v[214:217], v[76:79]
	v_mfma_i32_16x16x64_i8 v[72:75], v[156:159], v[214:217], v[72:75]
	v_mfma_i32_16x16x64_i8 v[116:119], v[160:163], v[186:189], v[116:119]
	v_mfma_i32_16x16x64_i8 v[112:115], v[168:171], v[186:189], v[112:115]
	v_mfma_i32_16x16x64_i8 v[100:103], v[160:163], v[194:197], v[100:103]
	v_mfma_i32_16x16x64_i8 v[96:99], v[168:171], v[194:197], v[96:99]
	v_mfma_i32_16x16x64_i8 v[84:87], v[160:163], v[202:205], v[84:87]
	v_mfma_i32_16x16x64_i8 v[80:83], v[168:171], v[202:205], v[80:83]
	v_mfma_i32_16x16x64_i8 v[68:71], v[160:163], v[210:213], v[68:71]
	v_mfma_i32_16x16x64_i8 v[64:67], v[168:171], v[210:213], v[64:67]
	v_mfma_i32_16x16x64_i8 v[116:119], v[164:167], v[190:193], v[116:119]
	v_mfma_i32_16x16x64_i8 v[112:115], v[172:175], v[190:193], v[112:115]
	v_mfma_i32_16x16x64_i8 v[100:103], v[164:167], v[198:201], v[100:103]
	v_mfma_i32_16x16x64_i8 v[96:99], v[172:175], v[198:201], v[96:99]
	v_mfma_i32_16x16x64_i8 v[84:87], v[164:167], v[206:209], v[84:87]
	v_mfma_i32_16x16x64_i8 v[80:83], v[172:175], v[206:209], v[80:83]
	v_mfma_i32_16x16x64_i8 v[68:71], v[164:167], v[214:217], v[68:71]
	v_mfma_i32_16x16x64_i8 v[64:67], v[172:175], v[214:217], v[64:67]
	s_barrier
	ds_read_b128 v[186:189], v182 offset:16384
	ds_read_b128 v[190:193], v182 offset:17408
	ds_read_b128 v[194:197], v182 offset:18432
	ds_read_b128 v[198:201], v182 offset:19456
	ds_read_b128 v[202:205], v182 offset:20480
	ds_read_b128 v[206:209], v182 offset:21504
	ds_read_b128 v[210:213], v182 offset:22528
	ds_read_b128 v[214:217], v182 offset:23552
	s_mov_b32 m0, s59
	s_nop 0
	global_load_lds_dwordx4 v130, s[34:35]
	s_add_i32 m0, s59, 0x2000
	s_add_i32 s59, s53, s42
	global_load_lds_dwordx4 v134, s[34:35]
	s_mov_b32 m0, s59
	s_nop 0
	global_load_lds_dwordx4 v130, s[60:61]
	s_add_i32 m0, s59, 0x2000
	s_nop 0
	global_load_lds_dwordx4 v134, s[60:61]
	s_mov_b32 m0, s43
	s_nop 0
	global_load_lds_dwordx4 v128, s[36:37]
	s_mov_b32 m0, s44
	s_nop 0
	global_load_lds_dwordx4 v132, s[36:37]
	s_cmp_eq_u32 s94, 1
	s_cbranch_scc1 .Lrx11_1a
	s_waitcnt vmcnt(8)
	s_branch .Lrx11_1b

.Lrx11_1b:
	s_mov_b32 s94, 0
	s_waitcnt lgkmcnt(0)
	s_barrier
	s_waitcnt lgkmcnt(0)
	v_mfma_i32_16x16x64_i8 v[60:63], v[144:147], v[186:189], v[60:63]
	v_mfma_i32_16x16x64_i8 v[56:59], v[152:155], v[186:189], v[56:59]
	v_mfma_i32_16x16x64_i8 v[44:47], v[144:147], v[194:197], v[44:47]
	v_mfma_i32_16x16x64_i8 v[40:43], v[152:155], v[194:197], v[40:43]
	s_add_i32 s59, 0, 0x18000
	v_mfma_i32_16x16x64_i8 v[28:31], v[144:147], v[202:205], v[28:31]
	v_mfma_i32_16x16x64_i8 v[24:27], v[152:155], v[202:205], v[24:27]
	s_add_i32 s60, 0, 0x1c000
	v_mfma_i32_16x16x64_i8 v[12:15], v[144:147], v[210:213], v[12:15]
	v_mfma_i32_16x16x64_i8 v[8:11], v[152:155], v[210:213], v[8:11]
	s_add_u32 s36, s36, 0x80000
	v_mfma_i32_16x16x64_i8 v[60:63], v[148:151], v[190:193], v[60:63]
	v_mfma_i32_16x16x64_i8 v[56:59], v[156:159], v[190:193], v[56:59]
	s_addc_u32 s37, s37, 0
	v_mfma_i32_16x16x64_i8 v[44:47], v[148:151], v[198:201], v[44:47]
	v_mfma_i32_16x16x64_i8 v[40:43], v[156:159], v[198:201], v[40:43]
	v_mfma_i32_16x16x64_i8 v[28:31], v[148:151], v[206:209], v[28:31]
	v_mfma_i32_16x16x64_i8 v[24:27], v[156:159], v[206:209], v[24:27]
	v_mfma_i32_16x16x64_i8 v[12:15], v[148:151], v[214:217], v[12:15]
	v_mfma_i32_16x16x64_i8 v[8:11], v[156:159], v[214:217], v[8:11]
	v_mfma_i32_16x16x64_i8 v[52:55], v[160:163], v[186:189], v[52:55]
	v_mfma_i32_16x16x64_i8 v[48:51], v[168:171], v[186:189], v[48:51]
	v_mfma_i32_16x16x64_i8 v[36:39], v[160:163], v[194:197], v[36:39]
	v_mfma_i32_16x16x64_i8 v[32:35], v[168:171], v[194:197], v[32:35]
	v_mfma_i32_16x16x64_i8 v[20:23], v[160:163], v[202:205], v[20:23]
	v_mfma_i32_16x16x64_i8 v[16:19], v[168:171], v[202:205], v[16:19]
	v_mfma_i32_16x16x64_i8 v[4:7], v[160:163], v[210:213], v[4:7]
	v_mfma_i32_16x16x64_i8 v[0:3], v[168:171], v[210:213], v[0:3]
	v_mfma_i32_16x16x64_i8 v[52:55], v[164:167], v[190:193], v[52:55]
	v_mfma_i32_16x16x64_i8 v[48:51], v[172:175], v[190:193], v[48:51]
	v_mfma_i32_16x16x64_i8 v[36:39], v[164:167], v[198:201], v[36:39]
	v_mfma_i32_16x16x64_i8 v[32:35], v[172:175], v[198:201], v[32:35]
	v_mfma_i32_16x16x64_i8 v[20:23], v[164:167], v[206:209], v[20:23]
	v_mfma_i32_16x16x64_i8 v[16:19], v[172:175], v[206:209], v[16:19]
	v_mfma_i32_16x16x64_i8 v[4:7], v[164:167], v[214:217], v[4:7]
	v_mfma_i32_16x16x64_i8 v[0:3], v[172:175], v[214:217], v[0:3]
	s_barrier
	ds_read_b128 v[186:189], v182 offset:32768
	ds_read_b128 v[190:193], v182 offset:33792
	ds_read_b128 v[194:197], v182 offset:34816
	ds_read_b128 v[198:201], v182 offset:35840
	ds_read_b128 v[202:205], v182 offset:36864
	ds_read_b128 v[206:209], v182 offset:37888
	ds_read_b128 v[210:213], v182 offset:38912
	ds_read_b128 v[214:217], v182 offset:39936
	v_add_u32_e32 v156, s59, v178
	v_add_u32_e32 v172, s60, v178
	ds_read_b128 v[144:147], v156
	ds_read_b128 v[148:151], v156 offset:1024
	ds_read_b128 v[152:155], v156 offset:2048
	ds_read_b128 v[156:159], v156 offset:3072
	ds_read_b128 v[160:163], v172
	ds_read_b128 v[164:167], v172 offset:1024
	ds_read_b128 v[168:171], v172 offset:2048
	ds_read_b128 v[172:175], v172 offset:3072
	s_mov_b32 m0, s45
	s_nop 0
	global_load_lds_dwordx4 v128, s[36:37]
	s_mov_b32 m0, s46
	s_nop 0
	global_load_lds_dwordx4 v132, s[36:37]
	s_waitcnt vmcnt(8)
	s_waitcnt lgkmcnt(0)
	s_barrier
	s_waitcnt lgkmcnt(0)
	v_mfma_i32_16x16x64_i8 v[124:127], v[144:147], v[186:189], v[124:127]
	v_mfma_i32_16x16x64_i8 v[120:123], v[152:155], v[186:189], v[120:123]
	v_mfma_i32_16x16x64_i8 v[108:111], v[144:147], v[194:197], v[108:111]
	v_mfma_i32_16x16x64_i8 v[104:107], v[152:155], v[194:197], v[104:107]
	s_add_i32 s36, s59, s42
	v_mfma_i32_16x16x64_i8 v[92:95], v[144:147], v[202:205], v[92:95]
	v_mfma_i32_16x16x64_i8 v[88:91], v[152:155], v[202:205], v[88:91]
	v_mfma_i32_16x16x64_i8 v[76:79], v[144:147], v[210:213], v[76:79]
	v_mfma_i32_16x16x64_i8 v[72:75], v[152:155], v[210:213], v[72:75]
	s_add_u32 s34, s34, 0x80080
	v_mfma_i32_16x16x64_i8 v[124:127], v[148:151], v[190:193], v[124:127]
	v_mfma_i32_16x16x64_i8 v[120:123], v[156:159], v[190:193], v[120:123]
	v_mfma_i32_16x16x64_i8 v[108:111], v[148:151], v[198:201], v[108:111]
	v_mfma_i32_16x16x64_i8 v[104:107], v[156:159], v[198:201], v[104:107]
	s_addc_u32 s35, s35, 0
	v_mfma_i32_16x16x64_i8 v[92:95], v[148:151], v[206:209], v[92:95]
	v_mfma_i32_16x16x64_i8 v[88:91], v[156:159], v[206:209], v[88:91]
	v_mfma_i32_16x16x64_i8 v[76:79], v[148:151], v[214:217], v[76:79]
	v_mfma_i32_16x16x64_i8 v[72:75], v[156:159], v[214:217], v[72:75]
	v_mfma_i32_16x16x64_i8 v[116:119], v[160:163], v[186:189], v[116:119]
	v_mfma_i32_16x16x64_i8 v[112:115], v[168:171], v[186:189], v[112:115]
	v_mfma_i32_16x16x64_i8 v[100:103], v[160:163], v[194:197], v[100:103]
	v_mfma_i32_16x16x64_i8 v[96:99], v[168:171], v[194:197], v[96:99]
	v_mfma_i32_16x16x64_i8 v[84:87], v[160:163], v[202:205], v[84:87]
	v_mfma_i32_16x16x64_i8 v[80:83], v[168:171], v[202:205], v[80:83]
	v_mfma_i32_16x16x64_i8 v[68:71], v[160:163], v[210:213], v[68:71]
	v_mfma_i32_16x16x64_i8 v[64:67], v[168:171], v[210:213], v[64:67]
	v_mfma_i32_16x16x64_i8 v[116:119], v[164:167], v[190:193], v[116:119]
	v_mfma_i32_16x16x64_i8 v[112:115], v[172:175], v[190:193], v[112:115]
	v_mfma_i32_16x16x64_i8 v[100:103], v[164:167], v[198:201], v[100:103]
	v_mfma_i32_16x16x64_i8 v[96:99], v[172:175], v[198:201], v[96:99]
	v_mfma_i32_16x16x64_i8 v[84:87], v[164:167], v[206:209], v[84:87]
	v_mfma_i32_16x16x64_i8 v[80:83], v[172:175], v[206:209], v[80:83]
	v_mfma_i32_16x16x64_i8 v[68:71], v[164:167], v[214:217], v[68:71]
	v_mfma_i32_16x16x64_i8 v[64:67], v[172:175], v[214:217], v[64:67]
	s_barrier
	ds_read_b128 v[186:189], v182 offset:49152
	ds_read_b128 v[190:193], v182 offset:50176
	ds_read_b128 v[194:197], v182 offset:51200
	ds_read_b128 v[198:201], v182 offset:52224
	ds_read_b128 v[202:205], v182 offset:53248
	ds_read_b128 v[206:209], v182 offset:54272
	ds_read_b128 v[210:213], v182 offset:55296
	ds_read_b128 v[214:217], v182 offset:56320
	s_mov_b32 m0, s36
	s_nop 0
	global_load_lds_dwordx4 v130, s[98:99]
	s_add_i32 m0, s36, 0x2000
	s_add_i32 s36, s60, s42
	global_load_lds_dwordx4 v134, s[98:99]
	s_mov_b32 m0, s36
	s_nop 0
	global_load_lds_dwordx4 v130, s[34:35]
	s_add_i32 m0, s36, 0x2000
	s_nop 0
	global_load_lds_dwordx4 v134, s[34:35]
	s_mov_b32 m0, s48
	s_nop 0
	global_load_lds_dwordx4 v128, s[100:101]
	s_mov_b32 m0, s49
	s_nop 0
	global_load_lds_dwordx4 v132, s[100:101]
	s_waitcnt vmcnt(8)
	s_waitcnt lgkmcnt(0)
	s_barrier
	s_waitcnt lgkmcnt(0)
	v_mfma_i32_16x16x64_i8 v[60:63], v[144:147], v[186:189], v[60:63]
	v_mfma_i32_16x16x64_i8 v[56:59], v[152:155], v[186:189], v[56:59]
	v_mfma_i32_16x16x64_i8 v[44:47], v[144:147], v[194:197], v[44:47]
	v_mfma_i32_16x16x64_i8 v[40:43], v[152:155], v[194:197], v[40:43]
	v_mfma_i32_16x16x64_i8 v[28:31], v[144:147], v[202:205], v[28:31]
	v_mfma_i32_16x16x64_i8 v[24:27], v[152:155], v[202:205], v[24:27]
	v_mfma_i32_16x16x64_i8 v[12:15], v[144:147], v[210:213], v[12:15]
	v_mfma_i32_16x16x64_i8 v[8:11], v[152:155], v[210:213], v[8:11]
	v_mfma_i32_16x16x64_i8 v[60:63], v[148:151], v[190:193], v[60:63]
	v_mfma_i32_16x16x64_i8 v[56:59], v[156:159], v[190:193], v[56:59]
	v_mfma_i32_16x16x64_i8 v[44:47], v[148:151], v[198:201], v[44:47]
	v_mfma_i32_16x16x64_i8 v[40:43], v[156:159], v[198:201], v[40:43]
	v_mfma_i32_16x16x64_i8 v[28:31], v[148:151], v[206:209], v[28:31]
	v_mfma_i32_16x16x64_i8 v[24:27], v[156:159], v[206:209], v[24:27]
	v_mfma_i32_16x16x64_i8 v[12:15], v[148:151], v[214:217], v[12:15]
	v_mfma_i32_16x16x64_i8 v[8:11], v[156:159], v[214:217], v[8:11]
	v_mfma_i32_16x16x64_i8 v[52:55], v[160:163], v[186:189], v[52:55]
	v_mfma_i32_16x16x64_i8 v[48:51], v[168:171], v[186:189], v[48:51]
	v_mfma_i32_16x16x64_i8 v[36:39], v[160:163], v[194:197], v[36:39]
	v_mfma_i32_16x16x64_i8 v[32:35], v[168:171], v[194:197], v[32:35]
	v_mfma_i32_16x16x64_i8 v[20:23], v[160:163], v[202:205], v[20:23]
	v_mfma_i32_16x16x64_i8 v[16:19], v[168:171], v[202:205], v[16:19]
	v_mfma_i32_16x16x64_i8 v[4:7], v[160:163], v[210:213], v[4:7]
	v_mfma_i32_16x16x64_i8 v[0:3], v[168:171], v[210:213], v[0:3]
	v_mfma_i32_16x16x64_i8 v[52:55], v[164:167], v[190:193], v[52:55]
	v_mfma_i32_16x16x64_i8 v[48:51], v[172:175], v[190:193], v[48:51]
	v_mfma_i32_16x16x64_i8 v[36:39], v[164:167], v[198:201], v[36:39]
	v_mfma_i32_16x16x64_i8 v[32:35], v[172:175], v[198:201], v[32:35]
	v_mfma_i32_16x16x64_i8 v[20:23], v[164:167], v[206:209], v[20:23]
	v_mfma_i32_16x16x64_i8 v[16:19], v[172:175], v[206:209], v[16:19]
	v_mfma_i32_16x16x64_i8 v[4:7], v[164:167], v[214:217], v[4:7]
	v_mfma_i32_16x16x64_i8 v[0:3], v[172:175], v[214:217], v[0:3]
	s_barrier
	s_add_i32 s58, s58, 2
	s_add_u32 s33, s33, 0x100
	s_addc_u32 s57, s57, 0
	s_add_u32 s30, s30, 0x100
	s_addc_u32 s31, s31, 0
	s_cmp_gt_u32 s58, 29
	s_cbranch_scc0 .LBB0_1356
	s_setprio 0
	s_and_b64 vcc, exec, s[18:19]
	s_cbranch_vccz .LBB0_1359
	s_barrier

.Llean_p11:
	s_mov_b32 s94, 1
	v_max3_i32 v228, v124, v125, v126
	v_max3_i32 v228, v228, v127, v120
	v_max3_i32 v228, v228, v121, v122
	v_max3_i32 v228, v228, v123, v116
	v_max3_i32 v228, v228, v117, v118
	v_max3_i32 v228, v228, v119, v112
	v_max3_i32 v228, v228, v113, v114
	v_max_i32_e32 v228, v228, v115
	v_cmp_ge_i32_e32 vcc, v228, v233
	v_max3_i32 v228, v108, v109, v110
	v_max3_i32 v228, v228, v111, v104
	v_max3_i32 v228, v228, v105, v106
	v_max3_i32 v228, v228, v107, v100
	v_max3_i32 v228, v228, v101, v102
	v_max3_i32 v228, v228, v103, v96
	v_max3_i32 v228, v228, v97, v98
	v_max_i32_e32 v228, v228, v99
	v_cmp_ge_i32_e64 s[96:97], v228, v235
	s_or_b64 vcc, vcc, s[96:97]
	v_max3_i32 v228, v92, v93, v94
	v_max3_i32 v228, v228, v95, v88
	v_max3_i32 v228, v228, v89, v90
	v_max3_i32 v228, v228, v91, v84
	v_max3_i32 v228, v228, v85, v86
	v_max3_i32 v228, v228, v87, v80
	v_max3_i32 v228, v228, v81, v82
	v_max_i32_e32 v228, v228, v83
	v_cmp_ge_i32_e64 s[96:97], v228, v237
	s_or_b64 vcc, vcc, s[96:97]
	v_max3_i32 v228, v76, v77, v78
	v_max3_i32 v228, v228, v79, v72
	v_max3_i32 v228, v228, v73, v74
	v_max3_i32 v228, v228, v75, v68
	v_max3_i32 v228, v228, v69, v70
	v_max3_i32 v228, v228, v71, v64
	v_max3_i32 v228, v228, v65, v66
	v_max_i32_e32 v228, v228, v67
	v_cmp_ge_i32_e64 s[96:97], v228, v239
	s_or_b64 vcc, vcc, s[96:97]
	v_max3_i32 v228, v60, v61, v62
	v_max3_i32 v228, v228, v63, v56
	v_max3_i32 v228, v228, v57, v58
	v_max3_i32 v228, v228, v59, v52
	v_max3_i32 v228, v228, v53, v54
	v_max3_i32 v228, v228, v55, v48
	v_max3_i32 v228, v228, v49, v50
	v_max_i32_e32 v228, v228, v51
	v_cmp_ge_i32_e64 s[96:97], v228, v241
	s_or_b64 vcc, vcc, s[96:97]
	v_max3_i32 v228, v44, v45, v46
	v_max3_i32 v228, v228, v47, v40
	v_max3_i32 v228, v228, v41, v42
	v_max3_i32 v228, v228, v43, v36
	v_max3_i32 v228, v228, v37, v38
	v_max3_i32 v228, v228, v39, v32
	v_max3_i32 v228, v228, v33, v34
	v_max_i32_e32 v228, v228, v35
	v_cmp_ge_i32_e64 s[96:97], v228, v243
	s_or_b64 vcc, vcc, s[96:97]
	v_max3_i32 v228, v28, v29, v30
	v_max3_i32 v228, v228, v31, v24
	v_max3_i32 v228, v228, v25, v26
	v_max3_i32 v228, v228, v27, v20
	v_max3_i32 v228, v228, v21, v22
	v_max3_i32 v228, v228, v23, v16
	v_max3_i32 v228, v228, v17, v18
	v_max_i32_e32 v228, v228, v19
	v_cmp_ge_i32_e64 s[96:97], v228, v245
	s_or_b64 vcc, vcc, s[96:97]
	v_max3_i32 v228, v12, v13, v14
	v_max3_i32 v228, v228, v15, v8
	v_max3_i32 v228, v228, v9, v10
	v_max3_i32 v228, v228, v11, v4
	v_max3_i32 v228, v228, v5, v6
	v_max3_i32 v228, v228, v7, v0
	v_max3_i32 v228, v228, v1, v2
	v_max_i32_e32 v228, v228, v3
	v_cmp_ge_i32_e64 s[96:97], v228, v247
	s_or_b64 vcc, vcc, s[96:97]
	s_cbranch_vccnz .Lorig_p11
	v_lshl_add_u32 v146, s28, 8, v177
	v_mov_b32_e32 v147, 0
	v_lshl_or_b32 v148, s0, 8, v179
	v_mov_b32_e32 v149, 0
	v_lshlrev_b64 v[146:147], 14, v[146:147]
	v_lshl_add_u64 v[146:147], s[10:11], 0, v[146:147]
	v_lshl_add_u64 v[150:151], v[146:147], 0, v[148:149]
	v_mov_b32_e32 v154, 0x41700000
	v_mov_b32_e32 v155, 0x41700000
	v_cvt_f32_i32_e32 v124, v124
	v_cvt_f32_i32_e32 v125, v125
	v_cvt_f32_i32_e32 v126, v126
	v_cvt_f32_i32_e32 v127, v127
	v_cvt_f32_i32_e32 v120, v120
	v_cvt_f32_i32_e32 v121, v121
	v_cvt_f32_i32_e32 v122, v122
	v_cvt_f32_i32_e32 v123, v123
	v_pk_mul_f32 v[124:125], v[232:233], v[124:125] op_sel_hi:[0,1]
	v_pk_mul_f32 v[126:127], v[232:233], v[126:127] op_sel_hi:[0,1]
	v_pk_mul_f32 v[120:121], v[232:233], v[120:121] op_sel_hi:[0,1]
	v_pk_mul_f32 v[122:123], v[232:233], v[122:123] op_sel_hi:[0,1]
	v_max_f32_e32 v124, 0, v124
	v_max_f32_e32 v125, 0, v125
	v_max_f32_e32 v126, 0, v126
	v_max_f32_e32 v127, 0, v127
	v_max_f32_e32 v120, 0, v120
	v_max_f32_e32 v121, 0, v121
	v_max_f32_e32 v122, 0, v122
	v_max_f32_e32 v123, 0, v123
	v_pk_mul_f32 v[124:125], v[124:125], v[124:125]
	v_pk_mul_f32 v[126:127], v[126:127], v[126:127]
	v_pk_mul_f32 v[120:121], v[120:121], v[120:121]
	v_pk_mul_f32 v[122:123], v[122:123], v[122:123]
	v_pk_mul_f32 v[124:125], v[154:155], v[124:125]
	v_pk_mul_f32 v[126:127], v[154:155], v[126:127]
	v_pk_mul_f32 v[120:121], v[154:155], v[120:121]
	v_pk_mul_f32 v[122:123], v[154:155], v[122:123]
	v_min_f32_e32 v124, 0x437f0000, v124
	v_min_f32_e32 v125, 0x437f0000, v125
	v_min_f32_e32 v126, 0x437f0000, v126
	v_min_f32_e32 v127, 0x437f0000, v127
	v_min_f32_e32 v120, 0x437f0000, v120
	v_min_f32_e32 v121, 0x437f0000, v121
	v_min_f32_e32 v122, 0x437f0000, v122
	v_min_f32_e32 v123, 0x437f0000, v123
	v_rndne_f32_e32 v124, v124
	v_rndne_f32_e32 v125, v125
	v_rndne_f32_e32 v126, v126
	v_rndne_f32_e32 v127, v127
	v_rndne_f32_e32 v120, v120
	v_rndne_f32_e32 v121, v121
	v_rndne_f32_e32 v122, v122
	v_rndne_f32_e32 v123, v123
	v_cvt_i32_f32_e32 v186, v124
	v_cvt_i32_f32_e32 v187, v120
	v_cvt_i32_f32_sdwa v186, v125 dst_sel:BYTE_1 dst_unused:UNUSED_PRESERVE src0_sel:DWORD
	v_cvt_i32_f32_sdwa v187, v121 dst_sel:BYTE_1 dst_unused:UNUSED_PRESERVE src0_sel:DWORD
	v_cvt_i32_f32_sdwa v186, v126 dst_sel:BYTE_2 dst_unused:UNUSED_PRESERVE src0_sel:DWORD
	v_cvt_i32_f32_sdwa v187, v122 dst_sel:BYTE_2 dst_unused:UNUSED_PRESERVE src0_sel:DWORD
	v_cvt_i32_f32_sdwa v186, v127 dst_sel:BYTE_3 dst_unused:UNUSED_PRESERVE src0_sel:DWORD
	v_cvt_i32_f32_sdwa v187, v123 dst_sel:BYTE_3 dst_unused:UNUSED_PRESERVE src0_sel:DWORD
	v_xor_b32_e32 v186, s55, v186
	v_xor_b32_e32 v187, s55, v187
	global_store_dwordx2 v[150:151], v[186:187], off
	v_cvt_f32_i32_e32 v116, v116
	v_cvt_f32_i32_e32 v117, v117
	v_cvt_f32_i32_e32 v118, v118
	v_cvt_f32_i32_e32 v119, v119
	v_cvt_f32_i32_e32 v112, v112
	v_cvt_f32_i32_e32 v113, v113
	v_cvt_f32_i32_e32 v114, v114
	v_cvt_f32_i32_e32 v115, v115
	v_pk_mul_f32 v[116:117], v[232:233], v[116:117] op_sel_hi:[0,1]
	v_pk_mul_f32 v[118:119], v[232:233], v[118:119] op_sel_hi:[0,1]
	v_pk_mul_f32 v[112:113], v[232:233], v[112:113] op_sel_hi:[0,1]
	v_pk_mul_f32 v[114:115], v[232:233], v[114:115] op_sel_hi:[0,1]
	v_max_f32_e32 v116, 0, v116
	v_max_f32_e32 v117, 0, v117
	v_max_f32_e32 v118, 0, v118
	v_max_f32_e32 v119, 0, v119
	v_max_f32_e32 v112, 0, v112
	v_max_f32_e32 v113, 0, v113
	v_max_f32_e32 v114, 0, v114
	v_max_f32_e32 v115, 0, v115
	v_pk_mul_f32 v[116:117], v[116:117], v[116:117]
	v_pk_mul_f32 v[118:119], v[118:119], v[118:119]
	v_pk_mul_f32 v[112:113], v[112:113], v[112:113]
	v_pk_mul_f32 v[114:115], v[114:115], v[114:115]
	v_pk_mul_f32 v[116:117], v[154:155], v[116:117]
	v_pk_mul_f32 v[118:119], v[154:155], v[118:119]
	v_pk_mul_f32 v[112:113], v[154:155], v[112:113]
	v_pk_mul_f32 v[114:115], v[154:155], v[114:115]
	v_min_f32_e32 v116, 0x437f0000, v116
	v_min_f32_e32 v117, 0x437f0000, v117
	v_min_f32_e32 v118, 0x437f0000, v118
	v_min_f32_e32 v119, 0x437f0000, v119
	v_min_f32_e32 v112, 0x437f0000, v112
	v_min_f32_e32 v113, 0x437f0000, v113
	v_min_f32_e32 v114, 0x437f0000, v114
	v_min_f32_e32 v115, 0x437f0000, v115
	v_rndne_f32_e32 v116, v116
	v_rndne_f32_e32 v117, v117
	v_rndne_f32_e32 v118, v118
	v_rndne_f32_e32 v119, v119
	v_rndne_f32_e32 v112, v112
	v_rndne_f32_e32 v113, v113
	v_rndne_f32_e32 v114, v114
	v_rndne_f32_e32 v115, v115
	v_cvt_i32_f32_e32 v188, v116
	v_cvt_i32_f32_e32 v189, v112
	v_cvt_i32_f32_sdwa v188, v117 dst_sel:BYTE_1 dst_unused:UNUSED_PRESERVE src0_sel:DWORD
	v_cvt_i32_f32_sdwa v189, v113 dst_sel:BYTE_1 dst_unused:UNUSED_PRESERVE src0_sel:DWORD
	v_cvt_i32_f32_sdwa v188, v118 dst_sel:BYTE_2 dst_unused:UNUSED_PRESERVE src0_sel:DWORD
	v_cvt_i32_f32_sdwa v189, v114 dst_sel:BYTE_2 dst_unused:UNUSED_PRESERVE src0_sel:DWORD
	v_cvt_i32_f32_sdwa v188, v119 dst_sel:BYTE_3 dst_unused:UNUSED_PRESERVE src0_sel:DWORD
	v_cvt_i32_f32_sdwa v189, v115 dst_sel:BYTE_3 dst_unused:UNUSED_PRESERVE src0_sel:DWORD
	v_xor_b32_e32 v188, s55, v188
	v_xor_b32_e32 v189, s55, v189
	global_store_dwordx2 v[150:151], v[188:189], off offset:128
	v_add_co_u32_e32 v152, vcc, 0x40000, v150
	s_nop 1
	v_addc_co_u32_e32 v153, vcc, 0, v151, vcc
	v_cvt_f32_i32_e32 v108, v108
	v_cvt_f32_i32_e32 v109, v109
	v_cvt_f32_i32_e32 v110, v110
	v_cvt_f32_i32_e32 v111, v111
	v_cvt_f32_i32_e32 v104, v104
	v_cvt_f32_i32_e32 v105, v105
	v_cvt_f32_i32_e32 v106, v106
	v_cvt_f32_i32_e32 v107, v107
	v_pk_mul_f32 v[108:109], v[234:235], v[108:109] op_sel_hi:[0,1]
	v_pk_mul_f32 v[110:111], v[234:235], v[110:111] op_sel_hi:[0,1]
	v_pk_mul_f32 v[104:105], v[234:235], v[104:105] op_sel_hi:[0,1]
	v_pk_mul_f32 v[106:107], v[234:235], v[106:107] op_sel_hi:[0,1]
	v_max_f32_e32 v108, 0, v108
	v_max_f32_e32 v109, 0, v109
	v_max_f32_e32 v110, 0, v110
	v_max_f32_e32 v111, 0, v111
	v_max_f32_e32 v104, 0, v104
	v_max_f32_e32 v105, 0, v105
	v_max_f32_e32 v106, 0, v106
	v_max_f32_e32 v107, 0, v107
	v_pk_mul_f32 v[108:109], v[108:109], v[108:109]
	v_pk_mul_f32 v[110:111], v[110:111], v[110:111]
	v_pk_mul_f32 v[104:105], v[104:105], v[104:105]
	v_pk_mul_f32 v[106:107], v[106:107], v[106:107]
	v_pk_mul_f32 v[108:109], v[154:155], v[108:109]
	v_pk_mul_f32 v[110:111], v[154:155], v[110:111]
	v_pk_mul_f32 v[104:105], v[154:155], v[104:105]
	v_pk_mul_f32 v[106:107], v[154:155], v[106:107]
	v_min_f32_e32 v108, 0x437f0000, v108
	v_min_f32_e32 v109, 0x437f0000, v109
	v_min_f32_e32 v110, 0x437f0000, v110
	v_min_f32_e32 v111, 0x437f0000, v111
	v_min_f32_e32 v104, 0x437f0000, v104
	v_min_f32_e32 v105, 0x437f0000, v105
	v_min_f32_e32 v106, 0x437f0000, v106
	v_min_f32_e32 v107, 0x437f0000, v107
	v_rndne_f32_e32 v108, v108
	v_rndne_f32_e32 v109, v109
	v_rndne_f32_e32 v110, v110
	v_rndne_f32_e32 v111, v111
	v_rndne_f32_e32 v104, v104
	v_rndne_f32_e32 v105, v105
	v_rndne_f32_e32 v106, v106
	v_rndne_f32_e32 v107, v107
	v_cvt_i32_f32_e32 v190, v108
	v_cvt_i32_f32_e32 v191, v104
	v_cvt_i32_f32_sdwa v190, v109 dst_sel:BYTE_1 dst_unused:UNUSED_PRESERVE src0_sel:DWORD
	v_cvt_i32_f32_sdwa v191, v105 dst_sel:BYTE_1 dst_unused:UNUSED_PRESERVE src0_sel:DWORD
	v_cvt_i32_f32_sdwa v190, v110 dst_sel:BYTE_2 dst_unused:UNUSED_PRESERVE src0_sel:DWORD
	v_cvt_i32_f32_sdwa v191, v106 dst_sel:BYTE_2 dst_unused:UNUSED_PRESERVE src0_sel:DWORD
	v_cvt_i32_f32_sdwa v190, v111 dst_sel:BYTE_3 dst_unused:UNUSED_PRESERVE src0_sel:DWORD
	v_cvt_i32_f32_sdwa v191, v107 dst_sel:BYTE_3 dst_unused:UNUSED_PRESERVE src0_sel:DWORD
	v_xor_b32_e32 v190, s55, v190
	v_xor_b32_e32 v191, s55, v191
	global_store_dwordx2 v[152:153], v[190:191], off
	v_cvt_f32_i32_e32 v100, v100
	v_cvt_f32_i32_e32 v101, v101
	v_cvt_f32_i32_e32 v102, v102
	v_cvt_f32_i32_e32 v103, v103
	v_cvt_f32_i32_e32 v96, v96
	v_cvt_f32_i32_e32 v97, v97
	v_cvt_f32_i32_e32 v98, v98
	v_cvt_f32_i32_e32 v99, v99
	v_pk_mul_f32 v[100:101], v[234:235], v[100:101] op_sel_hi:[0,1]
	v_pk_mul_f32 v[102:103], v[234:235], v[102:103] op_sel_hi:[0,1]
	v_pk_mul_f32 v[96:97], v[234:235], v[96:97] op_sel_hi:[0,1]
	v_pk_mul_f32 v[98:99], v[234:235], v[98:99] op_sel_hi:[0,1]
	v_max_f32_e32 v100, 0, v100
	v_max_f32_e32 v101, 0, v101
	v_max_f32_e32 v102, 0, v102
	v_max_f32_e32 v103, 0, v103
	v_max_f32_e32 v96, 0, v96
	v_max_f32_e32 v97, 0, v97
	v_max_f32_e32 v98, 0, v98
	v_max_f32_e32 v99, 0, v99
	v_pk_mul_f32 v[100:101], v[100:101], v[100:101]
	v_pk_mul_f32 v[102:103], v[102:103], v[102:103]
	v_pk_mul_f32 v[96:97], v[96:97], v[96:97]
	v_pk_mul_f32 v[98:99], v[98:99], v[98:99]
	v_pk_mul_f32 v[100:101], v[154:155], v[100:101]
	v_pk_mul_f32 v[102:103], v[154:155], v[102:103]
	v_pk_mul_f32 v[96:97], v[154:155], v[96:97]
	v_pk_mul_f32 v[98:99], v[154:155], v[98:99]
	v_min_f32_e32 v100, 0x437f0000, v100
	v_min_f32_e32 v101, 0x437f0000, v101
	v_min_f32_e32 v102, 0x437f0000, v102
	v_min_f32_e32 v103, 0x437f0000, v103
	v_min_f32_e32 v96, 0x437f0000, v96
	v_min_f32_e32 v97, 0x437f0000, v97
	v_min_f32_e32 v98, 0x437f0000, v98
	v_min_f32_e32 v99, 0x437f0000, v99
	v_rndne_f32_e32 v100, v100
	v_rndne_f32_e32 v101, v101
	v_rndne_f32_e32 v102, v102
	v_rndne_f32_e32 v103, v103
	v_rndne_f32_e32 v96, v96
	v_rndne_f32_e32 v97, v97
	v_rndne_f32_e32 v98, v98
	v_rndne_f32_e32 v99, v99
	v_cvt_i32_f32_e32 v192, v100
	v_cvt_i32_f32_e32 v193, v96
	v_cvt_i32_f32_sdwa v192, v101 dst_sel:BYTE_1 dst_unused:UNUSED_PRESERVE src0_sel:DWORD
	v_cvt_i32_f32_sdwa v193, v97 dst_sel:BYTE_1 dst_unused:UNUSED_PRESERVE src0_sel:DWORD
	v_cvt_i32_f32_sdwa v192, v102 dst_sel:BYTE_2 dst_unused:UNUSED_PRESERVE src0_sel:DWORD
	v_cvt_i32_f32_sdwa v193, v98 dst_sel:BYTE_2 dst_unused:UNUSED_PRESERVE src0_sel:DWORD
	v_cvt_i32_f32_sdwa v192, v103 dst_sel:BYTE_3 dst_unused:UNUSED_PRESERVE src0_sel:DWORD
	v_cvt_i32_f32_sdwa v193, v99 dst_sel:BYTE_3 dst_unused:UNUSED_PRESERVE src0_sel:DWORD
	v_xor_b32_e32 v192, s55, v192
	v_xor_b32_e32 v193, s55, v193
	global_store_dwordx2 v[152:153], v[192:193], off offset:128
	v_add_co_u32_e32 v152, vcc, 0x80000, v150
	s_nop 1
	v_addc_co_u32_e32 v153, vcc, 0, v151, vcc
	v_cvt_f32_i32_e32 v92, v92
	v_cvt_f32_i32_e32 v93, v93
	v_cvt_f32_i32_e32 v94, v94
	v_cvt_f32_i32_e32 v95, v95
	v_cvt_f32_i32_e32 v88, v88
	v_cvt_f32_i32_e32 v89, v89
	v_cvt_f32_i32_e32 v90, v90
	v_cvt_f32_i32_e32 v91, v91
	v_pk_mul_f32 v[92:93], v[236:237], v[92:93] op_sel_hi:[0,1]
	v_pk_mul_f32 v[94:95], v[236:237], v[94:95] op_sel_hi:[0,1]
	v_pk_mul_f32 v[88:89], v[236:237], v[88:89] op_sel_hi:[0,1]
	v_pk_mul_f32 v[90:91], v[236:237], v[90:91] op_sel_hi:[0,1]
	v_max_f32_e32 v92, 0, v92
	v_max_f32_e32 v93, 0, v93
	v_max_f32_e32 v94, 0, v94
	v_max_f32_e32 v95, 0, v95
	v_max_f32_e32 v88, 0, v88
	v_max_f32_e32 v89, 0, v89
	v_max_f32_e32 v90, 0, v90
	v_max_f32_e32 v91, 0, v91
	v_pk_mul_f32 v[92:93], v[92:93], v[92:93]
	v_pk_mul_f32 v[94:95], v[94:95], v[94:95]
	v_pk_mul_f32 v[88:89], v[88:89], v[88:89]
	v_pk_mul_f32 v[90:91], v[90:91], v[90:91]
	v_pk_mul_f32 v[92:93], v[154:155], v[92:93]
	v_pk_mul_f32 v[94:95], v[154:155], v[94:95]
	v_pk_mul_f32 v[88:89], v[154:155], v[88:89]
	v_pk_mul_f32 v[90:91], v[154:155], v[90:91]
	v_min_f32_e32 v92, 0x437f0000, v92
	v_min_f32_e32 v93, 0x437f0000, v93
	v_min_f32_e32 v94, 0x437f0000, v94
	v_min_f32_e32 v95, 0x437f0000, v95
	v_min_f32_e32 v88, 0x437f0000, v88
	v_min_f32_e32 v89, 0x437f0000, v89
	v_min_f32_e32 v90, 0x437f0000, v90
	v_min_f32_e32 v91, 0x437f0000, v91
	v_rndne_f32_e32 v92, v92
	v_rndne_f32_e32 v93, v93
	v_rndne_f32_e32 v94, v94
	v_rndne_f32_e32 v95, v95
	v_rndne_f32_e32 v88, v88
	v_rndne_f32_e32 v89, v89
	v_rndne_f32_e32 v90, v90
	v_rndne_f32_e32 v91, v91
	v_cvt_i32_f32_e32 v194, v92
	v_cvt_i32_f32_e32 v195, v88
	v_cvt_i32_f32_sdwa v194, v93 dst_sel:BYTE_1 dst_unused:UNUSED_PRESERVE src0_sel:DWORD
	v_cvt_i32_f32_sdwa v195, v89 dst_sel:BYTE_1 dst_unused:UNUSED_PRESERVE src0_sel:DWORD
	v_cvt_i32_f32_sdwa v194, v94 dst_sel:BYTE_2 dst_unused:UNUSED_PRESERVE src0_sel:DWORD
	v_cvt_i32_f32_sdwa v195, v90 dst_sel:BYTE_2 dst_unused:UNUSED_PRESERVE src0_sel:DWORD
	v_cvt_i32_f32_sdwa v194, v95 dst_sel:BYTE_3 dst_unused:UNUSED_PRESERVE src0_sel:DWORD
	v_cvt_i32_f32_sdwa v195, v91 dst_sel:BYTE_3 dst_unused:UNUSED_PRESERVE src0_sel:DWORD
	v_xor_b32_e32 v194, s55, v194
	v_xor_b32_e32 v195, s55, v195
	global_store_dwordx2 v[152:153], v[194:195], off
	v_cvt_f32_i32_e32 v84, v84
	v_cvt_f32_i32_e32 v85, v85
	v_cvt_f32_i32_e32 v86, v86
	v_cvt_f32_i32_e32 v87, v87
	v_cvt_f32_i32_e32 v80, v80
	v_cvt_f32_i32_e32 v81, v81
	v_cvt_f32_i32_e32 v82, v82
	v_cvt_f32_i32_e32 v83, v83
	v_pk_mul_f32 v[84:85], v[236:237], v[84:85] op_sel_hi:[0,1]
	v_pk_mul_f32 v[86:87], v[236:237], v[86:87] op_sel_hi:[0,1]
	v_pk_mul_f32 v[80:81], v[236:237], v[80:81] op_sel_hi:[0,1]
	v_pk_mul_f32 v[82:83], v[236:237], v[82:83] op_sel_hi:[0,1]
	v_max_f32_e32 v84, 0, v84
	v_max_f32_e32 v85, 0, v85
	v_max_f32_e32 v86, 0, v86
	v_max_f32_e32 v87, 0, v87
	v_max_f32_e32 v80, 0, v80
	v_max_f32_e32 v81, 0, v81
	v_max_f32_e32 v82, 0, v82
	v_max_f32_e32 v83, 0, v83
	v_pk_mul_f32 v[84:85], v[84:85], v[84:85]
	v_pk_mul_f32 v[86:87], v[86:87], v[86:87]
	v_pk_mul_f32 v[80:81], v[80:81], v[80:81]
	v_pk_mul_f32 v[82:83], v[82:83], v[82:83]
	v_pk_mul_f32 v[84:85], v[154:155], v[84:85]
	v_pk_mul_f32 v[86:87], v[154:155], v[86:87]
	v_pk_mul_f32 v[80:81], v[154:155], v[80:81]
	v_pk_mul_f32 v[82:83], v[154:155], v[82:83]
	v_min_f32_e32 v84, 0x437f0000, v84
	v_min_f32_e32 v85, 0x437f0000, v85
	v_min_f32_e32 v86, 0x437f0000, v86
	v_min_f32_e32 v87, 0x437f0000, v87
	v_min_f32_e32 v80, 0x437f0000, v80
	v_min_f32_e32 v81, 0x437f0000, v81
	v_min_f32_e32 v82, 0x437f0000, v82
	v_min_f32_e32 v83, 0x437f0000, v83
	v_rndne_f32_e32 v84, v84
	v_rndne_f32_e32 v85, v85
	v_rndne_f32_e32 v86, v86
	v_rndne_f32_e32 v87, v87
	v_rndne_f32_e32 v80, v80
	v_rndne_f32_e32 v81, v81
	v_rndne_f32_e32 v82, v82
	v_rndne_f32_e32 v83, v83
	v_cvt_i32_f32_e32 v196, v84
	v_cvt_i32_f32_e32 v197, v80
	v_cvt_i32_f32_sdwa v196, v85 dst_sel:BYTE_1 dst_unused:UNUSED_PRESERVE src0_sel:DWORD
	v_cvt_i32_f32_sdwa v197, v81 dst_sel:BYTE_1 dst_unused:UNUSED_PRESERVE src0_sel:DWORD
	v_cvt_i32_f32_sdwa v196, v86 dst_sel:BYTE_2 dst_unused:UNUSED_PRESERVE src0_sel:DWORD
	v_cvt_i32_f32_sdwa v197, v82 dst_sel:BYTE_2 dst_unused:UNUSED_PRESERVE src0_sel:DWORD
	v_cvt_i32_f32_sdwa v196, v87 dst_sel:BYTE_3 dst_unused:UNUSED_PRESERVE src0_sel:DWORD
	v_cvt_i32_f32_sdwa v197, v83 dst_sel:BYTE_3 dst_unused:UNUSED_PRESERVE src0_sel:DWORD
	v_xor_b32_e32 v196, s55, v196
	v_xor_b32_e32 v197, s55, v197
	global_store_dwordx2 v[152:153], v[196:197], off offset:128
	v_add_co_u32_e32 v152, vcc, 0xc0000, v150
	s_nop 1
	v_addc_co_u32_e32 v153, vcc, 0, v151, vcc
	v_cvt_f32_i32_e32 v76, v76
	v_cvt_f32_i32_e32 v77, v77
	v_cvt_f32_i32_e32 v78, v78
	v_cvt_f32_i32_e32 v79, v79
	v_cvt_f32_i32_e32 v72, v72
	v_cvt_f32_i32_e32 v73, v73
	v_cvt_f32_i32_e32 v74, v74
	v_cvt_f32_i32_e32 v75, v75
	v_pk_mul_f32 v[76:77], v[238:239], v[76:77] op_sel_hi:[0,1]
	v_pk_mul_f32 v[78:79], v[238:239], v[78:79] op_sel_hi:[0,1]
	v_pk_mul_f32 v[72:73], v[238:239], v[72:73] op_sel_hi:[0,1]
	v_pk_mul_f32 v[74:75], v[238:239], v[74:75] op_sel_hi:[0,1]
	v_max_f32_e32 v76, 0, v76
	v_max_f32_e32 v77, 0, v77
	v_max_f32_e32 v78, 0, v78
	v_max_f32_e32 v79, 0, v79
	v_max_f32_e32 v72, 0, v72
	v_max_f32_e32 v73, 0, v73
	v_max_f32_e32 v74, 0, v74
	v_max_f32_e32 v75, 0, v75
	v_pk_mul_f32 v[76:77], v[76:77], v[76:77]
	v_pk_mul_f32 v[78:79], v[78:79], v[78:79]
	v_pk_mul_f32 v[72:73], v[72:73], v[72:73]
	v_pk_mul_f32 v[74:75], v[74:75], v[74:75]
	v_pk_mul_f32 v[76:77], v[154:155], v[76:77]
	v_pk_mul_f32 v[78:79], v[154:155], v[78:79]
	v_pk_mul_f32 v[72:73], v[154:155], v[72:73]
	v_pk_mul_f32 v[74:75], v[154:155], v[74:75]
	v_min_f32_e32 v76, 0x437f0000, v76
	v_min_f32_e32 v77, 0x437f0000, v77
	v_min_f32_e32 v78, 0x437f0000, v78
	v_min_f32_e32 v79, 0x437f0000, v79
	v_min_f32_e32 v72, 0x437f0000, v72
	v_min_f32_e32 v73, 0x437f0000, v73
	v_min_f32_e32 v74, 0x437f0000, v74
	v_min_f32_e32 v75, 0x437f0000, v75
	v_rndne_f32_e32 v76, v76
	v_rndne_f32_e32 v77, v77
	v_rndne_f32_e32 v78, v78
	v_rndne_f32_e32 v79, v79
	v_rndne_f32_e32 v72, v72
	v_rndne_f32_e32 v73, v73
	v_rndne_f32_e32 v74, v74
	v_rndne_f32_e32 v75, v75
	v_cvt_i32_f32_e32 v198, v76
	v_cvt_i32_f32_e32 v199, v72
	v_cvt_i32_f32_sdwa v198, v77 dst_sel:BYTE_1 dst_unused:UNUSED_PRESERVE src0_sel:DWORD
	v_cvt_i32_f32_sdwa v199, v73 dst_sel:BYTE_1 dst_unused:UNUSED_PRESERVE src0_sel:DWORD
	v_cvt_i32_f32_sdwa v198, v78 dst_sel:BYTE_2 dst_unused:UNUSED_PRESERVE src0_sel:DWORD
	v_cvt_i32_f32_sdwa v199, v74 dst_sel:BYTE_2 dst_unused:UNUSED_PRESERVE src0_sel:DWORD
	v_cvt_i32_f32_sdwa v198, v79 dst_sel:BYTE_3 dst_unused:UNUSED_PRESERVE src0_sel:DWORD
	v_cvt_i32_f32_sdwa v199, v75 dst_sel:BYTE_3 dst_unused:UNUSED_PRESERVE src0_sel:DWORD
	v_xor_b32_e32 v198, s55, v198
	v_xor_b32_e32 v199, s55, v199
	global_store_dwordx2 v[152:153], v[198:199], off
	v_cvt_f32_i32_e32 v68, v68
	v_cvt_f32_i32_e32 v69, v69
	v_cvt_f32_i32_e32 v70, v70
	v_cvt_f32_i32_e32 v71, v71
	v_cvt_f32_i32_e32 v64, v64
	v_cvt_f32_i32_e32 v65, v65
	v_cvt_f32_i32_e32 v66, v66
	v_cvt_f32_i32_e32 v67, v67
	v_pk_mul_f32 v[68:69], v[238:239], v[68:69] op_sel_hi:[0,1]
	v_pk_mul_f32 v[70:71], v[238:239], v[70:71] op_sel_hi:[0,1]
	v_pk_mul_f32 v[64:65], v[238:239], v[64:65] op_sel_hi:[0,1]
	v_pk_mul_f32 v[66:67], v[238:239], v[66:67] op_sel_hi:[0,1]
	v_max_f32_e32 v68, 0, v68
	v_max_f32_e32 v69, 0, v69
	v_max_f32_e32 v70, 0, v70
	v_max_f32_e32 v71, 0, v71
	v_max_f32_e32 v64, 0, v64
	v_max_f32_e32 v65, 0, v65
	v_max_f32_e32 v66, 0, v66
	v_max_f32_e32 v67, 0, v67
	v_pk_mul_f32 v[68:69], v[68:69], v[68:69]
	v_pk_mul_f32 v[70:71], v[70:71], v[70:71]
	v_pk_mul_f32 v[64:65], v[64:65], v[64:65]
	v_pk_mul_f32 v[66:67], v[66:67], v[66:67]
	v_pk_mul_f32 v[68:69], v[154:155], v[68:69]
	v_pk_mul_f32 v[70:71], v[154:155], v[70:71]
	v_pk_mul_f32 v[64:65], v[154:155], v[64:65]
	v_pk_mul_f32 v[66:67], v[154:155], v[66:67]
	v_min_f32_e32 v68, 0x437f0000, v68
	v_min_f32_e32 v69, 0x437f0000, v69
	v_min_f32_e32 v70, 0x437f0000, v70
	v_min_f32_e32 v71, 0x437f0000, v71
	v_min_f32_e32 v64, 0x437f0000, v64
	v_min_f32_e32 v65, 0x437f0000, v65
	v_min_f32_e32 v66, 0x437f0000, v66
	v_min_f32_e32 v67, 0x437f0000, v67
	v_rndne_f32_e32 v68, v68
	v_rndne_f32_e32 v69, v69
	v_rndne_f32_e32 v70, v70
	v_rndne_f32_e32 v71, v71
	v_rndne_f32_e32 v64, v64
	v_rndne_f32_e32 v65, v65
	v_rndne_f32_e32 v66, v66
	v_rndne_f32_e32 v67, v67
	v_cvt_i32_f32_e32 v200, v68
	v_cvt_i32_f32_e32 v201, v64
	v_cvt_i32_f32_sdwa v200, v69 dst_sel:BYTE_1 dst_unused:UNUSED_PRESERVE src0_sel:DWORD
	v_cvt_i32_f32_sdwa v201, v65 dst_sel:BYTE_1 dst_unused:UNUSED_PRESERVE src0_sel:DWORD
	v_cvt_i32_f32_sdwa v200, v70 dst_sel:BYTE_2 dst_unused:UNUSED_PRESERVE src0_sel:DWORD
	v_cvt_i32_f32_sdwa v201, v66 dst_sel:BYTE_2 dst_unused:UNUSED_PRESERVE src0_sel:DWORD
	v_cvt_i32_f32_sdwa v200, v71 dst_sel:BYTE_3 dst_unused:UNUSED_PRESERVE src0_sel:DWORD
	v_cvt_i32_f32_sdwa v201, v67 dst_sel:BYTE_3 dst_unused:UNUSED_PRESERVE src0_sel:DWORD
	v_xor_b32_e32 v200, s55, v200
	v_xor_b32_e32 v201, s55, v201
	global_store_dwordx2 v[152:153], v[200:201], off offset:128
	v_add_co_u32_e32 v152, vcc, 0x200000, v150
	s_nop 1
	v_addc_co_u32_e32 v153, vcc, 0, v151, vcc
	v_cvt_f32_i32_e32 v60, v60
	v_cvt_f32_i32_e32 v61, v61
	v_cvt_f32_i32_e32 v62, v62
	v_cvt_f32_i32_e32 v63, v63
	v_cvt_f32_i32_e32 v56, v56
	v_cvt_f32_i32_e32 v57, v57
	v_cvt_f32_i32_e32 v58, v58
	v_cvt_f32_i32_e32 v59, v59
	v_pk_mul_f32 v[60:61], v[240:241], v[60:61] op_sel_hi:[0,1]
	v_pk_mul_f32 v[62:63], v[240:241], v[62:63] op_sel_hi:[0,1]
	v_pk_mul_f32 v[56:57], v[240:241], v[56:57] op_sel_hi:[0,1]
	v_pk_mul_f32 v[58:59], v[240:241], v[58:59] op_sel_hi:[0,1]
	v_max_f32_e32 v60, 0, v60
	v_max_f32_e32 v61, 0, v61
	v_max_f32_e32 v62, 0, v62
	v_max_f32_e32 v63, 0, v63
	v_max_f32_e32 v56, 0, v56
	v_max_f32_e32 v57, 0, v57
	v_max_f32_e32 v58, 0, v58
	v_max_f32_e32 v59, 0, v59
	v_pk_mul_f32 v[60:61], v[60:61], v[60:61]
	v_pk_mul_f32 v[62:63], v[62:63], v[62:63]
	v_pk_mul_f32 v[56:57], v[56:57], v[56:57]
	v_pk_mul_f32 v[58:59], v[58:59], v[58:59]
	v_pk_mul_f32 v[60:61], v[154:155], v[60:61]
	v_pk_mul_f32 v[62:63], v[154:155], v[62:63]
	v_pk_mul_f32 v[56:57], v[154:155], v[56:57]
	v_pk_mul_f32 v[58:59], v[154:155], v[58:59]
	v_min_f32_e32 v60, 0x437f0000, v60
	v_min_f32_e32 v61, 0x437f0000, v61
	v_min_f32_e32 v62, 0x437f0000, v62
	v_min_f32_e32 v63, 0x437f0000, v63
	v_min_f32_e32 v56, 0x437f0000, v56
	v_min_f32_e32 v57, 0x437f0000, v57
	v_min_f32_e32 v58, 0x437f0000, v58
	v_min_f32_e32 v59, 0x437f0000, v59
	v_rndne_f32_e32 v60, v60
	v_rndne_f32_e32 v61, v61
	v_rndne_f32_e32 v62, v62
	v_rndne_f32_e32 v63, v63
	v_rndne_f32_e32 v56, v56
	v_rndne_f32_e32 v57, v57
	v_rndne_f32_e32 v58, v58
	v_rndne_f32_e32 v59, v59
	v_cvt_i32_f32_e32 v186, v60
	v_cvt_i32_f32_e32 v187, v56
	v_cvt_i32_f32_sdwa v186, v61 dst_sel:BYTE_1 dst_unused:UNUSED_PRESERVE src0_sel:DWORD
	v_cvt_i32_f32_sdwa v187, v57 dst_sel:BYTE_1 dst_unused:UNUSED_PRESERVE src0_sel:DWORD
	v_cvt_i32_f32_sdwa v186, v62 dst_sel:BYTE_2 dst_unused:UNUSED_PRESERVE src0_sel:DWORD
	v_cvt_i32_f32_sdwa v187, v58 dst_sel:BYTE_2 dst_unused:UNUSED_PRESERVE src0_sel:DWORD
	v_cvt_i32_f32_sdwa v186, v63 dst_sel:BYTE_3 dst_unused:UNUSED_PRESERVE src0_sel:DWORD
	v_cvt_i32_f32_sdwa v187, v59 dst_sel:BYTE_3 dst_unused:UNUSED_PRESERVE src0_sel:DWORD
	v_xor_b32_e32 v186, s55, v186
	v_xor_b32_e32 v187, s55, v187
	global_store_dwordx2 v[152:153], v[186:187], off
	v_cvt_f32_i32_e32 v52, v52
	v_cvt_f32_i32_e32 v53, v53
	v_cvt_f32_i32_e32 v54, v54
	v_cvt_f32_i32_e32 v55, v55
	v_cvt_f32_i32_e32 v48, v48
	v_cvt_f32_i32_e32 v49, v49
	v_cvt_f32_i32_e32 v50, v50
	v_cvt_f32_i32_e32 v51, v51
	v_pk_mul_f32 v[52:53], v[240:241], v[52:53] op_sel_hi:[0,1]
	v_pk_mul_f32 v[54:55], v[240:241], v[54:55] op_sel_hi:[0,1]
	v_pk_mul_f32 v[48:49], v[240:241], v[48:49] op_sel_hi:[0,1]
	v_pk_mul_f32 v[50:51], v[240:241], v[50:51] op_sel_hi:[0,1]
	v_max_f32_e32 v52, 0, v52
	v_max_f32_e32 v53, 0, v53
	v_max_f32_e32 v54, 0, v54
	v_max_f32_e32 v55, 0, v55
	v_max_f32_e32 v48, 0, v48
	v_max_f32_e32 v49, 0, v49
	v_max_f32_e32 v50, 0, v50
	v_max_f32_e32 v51, 0, v51
	v_pk_mul_f32 v[52:53], v[52:53], v[52:53]
	v_pk_mul_f32 v[54:55], v[54:55], v[54:55]
	v_pk_mul_f32 v[48:49], v[48:49], v[48:49]
	v_pk_mul_f32 v[50:51], v[50:51], v[50:51]
	v_pk_mul_f32 v[52:53], v[154:155], v[52:53]
	v_pk_mul_f32 v[54:55], v[154:155], v[54:55]
	v_pk_mul_f32 v[48:49], v[154:155], v[48:49]
	v_pk_mul_f32 v[50:51], v[154:155], v[50:51]
	v_min_f32_e32 v52, 0x437f0000, v52
	v_min_f32_e32 v53, 0x437f0000, v53
	v_min_f32_e32 v54, 0x437f0000, v54
	v_min_f32_e32 v55, 0x437f0000, v55
	v_min_f32_e32 v48, 0x437f0000, v48
	v_min_f32_e32 v49, 0x437f0000, v49
	v_min_f32_e32 v50, 0x437f0000, v50
	v_min_f32_e32 v51, 0x437f0000, v51
	v_rndne_f32_e32 v52, v52
	v_rndne_f32_e32 v53, v53
	v_rndne_f32_e32 v54, v54
	v_rndne_f32_e32 v55, v55
	v_rndne_f32_e32 v48, v48
	v_rndne_f32_e32 v49, v49
	v_rndne_f32_e32 v50, v50
	v_rndne_f32_e32 v51, v51
	v_cvt_i32_f32_e32 v188, v52
	v_cvt_i32_f32_e32 v189, v48
	v_cvt_i32_f32_sdwa v188, v53 dst_sel:BYTE_1 dst_unused:UNUSED_PRESERVE src0_sel:DWORD
	v_cvt_i32_f32_sdwa v189, v49 dst_sel:BYTE_1 dst_unused:UNUSED_PRESERVE src0_sel:DWORD
	v_cvt_i32_f32_sdwa v188, v54 dst_sel:BYTE_2 dst_unused:UNUSED_PRESERVE src0_sel:DWORD
	v_cvt_i32_f32_sdwa v189, v50 dst_sel:BYTE_2 dst_unused:UNUSED_PRESERVE src0_sel:DWORD
	v_cvt_i32_f32_sdwa v188, v55 dst_sel:BYTE_3 dst_unused:UNUSED_PRESERVE src0_sel:DWORD
	v_cvt_i32_f32_sdwa v189, v51 dst_sel:BYTE_3 dst_unused:UNUSED_PRESERVE src0_sel:DWORD
	v_xor_b32_e32 v188, s55, v188
	v_xor_b32_e32 v189, s55, v189
	global_store_dwordx2 v[152:153], v[188:189], off offset:128
	v_add_co_u32_e32 v152, vcc, 0x240000, v150
	s_nop 1
	v_addc_co_u32_e32 v153, vcc, 0, v151, vcc
	v_cvt_f32_i32_e32 v44, v44
	v_cvt_f32_i32_e32 v45, v45
	v_cvt_f32_i32_e32 v46, v46
	v_cvt_f32_i32_e32 v47, v47
	v_cvt_f32_i32_e32 v40, v40
	v_cvt_f32_i32_e32 v41, v41
	v_cvt_f32_i32_e32 v42, v42
	v_cvt_f32_i32_e32 v43, v43
	v_pk_mul_f32 v[44:45], v[242:243], v[44:45] op_sel_hi:[0,1]
	v_pk_mul_f32 v[46:47], v[242:243], v[46:47] op_sel_hi:[0,1]
	v_pk_mul_f32 v[40:41], v[242:243], v[40:41] op_sel_hi:[0,1]
	v_pk_mul_f32 v[42:43], v[242:243], v[42:43] op_sel_hi:[0,1]
	v_max_f32_e32 v44, 0, v44
	v_max_f32_e32 v45, 0, v45
	v_max_f32_e32 v46, 0, v46
	v_max_f32_e32 v47, 0, v47
	v_max_f32_e32 v40, 0, v40
	v_max_f32_e32 v41, 0, v41
	v_max_f32_e32 v42, 0, v42
	v_max_f32_e32 v43, 0, v43
	v_pk_mul_f32 v[44:45], v[44:45], v[44:45]
	v_pk_mul_f32 v[46:47], v[46:47], v[46:47]
	v_pk_mul_f32 v[40:41], v[40:41], v[40:41]
	v_pk_mul_f32 v[42:43], v[42:43], v[42:43]
	v_pk_mul_f32 v[44:45], v[154:155], v[44:45]
	v_pk_mul_f32 v[46:47], v[154:155], v[46:47]
	v_pk_mul_f32 v[40:41], v[154:155], v[40:41]
	v_pk_mul_f32 v[42:43], v[154:155], v[42:43]
	v_min_f32_e32 v44, 0x437f0000, v44
	v_min_f32_e32 v45, 0x437f0000, v45
	v_min_f32_e32 v46, 0x437f0000, v46
	v_min_f32_e32 v47, 0x437f0000, v47
	v_min_f32_e32 v40, 0x437f0000, v40
	v_min_f32_e32 v41, 0x437f0000, v41
	v_min_f32_e32 v42, 0x437f0000, v42
	v_min_f32_e32 v43, 0x437f0000, v43
	v_rndne_f32_e32 v44, v44
	v_rndne_f32_e32 v45, v45
	v_rndne_f32_e32 v46, v46
	v_rndne_f32_e32 v47, v47
	v_rndne_f32_e32 v40, v40
	v_rndne_f32_e32 v41, v41
	v_rndne_f32_e32 v42, v42
	v_rndne_f32_e32 v43, v43
	v_cvt_i32_f32_e32 v190, v44
	v_cvt_i32_f32_e32 v191, v40
	v_cvt_i32_f32_sdwa v190, v45 dst_sel:BYTE_1 dst_unused:UNUSED_PRESERVE src0_sel:DWORD
	v_cvt_i32_f32_sdwa v191, v41 dst_sel:BYTE_1 dst_unused:UNUSED_PRESERVE src0_sel:DWORD
	v_cvt_i32_f32_sdwa v190, v46 dst_sel:BYTE_2 dst_unused:UNUSED_PRESERVE src0_sel:DWORD
	v_cvt_i32_f32_sdwa v191, v42 dst_sel:BYTE_2 dst_unused:UNUSED_PRESERVE src0_sel:DWORD
	v_cvt_i32_f32_sdwa v190, v47 dst_sel:BYTE_3 dst_unused:UNUSED_PRESERVE src0_sel:DWORD
	v_cvt_i32_f32_sdwa v191, v43 dst_sel:BYTE_3 dst_unused:UNUSED_PRESERVE src0_sel:DWORD
	v_xor_b32_e32 v190, s55, v190
	v_xor_b32_e32 v191, s55, v191
	global_store_dwordx2 v[152:153], v[190:191], off
	v_cvt_f32_i32_e32 v36, v36
	v_cvt_f32_i32_e32 v37, v37
	v_cvt_f32_i32_e32 v38, v38
	v_cvt_f32_i32_e32 v39, v39
	v_cvt_f32_i32_e32 v32, v32
	v_cvt_f32_i32_e32 v33, v33
	v_cvt_f32_i32_e32 v34, v34
	v_cvt_f32_i32_e32 v35, v35
	v_pk_mul_f32 v[36:37], v[242:243], v[36:37] op_sel_hi:[0,1]
	v_pk_mul_f32 v[38:39], v[242:243], v[38:39] op_sel_hi:[0,1]
	v_pk_mul_f32 v[32:33], v[242:243], v[32:33] op_sel_hi:[0,1]
	v_pk_mul_f32 v[34:35], v[242:243], v[34:35] op_sel_hi:[0,1]
	v_max_f32_e32 v36, 0, v36
	v_max_f32_e32 v37, 0, v37
	v_max_f32_e32 v38, 0, v38
	v_max_f32_e32 v39, 0, v39
	v_max_f32_e32 v32, 0, v32
	v_max_f32_e32 v33, 0, v33
	v_max_f32_e32 v34, 0, v34
	v_max_f32_e32 v35, 0, v35
	v_pk_mul_f32 v[36:37], v[36:37], v[36:37]
	v_pk_mul_f32 v[38:39], v[38:39], v[38:39]
	v_pk_mul_f32 v[32:33], v[32:33], v[32:33]
	v_pk_mul_f32 v[34:35], v[34:35], v[34:35]
	v_pk_mul_f32 v[36:37], v[154:155], v[36:37]
	v_pk_mul_f32 v[38:39], v[154:155], v[38:39]
	v_pk_mul_f32 v[32:33], v[154:155], v[32:33]
	v_pk_mul_f32 v[34:35], v[154:155], v[34:35]
	v_min_f32_e32 v36, 0x437f0000, v36
	v_min_f32_e32 v37, 0x437f0000, v37
	v_min_f32_e32 v38, 0x437f0000, v38
	v_min_f32_e32 v39, 0x437f0000, v39
	v_min_f32_e32 v32, 0x437f0000, v32
	v_min_f32_e32 v33, 0x437f0000, v33
	v_min_f32_e32 v34, 0x437f0000, v34
	v_min_f32_e32 v35, 0x437f0000, v35
	v_rndne_f32_e32 v36, v36
	v_rndne_f32_e32 v37, v37
	v_rndne_f32_e32 v38, v38
	v_rndne_f32_e32 v39, v39
	v_rndne_f32_e32 v32, v32
	v_rndne_f32_e32 v33, v33
	v_rndne_f32_e32 v34, v34
	v_rndne_f32_e32 v35, v35
	v_cvt_i32_f32_e32 v192, v36
	v_cvt_i32_f32_e32 v193, v32
	v_cvt_i32_f32_sdwa v192, v37 dst_sel:BYTE_1 dst_unused:UNUSED_PRESERVE src0_sel:DWORD
	v_cvt_i32_f32_sdwa v193, v33 dst_sel:BYTE_1 dst_unused:UNUSED_PRESERVE src0_sel:DWORD
	v_cvt_i32_f32_sdwa v192, v38 dst_sel:BYTE_2 dst_unused:UNUSED_PRESERVE src0_sel:DWORD
	v_cvt_i32_f32_sdwa v193, v34 dst_sel:BYTE_2 dst_unused:UNUSED_PRESERVE src0_sel:DWORD
	v_cvt_i32_f32_sdwa v192, v39 dst_sel:BYTE_3 dst_unused:UNUSED_PRESERVE src0_sel:DWORD
	v_cvt_i32_f32_sdwa v193, v35 dst_sel:BYTE_3 dst_unused:UNUSED_PRESERVE src0_sel:DWORD
	v_xor_b32_e32 v192, s55, v192
	v_xor_b32_e32 v193, s55, v193
	global_store_dwordx2 v[152:153], v[192:193], off offset:128
	v_add_co_u32_e32 v152, vcc, 0x280000, v150
	s_nop 1
	v_addc_co_u32_e32 v153, vcc, 0, v151, vcc
	v_cvt_f32_i32_e32 v28, v28
	v_cvt_f32_i32_e32 v29, v29
	v_cvt_f32_i32_e32 v30, v30
	v_cvt_f32_i32_e32 v31, v31
	v_cvt_f32_i32_e32 v24, v24
	v_cvt_f32_i32_e32 v25, v25
	v_cvt_f32_i32_e32 v26, v26
	v_cvt_f32_i32_e32 v27, v27
	v_pk_mul_f32 v[28:29], v[244:245], v[28:29] op_sel_hi:[0,1]
	v_pk_mul_f32 v[30:31], v[244:245], v[30:31] op_sel_hi:[0,1]
	v_pk_mul_f32 v[24:25], v[244:245], v[24:25] op_sel_hi:[0,1]
	v_pk_mul_f32 v[26:27], v[244:245], v[26:27] op_sel_hi:[0,1]
	v_max_f32_e32 v28, 0, v28
	v_max_f32_e32 v29, 0, v29
	v_max_f32_e32 v30, 0, v30
	v_max_f32_e32 v31, 0, v31
	v_max_f32_e32 v24, 0, v24
	v_max_f32_e32 v25, 0, v25
	v_max_f32_e32 v26, 0, v26
	v_max_f32_e32 v27, 0, v27
	v_pk_mul_f32 v[28:29], v[28:29], v[28:29]
	v_pk_mul_f32 v[30:31], v[30:31], v[30:31]
	v_pk_mul_f32 v[24:25], v[24:25], v[24:25]
	v_pk_mul_f32 v[26:27], v[26:27], v[26:27]
	v_pk_mul_f32 v[28:29], v[154:155], v[28:29]
	v_pk_mul_f32 v[30:31], v[154:155], v[30:31]
	v_pk_mul_f32 v[24:25], v[154:155], v[24:25]
	v_pk_mul_f32 v[26:27], v[154:155], v[26:27]
	v_min_f32_e32 v28, 0x437f0000, v28
	v_min_f32_e32 v29, 0x437f0000, v29
	v_min_f32_e32 v30, 0x437f0000, v30
	v_min_f32_e32 v31, 0x437f0000, v31
	v_min_f32_e32 v24, 0x437f0000, v24
	v_min_f32_e32 v25, 0x437f0000, v25
	v_min_f32_e32 v26, 0x437f0000, v26
	v_min_f32_e32 v27, 0x437f0000, v27
	v_rndne_f32_e32 v28, v28
	v_rndne_f32_e32 v29, v29
	v_rndne_f32_e32 v30, v30
	v_rndne_f32_e32 v31, v31
	v_rndne_f32_e32 v24, v24
	v_rndne_f32_e32 v25, v25
	v_rndne_f32_e32 v26, v26
	v_rndne_f32_e32 v27, v27
	v_cvt_i32_f32_e32 v194, v28
	v_cvt_i32_f32_e32 v195, v24
	v_cvt_i32_f32_sdwa v194, v29 dst_sel:BYTE_1 dst_unused:UNUSED_PRESERVE src0_sel:DWORD
	v_cvt_i32_f32_sdwa v195, v25 dst_sel:BYTE_1 dst_unused:UNUSED_PRESERVE src0_sel:DWORD
	v_cvt_i32_f32_sdwa v194, v30 dst_sel:BYTE_2 dst_unused:UNUSED_PRESERVE src0_sel:DWORD
	v_cvt_i32_f32_sdwa v195, v26 dst_sel:BYTE_2 dst_unused:UNUSED_PRESERVE src0_sel:DWORD
	v_cvt_i32_f32_sdwa v194, v31 dst_sel:BYTE_3 dst_unused:UNUSED_PRESERVE src0_sel:DWORD
	v_cvt_i32_f32_sdwa v195, v27 dst_sel:BYTE_3 dst_unused:UNUSED_PRESERVE src0_sel:DWORD
	v_xor_b32_e32 v194, s55, v194
	v_xor_b32_e32 v195, s55, v195
	global_store_dwordx2 v[152:153], v[194:195], off
	v_cvt_f32_i32_e32 v20, v20
	v_cvt_f32_i32_e32 v21, v21
	v_cvt_f32_i32_e32 v22, v22
	v_cvt_f32_i32_e32 v23, v23
	v_cvt_f32_i32_e32 v16, v16
	v_cvt_f32_i32_e32 v17, v17
	v_cvt_f32_i32_e32 v18, v18
	v_cvt_f32_i32_e32 v19, v19
	v_pk_mul_f32 v[20:21], v[244:245], v[20:21] op_sel_hi:[0,1]
	v_pk_mul_f32 v[22:23], v[244:245], v[22:23] op_sel_hi:[0,1]
	v_pk_mul_f32 v[16:17], v[244:245], v[16:17] op_sel_hi:[0,1]
	v_pk_mul_f32 v[18:19], v[244:245], v[18:19] op_sel_hi:[0,1]
	v_max_f32_e32 v20, 0, v20
	v_max_f32_e32 v21, 0, v21
	v_max_f32_e32 v22, 0, v22
	v_max_f32_e32 v23, 0, v23
	v_max_f32_e32 v16, 0, v16
	v_max_f32_e32 v17, 0, v17
	v_max_f32_e32 v18, 0, v18
	v_max_f32_e32 v19, 0, v19
	v_pk_mul_f32 v[20:21], v[20:21], v[20:21]
	v_pk_mul_f32 v[22:23], v[22:23], v[22:23]
	v_pk_mul_f32 v[16:17], v[16:17], v[16:17]
	v_pk_mul_f32 v[18:19], v[18:19], v[18:19]
	v_pk_mul_f32 v[20:21], v[154:155], v[20:21]
	v_pk_mul_f32 v[22:23], v[154:155], v[22:23]
	v_pk_mul_f32 v[16:17], v[154:155], v[16:17]
	v_pk_mul_f32 v[18:19], v[154:155], v[18:19]
	v_min_f32_e32 v20, 0x437f0000, v20
	v_min_f32_e32 v21, 0x437f0000, v21
	v_min_f32_e32 v22, 0x437f0000, v22
	v_min_f32_e32 v23, 0x437f0000, v23
	v_min_f32_e32 v16, 0x437f0000, v16
	v_min_f32_e32 v17, 0x437f0000, v17
	v_min_f32_e32 v18, 0x437f0000, v18
	v_min_f32_e32 v19, 0x437f0000, v19
	v_rndne_f32_e32 v20, v20
	v_rndne_f32_e32 v21, v21
	v_rndne_f32_e32 v22, v22
	v_rndne_f32_e32 v23, v23
	v_rndne_f32_e32 v16, v16
	v_rndne_f32_e32 v17, v17
	v_rndne_f32_e32 v18, v18
	v_rndne_f32_e32 v19, v19
	v_cvt_i32_f32_e32 v196, v20
	v_cvt_i32_f32_e32 v197, v16
	v_cvt_i32_f32_sdwa v196, v21 dst_sel:BYTE_1 dst_unused:UNUSED_PRESERVE src0_sel:DWORD
	v_cvt_i32_f32_sdwa v197, v17 dst_sel:BYTE_1 dst_unused:UNUSED_PRESERVE src0_sel:DWORD
	v_cvt_i32_f32_sdwa v196, v22 dst_sel:BYTE_2 dst_unused:UNUSED_PRESERVE src0_sel:DWORD
	v_cvt_i32_f32_sdwa v197, v18 dst_sel:BYTE_2 dst_unused:UNUSED_PRESERVE src0_sel:DWORD
	v_cvt_i32_f32_sdwa v196, v23 dst_sel:BYTE_3 dst_unused:UNUSED_PRESERVE src0_sel:DWORD
	v_cvt_i32_f32_sdwa v197, v19 dst_sel:BYTE_3 dst_unused:UNUSED_PRESERVE src0_sel:DWORD
	v_xor_b32_e32 v196, s55, v196
	v_xor_b32_e32 v197, s55, v197
	global_store_dwordx2 v[152:153], v[196:197], off offset:128
	v_add_co_u32_e32 v152, vcc, 0x2c0000, v150
	s_nop 1
	v_addc_co_u32_e32 v153, vcc, 0, v151, vcc
	v_cvt_f32_i32_e32 v12, v12
	v_cvt_f32_i32_e32 v13, v13
	v_cvt_f32_i32_e32 v14, v14
	v_cvt_f32_i32_e32 v15, v15
	v_cvt_f32_i32_e32 v8, v8
	v_cvt_f32_i32_e32 v9, v9
	v_cvt_f32_i32_e32 v10, v10
	v_cvt_f32_i32_e32 v11, v11
	v_pk_mul_f32 v[12:13], v[246:247], v[12:13] op_sel_hi:[0,1]
	v_pk_mul_f32 v[14:15], v[246:247], v[14:15] op_sel_hi:[0,1]
	v_pk_mul_f32 v[8:9], v[246:247], v[8:9] op_sel_hi:[0,1]
	v_pk_mul_f32 v[10:11], v[246:247], v[10:11] op_sel_hi:[0,1]
	v_max_f32_e32 v12, 0, v12
	v_max_f32_e32 v13, 0, v13
	v_max_f32_e32 v14, 0, v14
	v_max_f32_e32 v15, 0, v15
	v_max_f32_e32 v8, 0, v8
	v_max_f32_e32 v9, 0, v9
	v_max_f32_e32 v10, 0, v10
	v_max_f32_e32 v11, 0, v11
	v_pk_mul_f32 v[12:13], v[12:13], v[12:13]
	v_pk_mul_f32 v[14:15], v[14:15], v[14:15]
	v_pk_mul_f32 v[8:9], v[8:9], v[8:9]
	v_pk_mul_f32 v[10:11], v[10:11], v[10:11]
	v_pk_mul_f32 v[12:13], v[154:155], v[12:13]
	v_pk_mul_f32 v[14:15], v[154:155], v[14:15]
	v_pk_mul_f32 v[8:9], v[154:155], v[8:9]
	v_pk_mul_f32 v[10:11], v[154:155], v[10:11]
	v_min_f32_e32 v12, 0x437f0000, v12
	v_min_f32_e32 v13, 0x437f0000, v13
	v_min_f32_e32 v14, 0x437f0000, v14
	v_min_f32_e32 v15, 0x437f0000, v15
	v_min_f32_e32 v8, 0x437f0000, v8
	v_min_f32_e32 v9, 0x437f0000, v9
	v_min_f32_e32 v10, 0x437f0000, v10
	v_min_f32_e32 v11, 0x437f0000, v11
	v_rndne_f32_e32 v12, v12
	v_rndne_f32_e32 v13, v13
	v_rndne_f32_e32 v14, v14
	v_rndne_f32_e32 v15, v15
	v_rndne_f32_e32 v8, v8
	v_rndne_f32_e32 v9, v9
	v_rndne_f32_e32 v10, v10
	v_rndne_f32_e32 v11, v11
	v_cvt_i32_f32_e32 v198, v12
	v_cvt_i32_f32_e32 v199, v8
	v_cvt_i32_f32_sdwa v198, v13 dst_sel:BYTE_1 dst_unused:UNUSED_PRESERVE src0_sel:DWORD
	v_cvt_i32_f32_sdwa v199, v9 dst_sel:BYTE_1 dst_unused:UNUSED_PRESERVE src0_sel:DWORD
	v_cvt_i32_f32_sdwa v198, v14 dst_sel:BYTE_2 dst_unused:UNUSED_PRESERVE src0_sel:DWORD
	v_cvt_i32_f32_sdwa v199, v10 dst_sel:BYTE_2 dst_unused:UNUSED_PRESERVE src0_sel:DWORD
	v_cvt_i32_f32_sdwa v198, v15 dst_sel:BYTE_3 dst_unused:UNUSED_PRESERVE src0_sel:DWORD
	v_cvt_i32_f32_sdwa v199, v11 dst_sel:BYTE_3 dst_unused:UNUSED_PRESERVE src0_sel:DWORD
	v_xor_b32_e32 v198, s55, v198
	v_xor_b32_e32 v199, s55, v199
	global_store_dwordx2 v[152:153], v[198:199], off
	v_cvt_f32_i32_e32 v4, v4
	v_cvt_f32_i32_e32 v5, v5
	v_cvt_f32_i32_e32 v6, v6
	v_cvt_f32_i32_e32 v7, v7
	v_cvt_f32_i32_e32 v0, v0
	v_cvt_f32_i32_e32 v1, v1
	v_cvt_f32_i32_e32 v2, v2
	v_cvt_f32_i32_e32 v3, v3
	v_pk_mul_f32 v[4:5], v[246:247], v[4:5] op_sel_hi:[0,1]
	v_pk_mul_f32 v[6:7], v[246:247], v[6:7] op_sel_hi:[0,1]
	v_pk_mul_f32 v[0:1], v[246:247], v[0:1] op_sel_hi:[0,1]
	v_pk_mul_f32 v[2:3], v[246:247], v[2:3] op_sel_hi:[0,1]
	v_max_f32_e32 v4, 0, v4
	v_max_f32_e32 v5, 0, v5
	v_max_f32_e32 v6, 0, v6
	v_max_f32_e32 v7, 0, v7
	v_max_f32_e32 v0, 0, v0
	v_max_f32_e32 v1, 0, v1
	v_max_f32_e32 v2, 0, v2
	v_max_f32_e32 v3, 0, v3
	v_pk_mul_f32 v[4:5], v[4:5], v[4:5]
	v_pk_mul_f32 v[6:7], v[6:7], v[6:7]
	v_pk_mul_f32 v[0:1], v[0:1], v[0:1]
	v_pk_mul_f32 v[2:3], v[2:3], v[2:3]
	v_pk_mul_f32 v[4:5], v[154:155], v[4:5]
	v_pk_mul_f32 v[6:7], v[154:155], v[6:7]
	v_pk_mul_f32 v[0:1], v[154:155], v[0:1]
	v_pk_mul_f32 v[2:3], v[154:155], v[2:3]
	v_min_f32_e32 v4, 0x437f0000, v4
	v_min_f32_e32 v5, 0x437f0000, v5
	v_min_f32_e32 v6, 0x437f0000, v6
	v_min_f32_e32 v7, 0x437f0000, v7
	v_min_f32_e32 v0, 0x437f0000, v0
	v_min_f32_e32 v1, 0x437f0000, v1
	v_min_f32_e32 v2, 0x437f0000, v2
	v_min_f32_e32 v3, 0x437f0000, v3
	v_rndne_f32_e32 v4, v4
	v_rndne_f32_e32 v5, v5
	v_rndne_f32_e32 v6, v6
	v_rndne_f32_e32 v7, v7
	v_rndne_f32_e32 v0, v0
	v_rndne_f32_e32 v1, v1
	v_rndne_f32_e32 v2, v2
	v_rndne_f32_e32 v3, v3
	v_cvt_i32_f32_e32 v200, v4
	v_cvt_i32_f32_e32 v201, v0
	v_cvt_i32_f32_sdwa v200, v5 dst_sel:BYTE_1 dst_unused:UNUSED_PRESERVE src0_sel:DWORD
	v_cvt_i32_f32_sdwa v201, v1 dst_sel:BYTE_1 dst_unused:UNUSED_PRESERVE src0_sel:DWORD
	v_cvt_i32_f32_sdwa v200, v6 dst_sel:BYTE_2 dst_unused:UNUSED_PRESERVE src0_sel:DWORD
	v_cvt_i32_f32_sdwa v201, v2 dst_sel:BYTE_2 dst_unused:UNUSED_PRESERVE src0_sel:DWORD
	v_cvt_i32_f32_sdwa v200, v7 dst_sel:BYTE_3 dst_unused:UNUSED_PRESERVE src0_sel:DWORD
	v_cvt_i32_f32_sdwa v201, v3 dst_sel:BYTE_3 dst_unused:UNUSED_PRESERVE src0_sel:DWORD
	v_xor_b32_e32 v200, s55, v200
	v_xor_b32_e32 v201, s55, v201
	global_store_dwordx2 v[152:153], v[200:201], off offset:128
	s_andn2_b64 vcc, exec, s[2:3]
	s_mov_b64 s[0:1], -1
	s_cbranch_vccnz .LBB0_1348
	s_branch .Ljoin_p11

.LBB0_1820:
	s_mov_b64 s[0:1], s[78:79]
	s_load_dword s0, s[0:1], 0xa8
	s_waitcnt lgkmcnt(0)
	s_cmp_gt_i32 s0, 12
	s_cbranch_scc1 .LBB0_1864
	s_mov_b64 s[0:1], s[78:79]
	s_load_dword s0, s[0:1], 0xac
	s_waitcnt lgkmcnt(0)
	s_cmp_lt_i32 s0, 13
	s_cbranch_scc1 .LBB0_1864
	s_mov_b32 s94, 0
	s_mov_b64 s[0:1], s[78:79]
	s_load_dwordx2 s[2:3], s[0:1], 0xa0
	s_cmpk_lt_i32 s87, 0x400
	s_mov_b32 s6, -1
	s_cselect_b64 s[0:1], -1, 0
	s_cmpk_gt_i32 s87, 0x3ff
	s_cbranch_scc1 .LBB0_1828
	s_ashr_i32 s4, s87, 31
	s_lshr_b32 s4, s4, 29
	s_add_i32 s9, s87, s4
	s_and_b32 s4, s9, -8
	s_sub_i32 s7, s87, s4
	s_cmp_gt_i32 s7, -1
	s_cbranch_scc0 .LBB0_1825
	s_lshl_b32 s8, s7, 7
	s_ashr_i32 s4, s9, 3
	s_cbranch_execz .LBB0_1826
	s_branch .LBB0_1827

.Lsp_skip9:
.LBB0_1841:
	ds_read_b128 v[186:189], v183
	ds_read_b128 v[190:193], v183 offset:1024
	ds_read_b128 v[194:197], v183 offset:2048
	ds_read_b128 v[198:201], v183 offset:3072
	ds_read_b128 v[202:205], v183 offset:4096
	ds_read_b128 v[206:209], v183 offset:5120
	ds_read_b128 v[210:213], v183 offset:6144
	ds_read_b128 v[214:217], v183 offset:7168
	v_add_u32_e32 v140, s47, v181
	v_add_u32_e32 v174, s48, v181
	ds_read_b128 v[124:127], v140
	ds_read_b128 v[132:135], v140 offset:1024
	ds_read_b128 v[136:139], v140 offset:2048
	ds_read_b128 v[140:143], v140 offset:3072
	ds_read_b128 v[162:165], v174
	ds_read_b128 v[166:169], v174 offset:1024
	ds_read_b128 v[170:173], v174 offset:2048
	ds_read_b128 v[174:177], v174 offset:3072
	s_add_u32 s30, s28, 0xffe00080
	s_addc_u32 s31, s29, -1
	s_cmpk_eq_i32 s53, 0x7c
	s_cselect_b32 s35, s19, s31
	s_cselect_b32 s34, s25, s30
	s_cselect_b32 s31, s17, s52
	s_cselect_b32 s30, s50, s51
	s_add_i32 m0, s27, 0xc000
	s_nop 0
	global_load_lds_dwordx4 v156, s[28:29]
	s_add_i32 m0, s27, 0xe000
	s_nop 0
	global_load_lds_dwordx4 v154, s[28:29]
	s_cmp_eq_u32 s94, 1
	s_cbranch_scc1 .Lrx12_0a
	s_waitcnt vmcnt(8)
	s_branch .Lrx12_0b

.Lrx12_0b:
	s_waitcnt lgkmcnt(0)
	s_barrier
	s_waitcnt lgkmcnt(0)
	v_mfma_i32_16x16x64_i8 v[116:119], v[124:127], v[186:189], v[116:119]
	v_mfma_i32_16x16x64_i8 v[104:107], v[136:139], v[186:189], v[104:107]
	v_mfma_i32_16x16x64_i8 v[112:115], v[124:127], v[194:197], v[112:115]
	v_mfma_i32_16x16x64_i8 v[108:111], v[136:139], v[194:197], v[108:111]
	s_add_u32 s98, s30, s10
	s_addc_u32 s99, s31, s11
	s_add_i32 s54, s47, s38
	v_mfma_i32_16x16x64_i8 v[92:95], v[124:127], v[202:205], v[92:95]
	s_add_u32 s100, s34, s10
	s_addc_u32 s101, s35, s11
	v_mfma_i32_16x16x64_i8 v[88:91], v[136:139], v[202:205], v[88:91]
	v_mfma_i32_16x16x64_i8 v[76:79], v[124:127], v[210:213], v[76:79]
	v_mfma_i32_16x16x64_i8 v[72:75], v[136:139], v[210:213], v[72:75]
	v_mfma_i32_16x16x64_i8 v[116:119], v[132:135], v[190:193], v[116:119]
	v_mfma_i32_16x16x64_i8 v[104:107], v[140:143], v[190:193], v[104:107]
	s_add_i32 s56, s48, s38
	v_mfma_i32_16x16x64_i8 v[112:115], v[132:135], v[198:201], v[112:115]
	v_mfma_i32_16x16x64_i8 v[108:111], v[140:143], v[198:201], v[108:111]
	v_mfma_i32_16x16x64_i8 v[92:95], v[132:135], v[206:209], v[92:95]
	v_mfma_i32_16x16x64_i8 v[88:91], v[140:143], v[206:209], v[88:91]
	v_mfma_i32_16x16x64_i8 v[76:79], v[132:135], v[214:217], v[76:79]
	v_mfma_i32_16x16x64_i8 v[72:75], v[140:143], v[214:217], v[72:75]
	v_mfma_i32_16x16x64_i8 v[128:131], v[162:165], v[186:189], v[128:131]
	v_mfma_i32_16x16x64_i8 v[120:123], v[170:173], v[186:189], v[120:123]
	v_mfma_i32_16x16x64_i8 v[100:103], v[162:165], v[194:197], v[100:103]
	v_mfma_i32_16x16x64_i8 v[96:99], v[170:173], v[194:197], v[96:99]
	v_mfma_i32_16x16x64_i8 v[84:87], v[162:165], v[202:205], v[84:87]
	v_mfma_i32_16x16x64_i8 v[80:83], v[170:173], v[202:205], v[80:83]
	v_mfma_i32_16x16x64_i8 v[68:71], v[162:165], v[210:213], v[68:71]
	v_mfma_i32_16x16x64_i8 v[64:67], v[170:173], v[210:213], v[64:67]
	v_mfma_i32_16x16x64_i8 v[128:131], v[166:169], v[190:193], v[128:131]
	v_mfma_i32_16x16x64_i8 v[120:123], v[174:177], v[190:193], v[120:123]
	v_mfma_i32_16x16x64_i8 v[100:103], v[166:169], v[198:201], v[100:103]
	v_mfma_i32_16x16x64_i8 v[96:99], v[174:177], v[198:201], v[96:99]
	v_mfma_i32_16x16x64_i8 v[84:87], v[166:169], v[206:209], v[84:87]
	v_mfma_i32_16x16x64_i8 v[80:83], v[174:177], v[206:209], v[80:83]
	v_mfma_i32_16x16x64_i8 v[68:71], v[166:169], v[214:217], v[68:71]
	v_mfma_i32_16x16x64_i8 v[64:67], v[174:177], v[214:217], v[64:67]
	s_barrier
	ds_read_b128 v[186:189], v183 offset:16384
	ds_read_b128 v[190:193], v183 offset:17408
	ds_read_b128 v[194:197], v183 offset:18432
	ds_read_b128 v[198:201], v183 offset:19456
	ds_read_b128 v[202:205], v183 offset:20480
	ds_read_b128 v[206:209], v183 offset:21504
	ds_read_b128 v[210:213], v183 offset:22528
	ds_read_b128 v[214:217], v183 offset:23552
	s_mov_b32 m0, s54
	s_nop 0
	global_load_lds_dwordx4 v146, s[30:31]
	s_add_i32 m0, s54, 0x2000
	s_add_u32 s54, s30, 0x200000
	s_addc_u32 s55, s31, 0
	global_load_lds_dwordx4 v150, s[30:31]
	s_mov_b32 m0, s56
	s_nop 0
	global_load_lds_dwordx4 v146, s[54:55]
	s_add_i32 m0, s56, 0x2000
	s_nop 0
	global_load_lds_dwordx4 v150, s[54:55]
	s_mov_b32 m0, s27
	s_nop 0
	global_load_lds_dwordx4 v144, s[34:35]
	s_mov_b32 m0, s39
	s_nop 0
	global_load_lds_dwordx4 v148, s[34:35]
	s_cmp_eq_u32 s94, 1
	s_cbranch_scc1 .Lrx12_1a
	s_waitcnt vmcnt(8)
	s_branch .Lrx12_1b

.Lrx12_1b:
	s_mov_b32 s94, 0
	s_waitcnt lgkmcnt(0)
	s_barrier
	s_waitcnt lgkmcnt(0)
	v_mfma_i32_16x16x64_i8 v[60:63], v[124:127], v[186:189], v[60:63]
	v_mfma_i32_16x16x64_i8 v[56:59], v[136:139], v[186:189], v[56:59]
	v_mfma_i32_16x16x64_i8 v[44:47], v[124:127], v[194:197], v[44:47]
	v_mfma_i32_16x16x64_i8 v[40:43], v[136:139], v[194:197], v[40:43]
	s_add_i32 s54, 0, 0x18000
	v_mfma_i32_16x16x64_i8 v[28:31], v[124:127], v[202:205], v[28:31]
	v_mfma_i32_16x16x64_i8 v[24:27], v[136:139], v[202:205], v[24:27]
	s_add_i32 s55, 0, 0x1c000
	v_mfma_i32_16x16x64_i8 v[12:15], v[124:127], v[210:213], v[12:15]
	v_mfma_i32_16x16x64_i8 v[8:11], v[136:139], v[210:213], v[8:11]
	s_add_u32 s34, s34, 0x200000
	v_mfma_i32_16x16x64_i8 v[60:63], v[132:135], v[190:193], v[60:63]
	v_mfma_i32_16x16x64_i8 v[56:59], v[140:143], v[190:193], v[56:59]
	s_addc_u32 s35, s35, 0
	v_mfma_i32_16x16x64_i8 v[44:47], v[132:135], v[198:201], v[44:47]
	v_mfma_i32_16x16x64_i8 v[40:43], v[140:143], v[198:201], v[40:43]
	v_mfma_i32_16x16x64_i8 v[28:31], v[132:135], v[206:209], v[28:31]
	v_mfma_i32_16x16x64_i8 v[24:27], v[140:143], v[206:209], v[24:27]
	v_mfma_i32_16x16x64_i8 v[12:15], v[132:135], v[214:217], v[12:15]
	v_mfma_i32_16x16x64_i8 v[8:11], v[140:143], v[214:217], v[8:11]
	v_mfma_i32_16x16x64_i8 v[52:55], v[162:165], v[186:189], v[52:55]
	v_mfma_i32_16x16x64_i8 v[48:51], v[170:173], v[186:189], v[48:51]
	v_mfma_i32_16x16x64_i8 v[36:39], v[162:165], v[194:197], v[36:39]
	v_mfma_i32_16x16x64_i8 v[32:35], v[170:173], v[194:197], v[32:35]
	v_mfma_i32_16x16x64_i8 v[20:23], v[162:165], v[202:205], v[20:23]
	v_mfma_i32_16x16x64_i8 v[16:19], v[170:173], v[202:205], v[16:19]
	v_mfma_i32_16x16x64_i8 v[4:7], v[162:165], v[210:213], v[4:7]
	v_mfma_i32_16x16x64_i8 v[0:3], v[170:173], v[210:213], v[0:3]
	v_mfma_i32_16x16x64_i8 v[52:55], v[166:169], v[190:193], v[52:55]
	v_mfma_i32_16x16x64_i8 v[48:51], v[174:177], v[190:193], v[48:51]
	v_mfma_i32_16x16x64_i8 v[36:39], v[166:169], v[198:201], v[36:39]
	v_mfma_i32_16x16x64_i8 v[32:35], v[174:177], v[198:201], v[32:35]
	v_mfma_i32_16x16x64_i8 v[20:23], v[166:169], v[206:209], v[20:23]
	v_mfma_i32_16x16x64_i8 v[16:19], v[174:177], v[206:209], v[16:19]
	v_mfma_i32_16x16x64_i8 v[4:7], v[166:169], v[214:217], v[4:7]
	v_mfma_i32_16x16x64_i8 v[0:3], v[174:177], v[214:217], v[0:3]
	s_barrier
	ds_read_b128 v[186:189], v183 offset:32768
	ds_read_b128 v[190:193], v183 offset:33792
	ds_read_b128 v[194:197], v183 offset:34816
	ds_read_b128 v[198:201], v183 offset:35840
	ds_read_b128 v[202:205], v183 offset:36864
	ds_read_b128 v[206:209], v183 offset:37888
	ds_read_b128 v[210:213], v183 offset:38912
	ds_read_b128 v[214:217], v183 offset:39936
	v_add_u32_e32 v140, s54, v181
	v_add_u32_e32 v174, s55, v181
	ds_read_b128 v[124:127], v140
	ds_read_b128 v[132:135], v140 offset:1024
	ds_read_b128 v[136:139], v140 offset:2048
	ds_read_b128 v[140:143], v140 offset:3072
	ds_read_b128 v[162:165], v174
	ds_read_b128 v[166:169], v174 offset:1024
	ds_read_b128 v[170:173], v174 offset:2048
	ds_read_b128 v[174:177], v174 offset:3072
	s_mov_b32 m0, s40
	s_nop 0
	global_load_lds_dwordx4 v144, s[34:35]
	s_mov_b32 m0, s41
	s_nop 0
	global_load_lds_dwordx4 v148, s[34:35]
	s_waitcnt vmcnt(8)
	s_waitcnt lgkmcnt(0)
	s_barrier
	s_waitcnt lgkmcnt(0)
	v_mfma_i32_16x16x64_i8 v[116:119], v[124:127], v[186:189], v[116:119]
	v_mfma_i32_16x16x64_i8 v[104:107], v[136:139], v[186:189], v[104:107]
	v_mfma_i32_16x16x64_i8 v[112:115], v[124:127], v[194:197], v[112:115]
	v_mfma_i32_16x16x64_i8 v[108:111], v[136:139], v[194:197], v[108:111]
	s_add_i32 s34, s54, s38
	v_mfma_i32_16x16x64_i8 v[92:95], v[124:127], v[202:205], v[92:95]
	v_mfma_i32_16x16x64_i8 v[88:91], v[136:139], v[202:205], v[88:91]
	v_mfma_i32_16x16x64_i8 v[76:79], v[124:127], v[210:213], v[76:79]
	v_mfma_i32_16x16x64_i8 v[72:75], v[136:139], v[210:213], v[72:75]
	s_add_u32 s30, s30, 0x200080
	v_mfma_i32_16x16x64_i8 v[116:119], v[132:135], v[190:193], v[116:119]
	v_mfma_i32_16x16x64_i8 v[104:107], v[140:143], v[190:193], v[104:107]
	v_mfma_i32_16x16x64_i8 v[112:115], v[132:135], v[198:201], v[112:115]
	v_mfma_i32_16x16x64_i8 v[108:111], v[140:143], v[198:201], v[108:111]
	s_addc_u32 s31, s31, 0
	v_mfma_i32_16x16x64_i8 v[92:95], v[132:135], v[206:209], v[92:95]
	v_mfma_i32_16x16x64_i8 v[88:91], v[140:143], v[206:209], v[88:91]
	v_mfma_i32_16x16x64_i8 v[76:79], v[132:135], v[214:217], v[76:79]
	v_mfma_i32_16x16x64_i8 v[72:75], v[140:143], v[214:217], v[72:75]
	v_mfma_i32_16x16x64_i8 v[128:131], v[162:165], v[186:189], v[128:131]
	v_mfma_i32_16x16x64_i8 v[120:123], v[170:173], v[186:189], v[120:123]
	v_mfma_i32_16x16x64_i8 v[100:103], v[162:165], v[194:197], v[100:103]
	v_mfma_i32_16x16x64_i8 v[96:99], v[170:173], v[194:197], v[96:99]
	v_mfma_i32_16x16x64_i8 v[84:87], v[162:165], v[202:205], v[84:87]
	v_mfma_i32_16x16x64_i8 v[80:83], v[170:173], v[202:205], v[80:83]
	v_mfma_i32_16x16x64_i8 v[68:71], v[162:165], v[210:213], v[68:71]
	v_mfma_i32_16x16x64_i8 v[64:67], v[170:173], v[210:213], v[64:67]
	v_mfma_i32_16x16x64_i8 v[128:131], v[166:169], v[190:193], v[128:131]
	v_mfma_i32_16x16x64_i8 v[120:123], v[174:177], v[190:193], v[120:123]
	v_mfma_i32_16x16x64_i8 v[100:103], v[166:169], v[198:201], v[100:103]
	v_mfma_i32_16x16x64_i8 v[96:99], v[174:177], v[198:201], v[96:99]
	v_mfma_i32_16x16x64_i8 v[84:87], v[166:169], v[206:209], v[84:87]
	v_mfma_i32_16x16x64_i8 v[80:83], v[174:177], v[206:209], v[80:83]
	v_mfma_i32_16x16x64_i8 v[68:71], v[166:169], v[214:217], v[68:71]
	v_mfma_i32_16x16x64_i8 v[64:67], v[174:177], v[214:217], v[64:67]
	s_barrier
	ds_read_b128 v[186:189], v183 offset:49152
	ds_read_b128 v[190:193], v183 offset:50176
	ds_read_b128 v[194:197], v183 offset:51200
	ds_read_b128 v[198:201], v183 offset:52224
	ds_read_b128 v[202:205], v183 offset:53248
	ds_read_b128 v[206:209], v183 offset:54272
	ds_read_b128 v[210:213], v183 offset:55296
	ds_read_b128 v[214:217], v183 offset:56320
	s_mov_b32 m0, s34
	s_nop 0
	global_load_lds_dwordx4 v146, s[98:99]
	s_add_i32 m0, s34, 0x2000
	s_add_i32 s34, s55, s38
	global_load_lds_dwordx4 v150, s[98:99]
	s_mov_b32 m0, s34
	s_nop 0
	global_load_lds_dwordx4 v146, s[30:31]
	s_add_i32 m0, s34, 0x2000
	s_nop 0
	global_load_lds_dwordx4 v150, s[30:31]
	s_mov_b32 m0, s43
	s_nop 0
	global_load_lds_dwordx4 v144, s[100:101]
	s_mov_b32 m0, s44
	s_nop 0
	global_load_lds_dwordx4 v148, s[100:101]
	s_waitcnt vmcnt(8)
	s_waitcnt lgkmcnt(0)
	s_barrier
	s_waitcnt lgkmcnt(0)
	v_mfma_i32_16x16x64_i8 v[60:63], v[124:127], v[186:189], v[60:63]
	v_mfma_i32_16x16x64_i8 v[56:59], v[136:139], v[186:189], v[56:59]
	v_mfma_i32_16x16x64_i8 v[44:47], v[124:127], v[194:197], v[44:47]
	v_mfma_i32_16x16x64_i8 v[40:43], v[136:139], v[194:197], v[40:43]
	v_mfma_i32_16x16x64_i8 v[28:31], v[124:127], v[202:205], v[28:31]
	v_mfma_i32_16x16x64_i8 v[24:27], v[136:139], v[202:205], v[24:27]
	v_mfma_i32_16x16x64_i8 v[12:15], v[124:127], v[210:213], v[12:15]
	v_mfma_i32_16x16x64_i8 v[8:11], v[136:139], v[210:213], v[8:11]
	v_mfma_i32_16x16x64_i8 v[60:63], v[132:135], v[190:193], v[60:63]
	v_mfma_i32_16x16x64_i8 v[56:59], v[140:143], v[190:193], v[56:59]
	v_mfma_i32_16x16x64_i8 v[44:47], v[132:135], v[198:201], v[44:47]
	v_mfma_i32_16x16x64_i8 v[40:43], v[140:143], v[198:201], v[40:43]
	v_mfma_i32_16x16x64_i8 v[28:31], v[132:135], v[206:209], v[28:31]
	v_mfma_i32_16x16x64_i8 v[24:27], v[140:143], v[206:209], v[24:27]
	v_mfma_i32_16x16x64_i8 v[12:15], v[132:135], v[214:217], v[12:15]
	v_mfma_i32_16x16x64_i8 v[8:11], v[140:143], v[214:217], v[8:11]
	v_mfma_i32_16x16x64_i8 v[52:55], v[162:165], v[186:189], v[52:55]
	v_mfma_i32_16x16x64_i8 v[48:51], v[170:173], v[186:189], v[48:51]
	v_mfma_i32_16x16x64_i8 v[36:39], v[162:165], v[194:197], v[36:39]
	v_mfma_i32_16x16x64_i8 v[32:35], v[170:173], v[194:197], v[32:35]
	v_mfma_i32_16x16x64_i8 v[20:23], v[162:165], v[202:205], v[20:23]
	v_mfma_i32_16x16x64_i8 v[16:19], v[170:173], v[202:205], v[16:19]
	v_mfma_i32_16x16x64_i8 v[4:7], v[162:165], v[210:213], v[4:7]
	v_mfma_i32_16x16x64_i8 v[0:3], v[170:173], v[210:213], v[0:3]
	v_mfma_i32_16x16x64_i8 v[52:55], v[166:169], v[190:193], v[52:55]
	v_mfma_i32_16x16x64_i8 v[48:51], v[174:177], v[190:193], v[48:51]
	v_mfma_i32_16x16x64_i8 v[36:39], v[166:169], v[198:201], v[36:39]
	v_mfma_i32_16x16x64_i8 v[32:35], v[174:177], v[198:201], v[32:35]
	v_mfma_i32_16x16x64_i8 v[20:23], v[166:169], v[206:209], v[20:23]
	v_mfma_i32_16x16x64_i8 v[16:19], v[174:177], v[206:209], v[16:19]
	v_mfma_i32_16x16x64_i8 v[4:7], v[166:169], v[214:217], v[4:7]
	v_mfma_i32_16x16x64_i8 v[0:3], v[174:177], v[214:217], v[0:3]
	s_barrier
	s_add_i32 s53, s53, 2
	s_add_u32 s51, s51, 0x100
	s_addc_u32 s52, s52, 0
	s_add_u32 s28, s28, 0x100
	s_addc_u32 s29, s29, 0
	s_cmpk_gt_u32 s53, 0x7d
	s_cbranch_scc0 .LBB0_1841
	s_setprio 0
	s_and_b64 vcc, exec, s[12:13]
	s_cbranch_vccz .LBB0_1844
	s_barrier
.LBB0_1844:
	v_lshl_or_b32 v162, s26, 8, v182
	v_lshl_add_u32 v166, s24, 8, v180
	v_ashrrev_i32_e32 v163, 31, v162
	v_lshlrev_b64 v[194:195], 1, v[162:163]
	v_ashrrev_i32_e32 v167, 31, v166
	v_lshl_add_u64 v[164:165], s[6:7], 0, v[194:195]
	v_lshlrev_b64 v[196:197], 13, v[166:167]
	v_lshl_add_u64 v[124:125], v[164:165], 0, v[196:197]
	global_load_dwordx4 v[186:189], v[124:125], off
	global_load_dwordx4 v[190:193], v[124:125], off offset:256
	v_or_b32_e32 v176, 16, v166
	v_or_b32_e32 v172, 32, v166
	v_or_b32_e32 v168, 48, v166
	v_ashrrev_i32_e32 v177, 31, v176
	v_ashrrev_i32_e32 v173, 31, v172
	v_ashrrev_i32_e32 v169, 31, v168
	v_lshlrev_b64 v[178:179], 13, v[176:177]
	v_lshlrev_b64 v[174:175], 13, v[172:173]
	v_cvt_f32_i32_e32 v203, v105
	v_cvt_f32_i32_e32 v202, v104
	v_cvt_f32_i32_e32 v205, v107
	v_cvt_f32_i32_e32 v204, v106
	v_lshlrev_b64 v[170:171], 13, v[168:169]
	v_lshl_add_u64 v[104:105], v[164:165], 0, v[178:179]
	v_lshl_add_u64 v[106:107], v[164:165], 0, v[174:175]
	v_cvt_f32_i32_e32 v199, v117
	v_cvt_f32_i32_e32 v198, v116
	v_cvt_f32_i32_e32 v201, v119
	v_cvt_f32_i32_e32 v200, v118
	v_lshl_add_u64 v[206:207], v[164:165], 0, v[170:171]
	global_load_dwordx4 v[140:143], v[104:105], off
	global_load_dwordx4 v[136:139], v[104:105], off offset:256
	global_load_dwordx4 v[132:135], v[106:107], off
	global_load_dwordx4 v[124:127], v[106:107], off offset:256
	global_load_dwordx4 v[116:119], v[206:207], off
	s_nop 0
	global_load_dwordx4 v[104:107], v[206:207], off offset:256
	v_cvt_f32_i32_e32 v129, v129
	v_cvt_f32_i32_e32 v128, v128
	v_cvt_f32_i32_e32 v131, v131
	v_cvt_f32_i32_e32 v130, v130
	v_cvt_f32_i32_e32 v121, v121
	v_cvt_f32_i32_e32 v120, v120
	v_cvt_f32_i32_e32 v123, v123
	v_cvt_f32_i32_e32 v122, v122
	s_waitcnt vmcnt(0)
	s_mov_b32 s94, 1
	v_lshlrev_b32_e32 v206, 16, v186
	v_and_b32_e32 v207, 0xffff0000, v186
	v_lshlrev_b32_e32 v186, 16, v187
	v_and_b32_e32 v187, 0xffff0000, v187
	v_lshlrev_b32_e32 v208, 16, v188
	v_and_b32_e32 v209, 0xffff0000, v188
	v_lshlrev_b32_e32 v210, 16, v190
	v_and_b32_e32 v211, 0xffff0000, v190
	v_lshlrev_b32_e32 v190, 16, v191
	v_and_b32_e32 v191, 0xffff0000, v191
	v_lshlrev_b32_e32 v188, 16, v189
	v_and_b32_e32 v189, 0xffff0000, v189
	v_lshlrev_b32_e32 v212, 16, v192
	v_and_b32_e32 v213, 0xffff0000, v192
	v_pk_fma_f32 v[186:187], v[200:201], s[14:15], v[186:187] op_sel_hi:[1,0,1]
	v_pk_fma_f32 v[198:199], v[198:199], s[14:15], v[206:207] op_sel_hi:[1,0,1]
	v_pk_fma_f32 v[200:201], v[202:203], s[14:15], v[208:209] op_sel_hi:[1,0,1]
	v_pk_fma_f32 v[190:191], v[130:131], s[14:15], v[190:191] op_sel_hi:[1,0,1]
	v_pk_fma_f32 v[202:203], v[128:129], s[14:15], v[210:211] op_sel_hi:[1,0,1]
	v_lshlrev_b32_e32 v192, 16, v193
	v_and_b32_e32 v193, 0xffff0000, v193
	v_pk_fma_f32 v[188:189], v[204:205], s[14:15], v[188:189] op_sel_hi:[1,0,1]
	v_pk_fma_f32 v[204:205], v[120:121], s[14:15], v[212:213] op_sel_hi:[1,0,1]
	v_cvt_pk_bf16_f32 v128, v198, v199
	v_cvt_pk_bf16_f32 v129, v186, v187
	v_mul_f32_e32 v120, v199, v199
	v_mul_f32_e32 v121, v187, v187
	v_mul_f32_e32 v185, v203, v203
	v_mul_f32_e32 v187, v191, v191
	v_pk_fma_f32 v[192:193], v[122:123], s[14:15], v[192:193] op_sel_hi:[1,0,1]
	v_cvt_pk_bf16_f32 v130, v200, v201
	v_cvt_pk_bf16_f32 v131, v188, v189
	v_mul_f32_e32 v122, v201, v201
	v_mul_f32_e32 v123, v189, v189
	v_mul_f32_e32 v189, v205, v205
	v_fmac_f32_e32 v120, v198, v198
	v_fmac_f32_e32 v121, v186, v186
	v_fmac_f32_e32 v185, v202, v202
	v_fmac_f32_e32 v187, v190, v190
	v_mul_f32_e32 v199, v193, v193
	v_fmac_f32_e32 v122, v200, v200
	v_fmac_f32_e32 v189, v204, v204
	v_add_f32_e32 v120, v120, v121
	v_add_f32_e32 v121, v185, v187
	v_fmac_f32_e32 v123, v188, v188
	v_add_f32_e32 v120, v122, v120
	v_add_f32_e32 v121, v189, v121
	v_fmac_f32_e32 v199, v192, v192
	v_add_f32_e32 v120, v123, v120
	v_add_f32_e32 v121, v199, v121
	v_and_b32_e32 v122, 64, v184
	v_add_f32_e32 v121, v120, v121
	v_xor_b32_e32 v120, 16, v184
	v_add_u32_e32 v185, 64, v122
	v_cmp_lt_i32_e32 vcc, v120, v185
	v_lshl_add_u64 v[122:123], s[6:7], 0, v[196:197]
	v_lshl_add_u64 v[186:187], v[122:123], 0, v[194:195]
	v_cndmask_b32_e32 v120, v184, v120, vcc
	v_lshlrev_b32_e32 v120, 2, v120
	ds_bpermute_b32 v188, v120, v121
	global_store_dwordx4 v[186:187], v[128:131], off
	s_waitcnt lgkmcnt(0)
	v_add_f32_e32 v122, v121, v188
	v_xor_b32_e32 v121, 32, v184
	v_cmp_lt_i32_e32 vcc, v121, v185
	v_cvt_pk_bf16_f32 v128, v202, v203
	v_cvt_pk_bf16_f32 v129, v190, v191
	v_cvt_pk_bf16_f32 v130, v204, v205
	v_cvt_pk_bf16_f32 v131, v192, v193
	global_store_dwordx4 v[186:187], v[128:131], off offset:256
	s_nop 0
	v_cndmask_b32_e32 v121, v184, v121, vcc
	v_lshlrev_b32_e32 v121, 2, v121
	ds_bpermute_b32 v123, v121, v122
	s_and_saveexec_b64 s[24:25], s[2:3]
	s_cbranch_execz .LBB0_1846
	s_waitcnt lgkmcnt(0)
	v_add_f32_e32 v122, v122, v123
	v_fma_f32 v122, v122, s49, 0.5
	v_trunc_f32_e32 v122, v122
	v_mul_f32_e32 v123, 0x2f800000, v122
	v_floor_f32_e32 v123, v123
	v_fmac_f32_e32 v122, 0xcf800000, v123
	v_cvt_u32_f32_e32 v122, v122
	v_cvt_u32_f32_e32 v123, v123
	v_lshl_add_u64 v[128:129], v[166:167], 3, s[8:9]
	global_atomic_add_x2 v[128:129], v[122:123], off
